# de-serialized load chains: odd_tiles conv taps (5 in flight), phase-0 transpose/GEMV/silu staging, norm output loops; plus scan 2-deep prefetch and natten load hoisting
# speedup vs baseline: 1.0358x; 1.0291x over previous
; __device__ __forceinline__ unsigned pack2(float a, float b) { return (unsigned)f2bf(a) | ((unsigned)f2bf(b) << 16); }
; __device__ void norm_phase(int tid_, int bid_, int nblk_, const Params& p, int lprev, int lnext) {
;     ...
;     float xv[32];
; #pragma unroll
;     for (int i = 0; i < 8; ++i) {
;       float4 v = *(const float4*)(xold + i * 256 + lane * 4);
;       xv[i * 4 + 0] = v.x; xv[i * 4 + 1] = v.y; xv[i * 4 + 2] = v.z; xv[i * 4 + 3] = v.w;
;     }
;     ...
;     if (lnext <= 3) {
;       float ss = 0.f;
; #pragma unroll
;       for (int i = 0; i < 32; ++i) ss += xv[i] * xv[i];
;       ss = wave_sum(ss);
;       float rs = rsqrtf(ss * (1.f / 2048.f) + 1e-6f);
;       const float* shift = p.mod + (lnext * 5 + mrow) * 6144;
;       const float* scale = shift + 2048;
;       const float* npre = p.norm_pre + lnext * D;
;       u16* hr = p.h + (size_t)row * D;
; #pragma unroll
;       for (int i = 0; i < 8; ++i) {
;         int idx = i * 256 + lane * 4;
;         float4 s4 = *(const float4*)(shift + idx);
;         float4 c4 = *(const float4*)(scale + idx);
;         float4 n4 = *(const float4*)(npre + idx);
;         float h0 = xv[i * 4 + 0] * rs * n4.x * (1.f + c4.x) + s4.x;
;         float h1 = xv[i * 4 + 1] * rs * n4.y * (1.f + c4.y) + s4.y;
;         float h2 = xv[i * 4 + 2] * rs * n4.z * (1.f + c4.z) + s4.z;
;         float h3 = xv[i * 4 + 3] * rs * n4.w * (1.f + c4.w) + s4.w;
;         uint2 o;
;         o.x = pack2(h0, h1);
;         o.y = pack2(h2, h3);
;         *(uint2*)(hr + idx) = o;
;       }
;     }
.LBB0_17:
	s_ashr_i32 s0, s40, 31
	s_lshr_b32 s0, s0, 20
	s_add_i32 s0, s40, s0
	s_ashr_i32 s0, s0, 12
	s_add_i32 s20, s40, 0xffffc000
	s_cmpk_gt_i32 s40, 0x3fff
	s_cselect_b32 s21, 0, s41
	s_cselect_b32 s20, s20, s40
	s_mulk_i32 s0, 0x1800
	s_cselect_b32 s23, s49, s45
	s_cselect_b32 s24, s48, s44
	s_cselect_b32 s22, 0x6000, s0
	s_lshl_b64 s[20:21], s[20:21], 13
	s_add_u32 s24, s24, s20
	s_addc_u32 s25, s23, s21
	global_load_dwordx4 v[14:17], v42, s[24:25]
	s_ashr_i32 s23, s22, 31
	s_lshl_b64 s[20:21], s[22:23], 2
	s_add_u32 s20, s12, s20
	s_addc_u32 s21, s13, s21
	s_add_u32 s22, s20, 0x2000
	s_addc_u32 s23, s21, 0
	global_load_dwordx4 v[18:21], v42, s[20:21]
	global_load_dwordx4 v[4:7], v42, s[22:23]
	global_load_dwordx4 v[22:25], v[30:31], off
	global_load_dwordx4 v[26:29], v42, s[24:25] offset:1024
	v_lshl_add_u64 v[2:3], s[24:25], 0, v[42:43]
	v_add_co_u32_e32 v2, vcc, s30, v2
	s_add_u32 s40, s40, s26
	s_nop 0
	v_addc_co_u32_e32 v3, vcc, 0, v3, vcc
	s_addc_u32 s41, s41, s27
	s_cmpk_gt_i32 s40, 0x43ff
	s_waitcnt vmcnt(4)
	v_mul_f32_e32 v46, v15, v15
	v_fmac_f32_e32 v46, v14, v14
	v_fmac_f32_e32 v46, v16, v16
	v_mov_b32_e32 v50, v14
	v_mov_b32_e32 v51, v16
	v_mov_b32_e32 v16, v15
	global_load_dwordx4 v[168:171], v42, s[24:25] offset:2048
	global_load_dwordx4 v[172:175], v42, s[24:25] offset:3072
	global_load_dwordx4 v[176:179], v[2:3], off
	global_load_dwordx4 v[180:183], v[2:3], off offset:1024
	global_load_dwordx4 v[184:187], v[2:3], off offset:2048
	global_load_dwordx4 v[188:191], v[2:3], off offset:3072
	v_fmac_f32_e32 v46, v17, v17
	s_waitcnt vmcnt(5)
	v_mov_b32_e32 v12, v168
	v_mov_b32_e32 v13, v169
	v_mov_b32_e32 v14, v170
	v_mov_b32_e32 v15, v171
	v_fmac_f32_e32 v46, v26, v26
	v_fmac_f32_e32 v46, v27, v27
	v_fmac_f32_e32 v46, v28, v28
	v_fmac_f32_e32 v46, v29, v29
	v_mov_b32_e32 v54, v22
	v_mov_b32_e32 v55, v24
	v_mov_b32_e32 v24, v23
	v_mov_b32_e32 v8, v4
	v_mov_b32_e32 v9, v6
	v_pk_add_f32 v[56:57], v[8:9], 1.0 op_sel_hi:[1,0]
	v_mov_b32_e32 v58, v18
	v_mov_b32_e32 v59, v20
	v_mov_b32_e32 v20, v19
	v_mov_b32_e32 v6, v5
	v_pk_add_f32 v[52:53], v[6:7], 1.0 op_sel_hi:[1,0]
	v_mov_b32_e32 v60, v26
	v_mov_b32_e32 v61, v28
	v_mov_b32_e32 v28, v27
	s_waitcnt vmcnt(5)
	v_fmac_f32_e32 v46, v12, v12
	v_fmac_f32_e32 v46, v13, v13
	v_fmac_f32_e32 v46, v14, v14
	v_mov_b32_e32 v22, v12
	v_mov_b32_e32 v23, v14
	v_mov_b32_e32 v14, v13
	v_fmac_f32_e32 v46, v15, v15
	s_waitcnt vmcnt(4)
	v_mov_b32_e32 v10, v172
	v_mov_b32_e32 v11, v173
	v_mov_b32_e32 v12, v174
	v_mov_b32_e32 v13, v175
	v_fmac_f32_e32 v46, v10, v10
	v_fmac_f32_e32 v46, v11, v11
	v_fmac_f32_e32 v46, v12, v12
	v_mov_b32_e32 v18, v10
	v_mov_b32_e32 v19, v12
	v_mov_b32_e32 v12, v11
	v_fmac_f32_e32 v46, v13, v13
	s_waitcnt vmcnt(3)
	v_mov_b32_e32 v8, v176
	v_mov_b32_e32 v9, v177
	v_mov_b32_e32 v10, v178
	v_mov_b32_e32 v11, v179
	v_fmac_f32_e32 v46, v8, v8
	v_fmac_f32_e32 v46, v9, v9
	v_fmac_f32_e32 v46, v10, v10
	v_mov_b32_e32 v48, v8
	v_mov_b32_e32 v49, v10
	v_mov_b32_e32 v10, v9
	v_fmac_f32_e32 v46, v11, v11
	s_waitcnt vmcnt(2)
	v_mov_b32_e32 v6, v180
	v_mov_b32_e32 v7, v181
	v_mov_b32_e32 v8, v182
	v_mov_b32_e32 v9, v183
	v_fmac_f32_e32 v46, v6, v6
	v_fmac_f32_e32 v46, v7, v7
	v_fmac_f32_e32 v46, v8, v8
	v_mov_b32_e32 v44, v6
	v_mov_b32_e32 v45, v8
	v_mov_b32_e32 v8, v7
	v_fmac_f32_e32 v46, v9, v9
	s_waitcnt vmcnt(1)
	v_mov_b32_e32 v4, v184
	v_mov_b32_e32 v5, v185
	v_mov_b32_e32 v6, v186
	v_mov_b32_e32 v7, v187
	v_fmac_f32_e32 v46, v4, v4
	v_fmac_f32_e32 v46, v5, v5
	v_fmac_f32_e32 v46, v6, v6
	v_mov_b32_e32 v26, v4
	v_mov_b32_e32 v27, v6
	v_mov_b32_e32 v6, v5
	v_fmac_f32_e32 v46, v7, v7
	s_waitcnt vmcnt(0)
	v_mov_b32_e32 v2, v188
	v_mov_b32_e32 v3, v189
	v_mov_b32_e32 v4, v190
	v_mov_b32_e32 v5, v191
	v_pk_mul_f32 v[76:77], v[2:3], v[2:3]
	s_nop 0
	v_add_f32_e32 v46, v46, v76
	v_pk_mul_f32 v[74:75], v[4:5], v[4:5]
	v_add_f32_e32 v46, v46, v77
	v_add_f32_e32 v46, v46, v74
	v_add_f32_e32 v46, v46, v75
	ds_bpermute_b32 v73, v1, v46
	s_waitcnt lgkmcnt(0)
	v_add_f32_e32 v46, v46, v73
	ds_bpermute_b32 v73, v47, v46
	s_waitcnt lgkmcnt(0)
	v_add_f32_e32 v46, v46, v73
	ds_bpermute_b32 v73, v62, v46
	s_waitcnt lgkmcnt(0)
	v_add_f32_e32 v46, v46, v73
	ds_bpermute_b32 v73, v63, v46
	s_waitcnt lgkmcnt(0)
	v_add_f32_e32 v46, v46, v73
	ds_bpermute_b32 v73, v64, v46
	s_waitcnt lgkmcnt(0)
	v_add_f32_e32 v46, v46, v73
	ds_bpermute_b32 v73, v65, v46
	s_waitcnt lgkmcnt(0)
	v_add_f32_e32 v46, v46, v73
	v_fmamk_f32 v46, v46, 0x3a000000, v193
	v_cmp_gt_f32_e32 vcc, s62, v46
	v_mul_f32_e32 v73, 0x4b800000, v46
	s_nop 0
	v_cndmask_b32_e32 v46, v46, v73, vcc
	v_rsq_f32_e32 v46, v46
	s_nop 0
	v_mul_f32_e32 v73, 0x45800000, v46
	v_cndmask_b32_e32 v46, v46, v73, vcc
	v_pk_mul_f32 v[16:17], v[16:17], v[46:47] op_sel_hi:[1,0]
	v_pk_mul_f32 v[50:51], v[50:51], v[46:47] op_sel_hi:[1,0]
	v_pk_mul_f32 v[16:17], v[24:25], v[16:17]
	v_pk_mul_f32 v[50:51], v[54:55], v[50:51]
	v_pk_fma_f32 v[16:17], v[52:53], v[16:17], v[20:21]
	v_pk_fma_f32 v[50:51], v[56:57], v[50:51], v[58:59]
	v_and_b32_sdwa v24, v17, v198 dst_sel:DWORD dst_unused:UNUSED_PAD src0_sel:WORD_1 src1_sel:DWORD
	v_and_b32_sdwa v25, v16, v198 dst_sel:DWORD dst_unused:UNUSED_PAD src0_sel:WORD_1 src1_sel:DWORD
	v_and_b32_sdwa v20, v51, v198 dst_sel:DWORD dst_unused:UNUSED_PAD src0_sel:WORD_1 src1_sel:DWORD
	v_and_b32_sdwa v21, v50, v198 dst_sel:DWORD dst_unused:UNUSED_PAD src0_sel:WORD_1 src1_sel:DWORD
	v_add3_u32 v17, v17, v24, s63
	v_add3_u32 v16, v16, v25, s63
	v_add3_u32 v21, v50, v21, s63
	v_add3_u32 v20, v51, v20, s63
	v_and_b32_e32 v17, 0xffff0000, v17
	v_and_b32_e32 v16, 0xffff0000, v16
	v_or_b32_sdwa v17, v17, v20 dst_sel:DWORD dst_unused:UNUSED_PAD src0_sel:DWORD src1_sel:WORD_1
	v_or_b32_sdwa v16, v16, v21 dst_sel:DWORD dst_unused:UNUSED_PAD src0_sel:DWORD src1_sel:WORD_1
	global_store_dwordx2 v[40:41], v[16:17], off
	global_load_dwordx4 v[120:123], v42, s[20:21] offset:1024
	global_load_dwordx4 v[124:127], v66, s[22:23]
	global_load_dwordx4 v[128:131], v[30:31], off offset:1024
	global_load_dwordx4 v[132:135], v42, s[20:21] offset:2048
	global_load_dwordx4 v[136:139], v67, s[22:23]
	global_load_dwordx4 v[140:143], v[30:31], off offset:2048
	global_load_dwordx4 v[144:147], v42, s[20:21] offset:3072
	global_load_dwordx4 v[148:151], v68, s[22:23]
	global_load_dwordx4 v[152:155], v[30:31], off offset:3072
	global_load_dwordx4 v[156:159], v69, s[20:21]
	global_load_dwordx4 v[160:163], v69, s[22:23]
	global_load_dwordx4 v[164:167], v[32:33], off
	v_pk_mul_f32 v[16:17], v[60:61], v[46:47] op_sel_hi:[1,0]
	v_pk_mul_f32 v[14:15], v[14:15], v[46:47] op_sel_hi:[1,0]
	v_pk_mul_f32 v[18:19], v[18:19], v[46:47] op_sel_hi:[1,0]
	v_pk_mul_f32 v[12:13], v[12:13], v[46:47] op_sel_hi:[1,0]
	v_pk_mul_f32 v[10:11], v[10:11], v[46:47] op_sel_hi:[1,0]
	v_pk_mul_f32 v[8:9], v[8:9], v[46:47] op_sel_hi:[1,0]
	v_pk_mul_f32 v[6:7], v[6:7], v[46:47] op_sel_hi:[1,0]
	s_waitcnt vmcnt(9)
; __device__ __forceinline__ unsigned pack2(float a, float b) { return (unsigned)f2bf(a) | ((unsigned)f2bf(b) << 16); }
; __device__ void norm_phase(int tid_, int bid_, int nblk_, const Params& p, int lprev, int lnext) {
;     ...
; #pragma unroll
;       for (int i = 0; i < 8; ++i) {
;         int idx = i * 256 + lane * 4;
;         float4 s4 = *(const float4*)(shift + idx);
;         float4 c4 = *(const float4*)(scale + idx);
;         float4 n4 = *(const float4*)(npre + idx);
;         float h0 = xv[i * 4 + 0] * rs * n4.x * (1.f + c4.x) + s4.x;
;         float h1 = xv[i * 4 + 1] * rs * n4.y * (1.f + c4.y) + s4.y;
;         float h2 = xv[i * 4 + 2] * rs * n4.z * (1.f + c4.z) + s4.z;
;         float h3 = xv[i * 4 + 3] * rs * n4.w * (1.f + c4.w) + s4.w;
;         uint2 o;
;         o.x = pack2(h0, h1);
;         o.y = pack2(h2, h3);
;         *(uint2*)(hr + idx) = o;
;       }
	v_mov_b32_e32 v50, v120
	v_mov_b32_e32 v51, v121
	v_mov_b32_e32 v52, v122
	v_mov_b32_e32 v53, v123
	v_mov_b32_e32 v54, v124
	v_mov_b32_e32 v55, v125
	v_mov_b32_e32 v56, v126
	v_mov_b32_e32 v57, v127
	v_mov_b32_e32 v74, v128
	v_mov_b32_e32 v75, v129
	v_mov_b32_e32 v76, v130
	v_mov_b32_e32 v77, v131
	v_mov_b32_e32 v24, v50
	v_mov_b32_e32 v25, v52
	s_waitcnt vmcnt(9)
	v_mov_b32_e32 v20, v74
	v_mov_b32_e32 v21, v76
	v_pk_mul_f32 v[16:17], v[16:17], v[20:21]
	v_mov_b32_e32 v20, v54
	v_mov_b32_e32 v21, v56
	v_pk_add_f32 v[20:21], v[20:21], 1.0 op_sel_hi:[1,0]
	v_mov_b32_e32 v76, v75
	v_pk_fma_f32 v[16:17], v[20:21], v[16:17], v[24:25]
	v_pk_mul_f32 v[20:21], v[28:29], v[46:47] op_sel_hi:[1,0]
	v_mov_b32_e32 v56, v55
	v_pk_mul_f32 v[20:21], v[20:21], v[76:77]
	v_pk_add_f32 v[24:25], v[56:57], 1.0 op_sel_hi:[1,0]
	v_mov_b32_e32 v52, v51
	v_pk_fma_f32 v[20:21], v[24:25], v[20:21], v[52:53]
	v_and_b32_sdwa v24, v17, v198 dst_sel:DWORD dst_unused:UNUSED_PAD src0_sel:WORD_1 src1_sel:DWORD
	v_and_b32_sdwa v25, v16, v198 dst_sel:DWORD dst_unused:UNUSED_PAD src0_sel:WORD_1 src1_sel:DWORD
	v_add3_u32 v16, v16, v25, s63
	v_add3_u32 v17, v17, v24, s63
	v_and_b32_sdwa v24, v21, v198 dst_sel:DWORD dst_unused:UNUSED_PAD src0_sel:WORD_1 src1_sel:DWORD
	v_and_b32_sdwa v25, v20, v198 dst_sel:DWORD dst_unused:UNUSED_PAD src0_sel:WORD_1 src1_sel:DWORD
	v_add3_u32 v21, v21, v24, s63
	v_add3_u32 v20, v20, v25, s63
	v_and_b32_e32 v21, 0xffff0000, v21
	v_and_b32_e32 v20, 0xffff0000, v20
	v_or_b32_sdwa v17, v21, v17 dst_sel:DWORD dst_unused:UNUSED_PAD src0_sel:DWORD src1_sel:WORD_1
	v_or_b32_sdwa v16, v20, v16 dst_sel:DWORD dst_unused:UNUSED_PAD src0_sel:DWORD src1_sel:WORD_1
	global_store_dwordx2 v[40:41], v[16:17], off offset:512
	v_pk_mul_f32 v[16:17], v[22:23], v[46:47] op_sel_hi:[1,0]
	s_waitcnt vmcnt(7)
	v_mov_b32_e32 v50, v132
	v_mov_b32_e32 v51, v133
	v_mov_b32_e32 v52, v134
	v_mov_b32_e32 v53, v135
	v_mov_b32_e32 v54, v136
	v_mov_b32_e32 v55, v137
	v_mov_b32_e32 v56, v138
	v_mov_b32_e32 v57, v139
	v_mov_b32_e32 v58, v140
	v_mov_b32_e32 v59, v141
	v_mov_b32_e32 v60, v142
	v_mov_b32_e32 v61, v143
	v_mov_b32_e32 v22, v50
	v_mov_b32_e32 v23, v52
	s_waitcnt vmcnt(7)
	v_mov_b32_e32 v20, v58
	v_mov_b32_e32 v21, v60
	v_pk_mul_f32 v[16:17], v[16:17], v[20:21]
	v_mov_b32_e32 v20, v54
	v_mov_b32_e32 v21, v56
	v_pk_add_f32 v[20:21], v[20:21], 1.0 op_sel_hi:[1,0]
	v_mov_b32_e32 v60, v59
	v_mov_b32_e32 v56, v55
	v_pk_fma_f32 v[16:17], v[20:21], v[16:17], v[22:23]
	v_pk_mul_f32 v[14:15], v[14:15], v[60:61]
	v_pk_add_f32 v[20:21], v[56:57], 1.0 op_sel_hi:[1,0]
	v_mov_b32_e32 v52, v51
	v_pk_fma_f32 v[14:15], v[20:21], v[14:15], v[52:53]
	v_and_b32_sdwa v20, v17, v198 dst_sel:DWORD dst_unused:UNUSED_PAD src0_sel:WORD_1 src1_sel:DWORD
	v_and_b32_sdwa v21, v16, v198 dst_sel:DWORD dst_unused:UNUSED_PAD src0_sel:WORD_1 src1_sel:DWORD
	v_add3_u32 v16, v16, v21, s63
	v_add3_u32 v17, v17, v20, s63
	v_and_b32_sdwa v20, v15, v198 dst_sel:DWORD dst_unused:UNUSED_PAD src0_sel:WORD_1 src1_sel:DWORD
	v_and_b32_sdwa v21, v14, v198 dst_sel:DWORD dst_unused:UNUSED_PAD src0_sel:WORD_1 src1_sel:DWORD
	v_add3_u32 v15, v15, v20, s63
	v_add3_u32 v14, v14, v21, s63
	v_and_b32_e32 v15, 0xffff0000, v15
	v_and_b32_e32 v14, 0xffff0000, v14
	v_or_b32_sdwa v15, v15, v17 dst_sel:DWORD dst_unused:UNUSED_PAD src0_sel:DWORD src1_sel:WORD_1
	v_or_b32_sdwa v14, v14, v16 dst_sel:DWORD dst_unused:UNUSED_PAD src0_sel:DWORD src1_sel:WORD_1
	global_store_dwordx2 v[40:41], v[14:15], off offset:1024
	s_nop 0
	s_waitcnt vmcnt(5)
	v_mov_b32_e32 v14, v144
	v_mov_b32_e32 v15, v145
	v_mov_b32_e32 v16, v146
	v_mov_b32_e32 v17, v147
	v_mov_b32_e32 v20, v148
	v_mov_b32_e32 v21, v149
	v_mov_b32_e32 v22, v150
	v_mov_b32_e32 v23, v151
	v_mov_b32_e32 v50, v152
	v_mov_b32_e32 v51, v153
	v_mov_b32_e32 v52, v154
	v_mov_b32_e32 v53, v155
	v_mov_b32_e32 v29, v16
	v_mov_b32_e32 v16, v15
	s_waitcnt vmcnt(5)
	v_mov_b32_e32 v24, v50
	v_mov_b32_e32 v25, v52
	v_pk_mul_f32 v[18:19], v[18:19], v[24:25]
	v_mov_b32_e32 v25, v22
	v_mov_b32_e32 v52, v51
	v_mov_b32_e32 v22, v21
	v_mov_b32_e32 v24, v20
	v_pk_mul_f32 v[12:13], v[12:13], v[52:53]
	v_pk_add_f32 v[20:21], v[22:23], 1.0 op_sel_hi:[1,0]
	v_pk_add_f32 v[24:25], v[24:25], 1.0 op_sel_hi:[1,0]
	v_mov_b32_e32 v28, v14
	v_pk_fma_f32 v[12:13], v[20:21], v[12:13], v[16:17]
	v_pk_fma_f32 v[18:19], v[24:25], v[18:19], v[28:29]
	v_and_b32_sdwa v16, v13, v198 dst_sel:DWORD dst_unused:UNUSED_PAD src0_sel:WORD_1 src1_sel:DWORD
	v_and_b32_sdwa v17, v12, v198 dst_sel:DWORD dst_unused:UNUSED_PAD src0_sel:WORD_1 src1_sel:DWORD
	v_and_b32_sdwa v14, v19, v198 dst_sel:DWORD dst_unused:UNUSED_PAD src0_sel:WORD_1 src1_sel:DWORD
	v_and_b32_sdwa v15, v18, v198 dst_sel:DWORD dst_unused:UNUSED_PAD src0_sel:WORD_1 src1_sel:DWORD
	v_add3_u32 v13, v13, v16, s63
	v_add3_u32 v12, v12, v17, s63
	v_add3_u32 v15, v18, v15, s63
	v_add3_u32 v14, v19, v14, s63
	v_and_b32_e32 v13, 0xffff0000, v13
	v_and_b32_e32 v12, 0xffff0000, v12
	v_or_b32_sdwa v13, v13, v14 dst_sel:DWORD dst_unused:UNUSED_PAD src0_sel:DWORD src1_sel:WORD_1
	v_or_b32_sdwa v12, v12, v15 dst_sel:DWORD dst_unused:UNUSED_PAD src0_sel:DWORD src1_sel:WORD_1
	global_store_dwordx2 v[40:41], v[12:13], off offset:1536
	s_nop 0
	v_pk_mul_f32 v[24:25], v[48:49], v[46:47] op_sel_hi:[1,0]
	s_waitcnt vmcnt(3)
	v_mov_b32_e32 v12, v156
	v_mov_b32_e32 v13, v157
	v_mov_b32_e32 v14, v158
	v_mov_b32_e32 v15, v159
	v_mov_b32_e32 v16, v160
	v_mov_b32_e32 v17, v161
	v_mov_b32_e32 v18, v162
	v_mov_b32_e32 v19, v163
	v_mov_b32_e32 v20, v164
	v_mov_b32_e32 v21, v165
	v_mov_b32_e32 v22, v166
	v_mov_b32_e32 v23, v167
	v_mov_b32_e32 v49, v14
	v_mov_b32_e32 v14, v13
	s_waitcnt vmcnt(3)
; __device__ __forceinline__ unsigned pack2(float a, float b) { return (unsigned)f2bf(a) | ((unsigned)f2bf(b) << 16); }
; __device__ void norm_phase(int tid_, int bid_, int nblk_, const Params& p, int lprev, int lnext) {
;     ...
; #pragma unroll
;       for (int i = 0; i < 8; ++i) {
;         int idx = i * 256 + lane * 4;
;         float4 s4 = *(const float4*)(shift + idx);
;         float4 c4 = *(const float4*)(scale + idx);
;         float4 n4 = *(const float4*)(npre + idx);
;         float h0 = xv[i * 4 + 0] * rs * n4.x * (1.f + c4.x) + s4.x;
;         float h1 = xv[i * 4 + 1] * rs * n4.y * (1.f + c4.y) + s4.y;
;         float h2 = xv[i * 4 + 2] * rs * n4.z * (1.f + c4.z) + s4.z;
;         float h3 = xv[i * 4 + 3] * rs * n4.w * (1.f + c4.w) + s4.w;
;         uint2 o;
;         o.x = pack2(h0, h1);
;         o.y = pack2(h2, h3);
;         *(uint2*)(hr + idx) = o;
;       }
	v_mov_b32_e32 v28, v20
	v_mov_b32_e32 v29, v22
	v_pk_mul_f32 v[24:25], v[24:25], v[28:29]
	v_mov_b32_e32 v29, v18
	v_mov_b32_e32 v22, v21
	v_mov_b32_e32 v18, v17
	v_mov_b32_e32 v28, v16
	v_pk_mul_f32 v[10:11], v[10:11], v[22:23]
	v_pk_add_f32 v[16:17], v[18:19], 1.0 op_sel_hi:[1,0]
	v_pk_add_f32 v[28:29], v[28:29], 1.0 op_sel_hi:[1,0]
	v_mov_b32_e32 v48, v12
	v_pk_fma_f32 v[10:11], v[16:17], v[10:11], v[14:15]
	v_pk_fma_f32 v[24:25], v[28:29], v[24:25], v[48:49]
	v_and_b32_sdwa v14, v11, v198 dst_sel:DWORD dst_unused:UNUSED_PAD src0_sel:WORD_1 src1_sel:DWORD
	v_and_b32_sdwa v15, v10, v198 dst_sel:DWORD dst_unused:UNUSED_PAD src0_sel:WORD_1 src1_sel:DWORD
	v_and_b32_sdwa v12, v25, v198 dst_sel:DWORD dst_unused:UNUSED_PAD src0_sel:WORD_1 src1_sel:DWORD
	v_and_b32_sdwa v13, v24, v198 dst_sel:DWORD dst_unused:UNUSED_PAD src0_sel:WORD_1 src1_sel:DWORD
	v_add3_u32 v11, v11, v14, s63
	v_add3_u32 v10, v10, v15, s63
	v_add3_u32 v13, v24, v13, s63
	v_add3_u32 v12, v25, v12, s63
	v_and_b32_e32 v11, 0xffff0000, v11
	v_and_b32_e32 v10, 0xffff0000, v10
	v_or_b32_sdwa v11, v11, v12 dst_sel:DWORD dst_unused:UNUSED_PAD src0_sel:DWORD src1_sel:WORD_1
	v_or_b32_sdwa v10, v10, v13 dst_sel:DWORD dst_unused:UNUSED_PAD src0_sel:DWORD src1_sel:WORD_1
	global_store_dwordx2 v[40:41], v[10:11], off offset:2048
	global_load_dwordx4 v[120:123], v70, s[20:21]
	global_load_dwordx4 v[124:127], v70, s[22:23]
	global_load_dwordx4 v[128:131], v[34:35], off
	global_load_dwordx4 v[132:135], v71, s[20:21]
	global_load_dwordx4 v[136:139], v71, s[22:23]
	global_load_dwordx4 v[140:143], v[36:37], off
	global_load_dwordx4 v[144:147], v72, s[20:21]
	global_load_dwordx4 v[148:151], v72, s[22:23]
	global_load_dwordx4 v[152:155], v[38:39], off
	s_nop 0
	v_pk_mul_f32 v[22:23], v[44:45], v[46:47] op_sel_hi:[1,0]
	s_waitcnt vmcnt(6)
	v_mov_b32_e32 v10, v120
	v_mov_b32_e32 v11, v121
	v_mov_b32_e32 v12, v122
	v_mov_b32_e32 v13, v123
	v_mov_b32_e32 v14, v124
	v_mov_b32_e32 v15, v125
	v_mov_b32_e32 v16, v126
	v_mov_b32_e32 v17, v127
	v_mov_b32_e32 v18, v128
	v_mov_b32_e32 v19, v129
	v_mov_b32_e32 v20, v130
	v_mov_b32_e32 v21, v131
	v_mov_b32_e32 v29, v12
	v_mov_b32_e32 v12, v11
	s_waitcnt vmcnt(6)
	v_mov_b32_e32 v24, v18
	v_mov_b32_e32 v25, v20
	v_pk_mul_f32 v[22:23], v[22:23], v[24:25]
	v_mov_b32_e32 v25, v16
	v_mov_b32_e32 v20, v19
	v_mov_b32_e32 v16, v15
	v_mov_b32_e32 v24, v14
	v_pk_mul_f32 v[8:9], v[8:9], v[20:21]
	v_pk_add_f32 v[14:15], v[16:17], 1.0 op_sel_hi:[1,0]
	v_pk_add_f32 v[24:25], v[24:25], 1.0 op_sel_hi:[1,0]
	v_mov_b32_e32 v28, v10
	v_pk_fma_f32 v[8:9], v[14:15], v[8:9], v[12:13]
	v_pk_fma_f32 v[22:23], v[24:25], v[22:23], v[28:29]
	v_and_b32_sdwa v12, v9, v198 dst_sel:DWORD dst_unused:UNUSED_PAD src0_sel:WORD_1 src1_sel:DWORD
	v_and_b32_sdwa v13, v8, v198 dst_sel:DWORD dst_unused:UNUSED_PAD src0_sel:WORD_1 src1_sel:DWORD
	v_and_b32_sdwa v10, v23, v198 dst_sel:DWORD dst_unused:UNUSED_PAD src0_sel:WORD_1 src1_sel:DWORD
	v_and_b32_sdwa v11, v22, v198 dst_sel:DWORD dst_unused:UNUSED_PAD src0_sel:WORD_1 src1_sel:DWORD
	v_add3_u32 v9, v9, v12, s63
	v_add3_u32 v8, v8, v13, s63
	v_add3_u32 v11, v22, v11, s63
	v_add3_u32 v10, v23, v10, s63
	v_and_b32_e32 v9, 0xffff0000, v9
	v_and_b32_e32 v8, 0xffff0000, v8
	v_or_b32_sdwa v9, v9, v10 dst_sel:DWORD dst_unused:UNUSED_PAD src0_sel:DWORD src1_sel:WORD_1
	v_or_b32_sdwa v8, v8, v11 dst_sel:DWORD dst_unused:UNUSED_PAD src0_sel:DWORD src1_sel:WORD_1
	global_store_dwordx2 v[40:41], v[8:9], off offset:2560
	s_nop 0
	v_pk_mul_f32 v[20:21], v[26:27], v[46:47] op_sel_hi:[1,0]
	s_waitcnt vmcnt(4)
; __device__ __forceinline__ unsigned pack2(float a, float b) { return (unsigned)f2bf(a) | ((unsigned)f2bf(b) << 16); }
; __device__ void norm_phase(int tid_, int bid_, int nblk_, const Params& p, int lprev, int lnext) {
;     ...
; #pragma unroll
;       for (int i = 0; i < 8; ++i) {
;         int idx = i * 256 + lane * 4;
;         float4 s4 = *(const float4*)(shift + idx);
;         float4 c4 = *(const float4*)(scale + idx);
;         float4 n4 = *(const float4*)(npre + idx);
;         float h0 = xv[i * 4 + 0] * rs * n4.x * (1.f + c4.x) + s4.x;
;         float h1 = xv[i * 4 + 1] * rs * n4.y * (1.f + c4.y) + s4.y;
;         float h2 = xv[i * 4 + 2] * rs * n4.z * (1.f + c4.z) + s4.z;
;         float h3 = xv[i * 4 + 3] * rs * n4.w * (1.f + c4.w) + s4.w;
;         uint2 o;
;         o.x = pack2(h0, h1);
;         o.y = pack2(h2, h3);
;         *(uint2*)(hr + idx) = o;
;       }
	v_mov_b32_e32 v8, v132
	v_mov_b32_e32 v9, v133
	v_mov_b32_e32 v10, v134
	v_mov_b32_e32 v11, v135
	v_mov_b32_e32 v12, v136
	v_mov_b32_e32 v13, v137
	v_mov_b32_e32 v14, v138
	v_mov_b32_e32 v15, v139
	v_mov_b32_e32 v16, v140
	v_mov_b32_e32 v17, v141
	v_mov_b32_e32 v18, v142
	v_mov_b32_e32 v19, v143
	v_mov_b32_e32 v25, v10
	v_mov_b32_e32 v10, v9
	s_waitcnt vmcnt(4)
	v_mov_b32_e32 v22, v16
	v_mov_b32_e32 v23, v18
	v_pk_mul_f32 v[20:21], v[20:21], v[22:23]
	v_mov_b32_e32 v23, v14
	v_mov_b32_e32 v18, v17
	v_mov_b32_e32 v14, v13
	v_mov_b32_e32 v22, v12
	v_pk_mul_f32 v[6:7], v[6:7], v[18:19]
	v_pk_add_f32 v[12:13], v[14:15], 1.0 op_sel_hi:[1,0]
	v_pk_add_f32 v[22:23], v[22:23], 1.0 op_sel_hi:[1,0]
	v_mov_b32_e32 v24, v8
	v_pk_fma_f32 v[6:7], v[12:13], v[6:7], v[10:11]
	v_pk_fma_f32 v[20:21], v[22:23], v[20:21], v[24:25]
	v_and_b32_sdwa v10, v7, v198 dst_sel:DWORD dst_unused:UNUSED_PAD src0_sel:WORD_1 src1_sel:DWORD
	v_and_b32_sdwa v11, v6, v198 dst_sel:DWORD dst_unused:UNUSED_PAD src0_sel:WORD_1 src1_sel:DWORD
	v_and_b32_sdwa v8, v21, v198 dst_sel:DWORD dst_unused:UNUSED_PAD src0_sel:WORD_1 src1_sel:DWORD
	v_and_b32_sdwa v9, v20, v198 dst_sel:DWORD dst_unused:UNUSED_PAD src0_sel:WORD_1 src1_sel:DWORD
	v_add3_u32 v7, v7, v10, s63
	v_add3_u32 v6, v6, v11, s63
	v_add3_u32 v9, v20, v9, s63
	v_add3_u32 v8, v21, v8, s63
	v_and_b32_e32 v7, 0xffff0000, v7
	v_and_b32_e32 v6, 0xffff0000, v6
	v_or_b32_sdwa v7, v7, v8 dst_sel:DWORD dst_unused:UNUSED_PAD src0_sel:DWORD src1_sel:WORD_1
	v_or_b32_sdwa v6, v6, v9 dst_sel:DWORD dst_unused:UNUSED_PAD src0_sel:DWORD src1_sel:WORD_1
	global_store_dwordx2 v[40:41], v[6:7], off offset:3072
	s_nop 0
	v_mov_b32_e32 v18, v2
	v_mov_b32_e32 v19, v4
	v_pk_mul_f32 v[18:19], v[18:19], v[46:47] op_sel_hi:[1,0]
	v_mov_b32_e32 v4, v3
	v_pk_mul_f32 v[2:3], v[4:5], v[46:47] op_sel_hi:[1,0]
	s_waitcnt vmcnt(2)
	v_mov_b32_e32 v6, v144
	v_mov_b32_e32 v7, v145
	v_mov_b32_e32 v8, v146
	v_mov_b32_e32 v9, v147
	v_mov_b32_e32 v10, v148
	v_mov_b32_e32 v11, v149
	v_mov_b32_e32 v12, v150
	v_mov_b32_e32 v13, v151
	v_mov_b32_e32 v14, v152
	v_mov_b32_e32 v15, v153
	v_mov_b32_e32 v16, v154
	v_mov_b32_e32 v17, v155
	v_mov_b32_e32 v23, v8
	v_mov_b32_e32 v8, v7
	s_waitcnt vmcnt(2)
	v_mov_b32_e32 v20, v14
	v_mov_b32_e32 v21, v16
	v_pk_mul_f32 v[18:19], v[18:19], v[20:21]
	v_mov_b32_e32 v21, v12
	v_mov_b32_e32 v16, v15
	v_mov_b32_e32 v12, v11
	v_mov_b32_e32 v20, v10
	v_pk_mul_f32 v[2:3], v[2:3], v[16:17]
	v_pk_add_f32 v[4:5], v[12:13], 1.0 op_sel_hi:[1,0]
	v_pk_add_f32 v[20:21], v[20:21], 1.0 op_sel_hi:[1,0]
	v_mov_b32_e32 v22, v6
	v_pk_fma_f32 v[2:3], v[4:5], v[2:3], v[8:9]
	v_pk_fma_f32 v[18:19], v[20:21], v[18:19], v[22:23]
	v_and_b32_sdwa v6, v3, v198 dst_sel:DWORD dst_unused:UNUSED_PAD src0_sel:WORD_1 src1_sel:DWORD
	v_and_b32_sdwa v7, v2, v198 dst_sel:DWORD dst_unused:UNUSED_PAD src0_sel:WORD_1 src1_sel:DWORD
	v_and_b32_sdwa v4, v19, v198 dst_sel:DWORD dst_unused:UNUSED_PAD src0_sel:WORD_1 src1_sel:DWORD
	v_and_b32_sdwa v5, v18, v198 dst_sel:DWORD dst_unused:UNUSED_PAD src0_sel:WORD_1 src1_sel:DWORD
	v_add3_u32 v3, v3, v6, s63
	v_add3_u32 v2, v2, v7, s63
	v_add3_u32 v5, v18, v5, s63
	v_add3_u32 v4, v19, v4, s63
	v_and_b32_e32 v3, 0xffff0000, v3
	v_and_b32_e32 v2, 0xffff0000, v2
	v_or_b32_sdwa v3, v3, v4 dst_sel:DWORD dst_unused:UNUSED_PAD src0_sel:DWORD src1_sel:WORD_1
	v_or_b32_sdwa v2, v2, v5 dst_sel:DWORD dst_unused:UNUSED_PAD src0_sel:DWORD src1_sel:WORD_1
	global_store_dwordx2 v[40:41], v[2:3], off offset:3584
	v_lshl_add_u64 v[40:41], v[40:41], 0, s[28:29]
	s_cbranch_scc0 .LBB0_17

; __device__ __forceinline__ float bflo(unsigned v) { return __uint_as_float(v << 16); }
; __device__ __forceinline__ float bfhi(unsigned v) { return __uint_as_float(v & 0xffff0000u); }
; __device__ __forceinline__ unsigned pack2(float a, float b) { return (unsigned)f2bf(a) | ((unsigned)f2bf(b) << 16); }
; __device__ void odd_tiles(int tid_, int bid_, int nblk_, const Params& p, int oi, int mode, bool skip_ctx, char* smem) {
;     ...
; #pragma unroll
;     for (int i = 0; i < 5; ++i) {
;       int e = tid + i * 256, t = e / 40, c4 = (e % 40) * 4;
;       float4 acc = *(const float4*)(p.od_conv_b + oi * DC + cb + c4);
; #pragma unroll
;       for (int j = 0; j < 4; ++j) {
;         uint2 xv = xr[i][j];
;         float4 wv = *(const float4*)(p.od_conv_w + ((size_t)oi * 4 + j) * DC + cb + c4);
;         acc.x += bflo(xv.x) * wv.x; acc.y += bfhi(xv.x) * wv.y; acc.z += bflo(xv.y) * wv.z; acc.w += bfhi(xv.y) * wv.w;
;       }
;       uint2 o;
;       o.x = pack2(acc.x, acc.y);
;       o.y = pack2(acc.z, acc.w);
;       *(uint2*)(sU + t * 168 + c4) = o;
;     }
.LBB0_100:
	s_and_b32 s30, s26, 15
	s_mul_i32 s34, s30, 0xa0
	s_lshl_b32 s22, s34, 2
	s_add_u32 s20, s89, s22
	v_readlane_b32 s64, v252, 33
	s_addc_u32 s21, s90, 0
	v_readlane_b32 s76, v252, 45
	v_readlane_b32 s77, v252, 46
	s_add_u32 s22, s76, s22
	v_lshlrev_b64 v[2:3], 2, v[96:97]
	s_addc_u32 s23, s77, 0
	v_lshl_add_u64 v[4:5], s[20:21], 0, v[2:3]
	v_lshl_add_u64 v[2:3], s[22:23], 0, v[2:3]
	s_mov_b32 s61, s1
	v_lshl_add_u64 v[10:11], v[2:3], 0, s[60:61]
	global_load_dwordx4 v[2:5], v[4:5], off
	s_nop 0
	global_load_dwordx4 v[6:9], v[10:11], off
	v_add_co_u32_e32 v20, vcc, 0x2800, v10
	s_nop 1
	v_addc_co_u32_e32 v21, vcc, 0, v11, vcc
	global_load_dwordx4 v[24:27], v[20:21], off
	v_add_co_u32_e32 v20, vcc, 0x5000, v10
	s_nop 1
	v_addc_co_u32_e32 v21, vcc, 0, v11, vcc
	global_load_dwordx4 v[28:31], v[20:21], off
	v_add_co_u32_e32 v20, vcc, 0x7800, v10
	s_nop 1
	v_addc_co_u32_e32 v21, vcc, 0, v11, vcc
	global_load_dwordx4 v[32:35], v[20:21], off
	s_movk_i32 s24, 0x2000
	s_waitcnt vmcnt(3)
	v_and_b32_e32 v14, 0xffff0000, v70
	v_and_b32_e32 v15, 0xffff0000, v71
	v_lshlrev_b32_e32 v12, 16, v70
	v_lshlrev_b32_e32 v13, 16, v71
	s_movk_i32 s25, 0x5000
	s_movk_i32 s28, 0x7000
	s_movk_i32 s2, 0x2000
	v_readlane_b32 s65, v252, 34
	v_readlane_b32 s66, v252, 35
	v_readlane_b32 s67, v252, 36
	v_readlane_b32 s68, v252, 37
	v_readlane_b32 s69, v252, 38
	v_readlane_b32 s70, v252, 39
	v_readlane_b32 s71, v252, 40
	v_readlane_b32 s72, v252, 41
	v_readlane_b32 s73, v252, 42
	v_readlane_b32 s74, v252, 43
	v_readlane_b32 s75, v252, 44
	v_readlane_b32 s78, v252, 47
	v_readlane_b32 s79, v252, 48
	v_mov_b32_e32 v18, v2
	v_mov_b32_e32 v17, v8
	v_mov_b32_e32 v19, v4
	v_mov_b32_e32 v8, v7
	v_mov_b32_e32 v4, v3
	v_mov_b32_e32 v16, v6
	v_pk_fma_f32 v[6:7], v[8:9], v[14:15], v[4:5]
	v_pk_fma_f32 v[12:13], v[16:17], v[12:13], v[18:19]
	v_lshlrev_b32_e32 v9, 16, v73
	v_lshlrev_b32_e32 v8, 16, v72
	s_waitcnt vmcnt(2)
	v_mov_b32_e32 v2, v24
	v_mov_b32_e32 v3, v25
	v_mov_b32_e32 v4, v26
	v_mov_b32_e32 v5, v27
	v_mov_b32_e32 v14, v2
	v_mov_b32_e32 v15, v4
	v_pk_fma_f32 v[8:9], v[14:15], v[8:9], v[12:13]
	v_and_b32_e32 v13, 0xffff0000, v73
	v_and_b32_e32 v12, 0xffff0000, v72
	v_mov_b32_e32 v4, v3
	v_pk_fma_f32 v[6:7], v[4:5], v[12:13], v[6:7]
	v_lshlrev_b32_e32 v13, 16, v75
	v_lshlrev_b32_e32 v12, 16, v74
	s_waitcnt vmcnt(1)
	v_mov_b32_e32 v2, v28
	v_mov_b32_e32 v3, v29
	v_mov_b32_e32 v4, v30
	v_mov_b32_e32 v5, v31
	v_mov_b32_e32 v14, v2
	v_mov_b32_e32 v15, v4
	v_pk_fma_f32 v[8:9], v[14:15], v[12:13], v[8:9]
	v_and_b32_e32 v13, 0xffff0000, v75
	v_and_b32_e32 v12, 0xffff0000, v74
	v_mov_b32_e32 v4, v3
	v_pk_fma_f32 v[6:7], v[4:5], v[12:13], v[6:7]
	v_lshlrev_b32_e32 v11, 16, v77
	v_lshlrev_b32_e32 v10, 16, v76
	v_and_b32_e32 v14, 0xffff0000, v78
	v_and_b32_e32 v15, 0xffff0000, v79
	s_waitcnt vmcnt(0)
	v_mov_b32_e32 v2, v32
	v_mov_b32_e32 v3, v33
	v_mov_b32_e32 v4, v34
	v_mov_b32_e32 v5, v35
	v_mov_b32_e32 v12, v2
	v_mov_b32_e32 v13, v4
	v_pk_fma_f32 v[8:9], v[12:13], v[10:11], v[8:9]
	v_and_b32_e32 v11, 0xffff0000, v77
	v_and_b32_e32 v10, 0xffff0000, v76
	v_mov_b32_e32 v4, v3
	v_pk_fma_f32 v[2:3], v[4:5], v[10:11], v[6:7]
	v_and_b32_sdwa v1, v9, v198 dst_sel:DWORD dst_unused:UNUSED_PAD src0_sel:WORD_1 src1_sel:DWORD
	v_and_b32_sdwa v5, v3, v198 dst_sel:DWORD dst_unused:UNUSED_PAD src0_sel:WORD_1 src1_sel:DWORD
	v_and_b32_sdwa v6, v2, v198 dst_sel:DWORD dst_unused:UNUSED_PAD src0_sel:WORD_1 src1_sel:DWORD
	v_and_b32_sdwa v4, v8, v198 dst_sel:DWORD dst_unused:UNUSED_PAD src0_sel:WORD_1 src1_sel:DWORD
	v_add3_u32 v3, v3, v5, s63
	v_add3_u32 v2, v2, v6, s63
	v_add3_u32 v4, v8, v4, s63
	v_add3_u32 v1, v9, v1, s63
	v_and_b32_e32 v3, 0xffff0000, v3
	v_and_b32_e32 v2, 0xffff0000, v2
	v_or_b32_sdwa v3, v3, v1 dst_sel:DWORD dst_unused:UNUSED_PAD src0_sel:DWORD src1_sel:WORD_1
	v_or_b32_sdwa v2, v2, v4 dst_sel:DWORD dst_unused:UNUSED_PAD src0_sel:DWORD src1_sel:WORD_1
	ds_write_b64 v155, v[2:3]
	v_lshlrev_b64 v[2:3], 2, v[98:99]
	v_lshl_add_u64 v[4:5], s[20:21], 0, v[2:3]
	v_lshl_add_u64 v[2:3], s[22:23], 0, v[2:3]
	v_lshl_add_u64 v[10:11], v[2:3], 0, s[60:61]
	global_load_dwordx4 v[2:5], v[4:5], off
	s_nop 0
	global_load_dwordx4 v[6:9], v[10:11], off
	v_add_co_u32_e32 v20, vcc, 0x2800, v10
	s_nop 1
	v_addc_co_u32_e32 v21, vcc, 0, v11, vcc
	global_load_dwordx4 v[24:27], v[20:21], off
	v_add_co_u32_e32 v20, vcc, 0x5000, v10
	s_nop 1
	v_addc_co_u32_e32 v21, vcc, 0, v11, vcc
	global_load_dwordx4 v[28:31], v[20:21], off
	v_add_co_u32_e32 v20, vcc, 0x7800, v10
	s_nop 1
	v_addc_co_u32_e32 v21, vcc, 0, v11, vcc
	global_load_dwordx4 v[32:35], v[20:21], off
	v_lshlrev_b32_e32 v12, 16, v78
	v_lshlrev_b32_e32 v13, 16, v79
	s_waitcnt vmcnt(4)
	v_mov_b32_e32 v18, v2
	s_waitcnt vmcnt(3)
	v_mov_b32_e32 v17, v8
	v_mov_b32_e32 v19, v4
	v_mov_b32_e32 v8, v7
	v_mov_b32_e32 v4, v3
	v_mov_b32_e32 v16, v6
	v_pk_fma_f32 v[6:7], v[8:9], v[14:15], v[4:5]
	v_pk_fma_f32 v[12:13], v[16:17], v[12:13], v[18:19]
	v_lshlrev_b32_e32 v9, 16, v81
	v_lshlrev_b32_e32 v8, 16, v80
	s_waitcnt vmcnt(2)
	v_mov_b32_e32 v2, v24
	v_mov_b32_e32 v3, v25
	v_mov_b32_e32 v4, v26
	v_mov_b32_e32 v5, v27
	v_mov_b32_e32 v14, v2
	v_mov_b32_e32 v15, v4
	v_pk_fma_f32 v[8:9], v[14:15], v[8:9], v[12:13]
	v_and_b32_e32 v13, 0xffff0000, v81
	v_and_b32_e32 v12, 0xffff0000, v80
	v_mov_b32_e32 v4, v3
	v_pk_fma_f32 v[6:7], v[4:5], v[12:13], v[6:7]
	v_lshlrev_b32_e32 v13, 16, v83
	v_lshlrev_b32_e32 v12, 16, v82
	s_waitcnt vmcnt(1)
; __device__ __forceinline__ float bflo(unsigned v) { return __uint_as_float(v << 16); }
; __device__ __forceinline__ float bfhi(unsigned v) { return __uint_as_float(v & 0xffff0000u); }
; __device__ __forceinline__ unsigned pack2(float a, float b) { return (unsigned)f2bf(a) | ((unsigned)f2bf(b) << 16); }
; __device__ void odd_tiles(int tid_, int bid_, int nblk_, const Params& p, int oi, int mode, bool skip_ctx, char* smem) {
;     ...
; #pragma unroll
;     for (int i = 0; i < 5; ++i) {
;       int e = tid + i * 256, t = e / 40, c4 = (e % 40) * 4;
;       float4 acc = *(const float4*)(p.od_conv_b + oi * DC + cb + c4);
; #pragma unroll
;       for (int j = 0; j < 4; ++j) {
;         uint2 xv = xr[i][j];
;         float4 wv = *(const float4*)(p.od_conv_w + ((size_t)oi * 4 + j) * DC + cb + c4);
;         acc.x += bflo(xv.x) * wv.x; acc.y += bfhi(xv.x) * wv.y; acc.z += bflo(xv.y) * wv.z; acc.w += bfhi(xv.y) * wv.w;
;       }
;       uint2 o;
;       o.x = pack2(acc.x, acc.y);
;       o.y = pack2(acc.z, acc.w);
;       *(uint2*)(sU + t * 168 + c4) = o;
;     }
	v_mov_b32_e32 v2, v28
	v_mov_b32_e32 v3, v29
	v_mov_b32_e32 v4, v30
	v_mov_b32_e32 v5, v31
	v_mov_b32_e32 v14, v2
	v_mov_b32_e32 v15, v4
	v_pk_fma_f32 v[8:9], v[14:15], v[12:13], v[8:9]
	v_and_b32_e32 v13, 0xffff0000, v83
	v_and_b32_e32 v12, 0xffff0000, v82
	v_mov_b32_e32 v4, v3
	v_pk_fma_f32 v[6:7], v[4:5], v[12:13], v[6:7]
	v_lshlrev_b32_e32 v11, 16, v85
	v_lshlrev_b32_e32 v10, 16, v84
	v_and_b32_e32 v14, 0xffff0000, v86
	v_and_b32_e32 v15, 0xffff0000, v87
	s_waitcnt vmcnt(0)
	v_mov_b32_e32 v2, v32
	v_mov_b32_e32 v3, v33
	v_mov_b32_e32 v4, v34
	v_mov_b32_e32 v5, v35
	v_mov_b32_e32 v12, v2
	v_mov_b32_e32 v13, v4
	v_pk_fma_f32 v[8:9], v[12:13], v[10:11], v[8:9]
	v_and_b32_e32 v11, 0xffff0000, v85
	v_and_b32_e32 v10, 0xffff0000, v84
	v_mov_b32_e32 v4, v3
	v_pk_fma_f32 v[2:3], v[4:5], v[10:11], v[6:7]
	v_and_b32_sdwa v1, v9, v198 dst_sel:DWORD dst_unused:UNUSED_PAD src0_sel:WORD_1 src1_sel:DWORD
	v_and_b32_sdwa v5, v3, v198 dst_sel:DWORD dst_unused:UNUSED_PAD src0_sel:WORD_1 src1_sel:DWORD
	v_and_b32_sdwa v6, v2, v198 dst_sel:DWORD dst_unused:UNUSED_PAD src0_sel:WORD_1 src1_sel:DWORD
	v_and_b32_sdwa v4, v8, v198 dst_sel:DWORD dst_unused:UNUSED_PAD src0_sel:WORD_1 src1_sel:DWORD
	v_add3_u32 v3, v3, v5, s63
	v_add3_u32 v2, v2, v6, s63
	v_add3_u32 v4, v8, v4, s63
	v_add3_u32 v1, v9, v1, s63
	v_and_b32_e32 v3, 0xffff0000, v3
	v_and_b32_e32 v2, 0xffff0000, v2
	v_or_b32_sdwa v3, v3, v1 dst_sel:DWORD dst_unused:UNUSED_PAD src0_sel:DWORD src1_sel:WORD_1
	v_or_b32_sdwa v2, v2, v4 dst_sel:DWORD dst_unused:UNUSED_PAD src0_sel:DWORD src1_sel:WORD_1
	ds_write_b64 v161, v[2:3]
	v_lshlrev_b64 v[2:3], 2, v[100:101]
	v_lshl_add_u64 v[4:5], s[20:21], 0, v[2:3]
	v_lshl_add_u64 v[2:3], s[22:23], 0, v[2:3]
	v_lshl_add_u64 v[2:3], v[2:3], 0, s[60:61]
	global_load_dwordx4 v[4:7], v[4:5], off
	s_nop 0
	global_load_dwordx4 v[8:11], v[2:3], off
	v_add_co_u32_e32 v20, vcc, 0x2800, v2
	s_nop 1
	v_addc_co_u32_e32 v21, vcc, 0, v3, vcc
	global_load_dwordx4 v[24:27], v[20:21], off
	v_add_co_u32_e32 v20, vcc, 0x5000, v2
	s_nop 1
	v_addc_co_u32_e32 v21, vcc, 0, v3, vcc
	global_load_dwordx4 v[28:31], v[20:21], off
	v_add_co_u32_e32 v20, vcc, 0x7800, v2
	s_nop 1
	v_addc_co_u32_e32 v21, vcc, 0, v3, vcc
	global_load_dwordx4 v[32:35], v[20:21], off
	v_lshlrev_b32_e32 v12, 16, v86
	v_lshlrev_b32_e32 v13, 16, v87
	s_waitcnt vmcnt(4)
	v_mov_b32_e32 v18, v4
	s_waitcnt vmcnt(3)
	v_mov_b32_e32 v17, v10
	v_mov_b32_e32 v19, v6
	v_mov_b32_e32 v10, v9
	v_mov_b32_e32 v6, v5
	v_mov_b32_e32 v16, v8
	v_pk_fma_f32 v[8:9], v[10:11], v[14:15], v[6:7]
	v_pk_fma_f32 v[12:13], v[16:17], v[12:13], v[18:19]
	v_lshlrev_b32_e32 v11, 16, v89
	v_lshlrev_b32_e32 v10, 16, v88
	s_waitcnt vmcnt(2)
	v_mov_b32_e32 v4, v24
	v_mov_b32_e32 v5, v25
	v_mov_b32_e32 v6, v26
	v_mov_b32_e32 v7, v27
	v_mov_b32_e32 v14, v4
	v_mov_b32_e32 v15, v6
	v_pk_fma_f32 v[10:11], v[14:15], v[10:11], v[12:13]
	v_and_b32_e32 v13, 0xffff0000, v89
	v_and_b32_e32 v12, 0xffff0000, v88
	v_mov_b32_e32 v6, v5
	v_pk_fma_f32 v[8:9], v[6:7], v[12:13], v[8:9]
	v_lshlrev_b32_e32 v13, 16, v91
	s_nop 0
	v_lshlrev_b32_e32 v12, 16, v90
	s_waitcnt vmcnt(1)
	v_mov_b32_e32 v4, v28
	v_mov_b32_e32 v5, v29
	v_mov_b32_e32 v6, v30
	v_mov_b32_e32 v7, v31
	v_mov_b32_e32 v14, v4
	v_mov_b32_e32 v15, v6
	v_mov_b32_e32 v6, v5
	v_pk_fma_f32 v[10:11], v[14:15], v[12:13], v[10:11]
	v_and_b32_e32 v13, 0xffff0000, v91
	v_and_b32_e32 v12, 0xffff0000, v90
	v_pk_fma_f32 v[6:7], v[6:7], v[12:13], v[8:9]
	v_lshlrev_b32_e32 v9, 16, v93
	v_lshlrev_b32_e32 v8, 16, v92
	v_and_b32_e32 v14, 0xffff0000, v102
	v_and_b32_e32 v15, 0xffff0000, v103
	s_waitcnt vmcnt(0)
	v_mov_b32_e32 v2, v32
	v_mov_b32_e32 v3, v33
	v_mov_b32_e32 v4, v34
	v_mov_b32_e32 v5, v35
	v_mov_b32_e32 v12, v2
	v_mov_b32_e32 v13, v4
	v_pk_fma_f32 v[8:9], v[12:13], v[8:9], v[10:11]
	v_and_b32_e32 v11, 0xffff0000, v93
	v_and_b32_e32 v10, 0xffff0000, v92
	v_mov_b32_e32 v4, v3
	v_pk_fma_f32 v[2:3], v[4:5], v[10:11], v[6:7]
	v_and_b32_sdwa v1, v9, v198 dst_sel:DWORD dst_unused:UNUSED_PAD src0_sel:WORD_1 src1_sel:DWORD
	v_and_b32_sdwa v5, v3, v198 dst_sel:DWORD dst_unused:UNUSED_PAD src0_sel:WORD_1 src1_sel:DWORD
	v_and_b32_sdwa v6, v2, v198 dst_sel:DWORD dst_unused:UNUSED_PAD src0_sel:WORD_1 src1_sel:DWORD
	v_and_b32_sdwa v4, v8, v198 dst_sel:DWORD dst_unused:UNUSED_PAD src0_sel:WORD_1 src1_sel:DWORD
	v_add3_u32 v3, v3, v5, s63
	v_add3_u32 v2, v2, v6, s63
	v_add3_u32 v4, v8, v4, s63
	v_add3_u32 v1, v9, v1, s63
	v_and_b32_e32 v3, 0xffff0000, v3
	v_and_b32_e32 v2, 0xffff0000, v2
	v_or_b32_sdwa v3, v3, v1 dst_sel:DWORD dst_unused:UNUSED_PAD src0_sel:DWORD src1_sel:WORD_1
	v_or_b32_sdwa v2, v2, v4 dst_sel:DWORD dst_unused:UNUSED_PAD src0_sel:DWORD src1_sel:WORD_1
	ds_write_b64 v180, v[2:3]
	v_lshlrev_b64 v[2:3], 2, v[104:105]
	v_lshl_add_u64 v[4:5], s[20:21], 0, v[2:3]
	v_lshl_add_u64 v[2:3], s[22:23], 0, v[2:3]
	v_lshl_add_u64 v[10:11], v[2:3], 0, s[60:61]
	global_load_dwordx4 v[2:5], v[4:5], off
	s_nop 0
	global_load_dwordx4 v[6:9], v[10:11], off
	v_add_co_u32_e32 v20, vcc, 0x2800, v10
	s_nop 1
	v_addc_co_u32_e32 v21, vcc, 0, v11, vcc
	global_load_dwordx4 v[24:27], v[20:21], off
	v_add_co_u32_e32 v20, vcc, 0x5000, v10
	s_nop 1
	v_addc_co_u32_e32 v21, vcc, 0, v11, vcc
	global_load_dwordx4 v[28:31], v[20:21], off
	v_add_co_u32_e32 v20, vcc, 0x7800, v10
	s_nop 1
	v_addc_co_u32_e32 v21, vcc, 0, v11, vcc
	global_load_dwordx4 v[32:35], v[20:21], off
	v_lshlrev_b32_e32 v12, 16, v102
	v_lshlrev_b32_e32 v13, 16, v103
	s_waitcnt vmcnt(4)
; __device__ __forceinline__ float bflo(unsigned v) { return __uint_as_float(v << 16); }
; __device__ __forceinline__ float bfhi(unsigned v) { return __uint_as_float(v & 0xffff0000u); }
; __device__ __forceinline__ unsigned pack2(float a, float b) { return (unsigned)f2bf(a) | ((unsigned)f2bf(b) << 16); }
; __device__ void odd_tiles(int tid_, int bid_, int nblk_, const Params& p, int oi, int mode, bool skip_ctx, char* smem) {
;     ...
; #pragma unroll
;     for (int i = 0; i < 5; ++i) {
;       int e = tid + i * 256, t = e / 40, c4 = (e % 40) * 4;
;       float4 acc = *(const float4*)(p.od_conv_b + oi * DC + cb + c4);
; #pragma unroll
;       for (int j = 0; j < 4; ++j) {
;         uint2 xv = xr[i][j];
;         float4 wv = *(const float4*)(p.od_conv_w + ((size_t)oi * 4 + j) * DC + cb + c4);
;         acc.x += bflo(xv.x) * wv.x; acc.y += bfhi(xv.x) * wv.y; acc.z += bflo(xv.y) * wv.z; acc.w += bfhi(xv.y) * wv.w;
;       }
;       uint2 o;
;       o.x = pack2(acc.x, acc.y);
;       o.y = pack2(acc.z, acc.w);
;       *(uint2*)(sU + t * 168 + c4) = o;
;     }
;     lds_barrier();
	v_mov_b32_e32 v18, v2
	s_waitcnt vmcnt(3)
	v_mov_b32_e32 v17, v8
	v_mov_b32_e32 v19, v4
	v_mov_b32_e32 v8, v7
	v_mov_b32_e32 v4, v3
	v_mov_b32_e32 v16, v6
	v_pk_fma_f32 v[6:7], v[8:9], v[14:15], v[4:5]
	v_pk_fma_f32 v[12:13], v[16:17], v[12:13], v[18:19]
	v_lshlrev_b32_e32 v9, 16, v109
	v_lshlrev_b32_e32 v8, 16, v108
	s_waitcnt vmcnt(2)
	v_mov_b32_e32 v2, v24
	v_mov_b32_e32 v3, v25
	v_mov_b32_e32 v4, v26
	v_mov_b32_e32 v5, v27
	v_mov_b32_e32 v14, v2
	v_mov_b32_e32 v15, v4
	v_pk_fma_f32 v[8:9], v[14:15], v[8:9], v[12:13]
	v_and_b32_e32 v13, 0xffff0000, v109
	v_and_b32_e32 v12, 0xffff0000, v108
	v_mov_b32_e32 v4, v3
	v_pk_fma_f32 v[6:7], v[4:5], v[12:13], v[6:7]
	v_lshlrev_b32_e32 v13, 16, v127
	v_lshlrev_b32_e32 v12, 16, v126
	s_waitcnt vmcnt(1)
	v_mov_b32_e32 v2, v28
	v_mov_b32_e32 v3, v29
	v_mov_b32_e32 v4, v30
	v_mov_b32_e32 v5, v31
	v_mov_b32_e32 v14, v2
	v_mov_b32_e32 v15, v4
	v_pk_fma_f32 v[8:9], v[14:15], v[12:13], v[8:9]
	v_and_b32_e32 v13, 0xffff0000, v127
	v_and_b32_e32 v12, 0xffff0000, v126
	v_mov_b32_e32 v4, v3
	v_pk_fma_f32 v[6:7], v[4:5], v[12:13], v[6:7]
	v_lshlrev_b32_e32 v11, 16, v133
	v_lshlrev_b32_e32 v10, 16, v132
	v_and_b32_e32 v14, 0xffff0000, v140
	v_and_b32_e32 v15, 0xffff0000, v141
	s_waitcnt vmcnt(0)
	v_mov_b32_e32 v2, v32
	v_mov_b32_e32 v3, v33
	v_mov_b32_e32 v4, v34
	v_mov_b32_e32 v5, v35
	v_mov_b32_e32 v12, v2
	v_mov_b32_e32 v13, v4
	v_pk_fma_f32 v[8:9], v[12:13], v[10:11], v[8:9]
	v_and_b32_e32 v11, 0xffff0000, v133
	v_and_b32_e32 v10, 0xffff0000, v132
	v_mov_b32_e32 v4, v3
	v_pk_fma_f32 v[2:3], v[4:5], v[10:11], v[6:7]
	v_and_b32_sdwa v1, v9, v198 dst_sel:DWORD dst_unused:UNUSED_PAD src0_sel:WORD_1 src1_sel:DWORD
	v_and_b32_sdwa v5, v3, v198 dst_sel:DWORD dst_unused:UNUSED_PAD src0_sel:WORD_1 src1_sel:DWORD
	v_and_b32_sdwa v6, v2, v198 dst_sel:DWORD dst_unused:UNUSED_PAD src0_sel:WORD_1 src1_sel:DWORD
	v_and_b32_sdwa v4, v8, v198 dst_sel:DWORD dst_unused:UNUSED_PAD src0_sel:WORD_1 src1_sel:DWORD
	v_add3_u32 v3, v3, v5, s63
	v_add3_u32 v2, v2, v6, s63
	v_add3_u32 v4, v8, v4, s63
	v_add3_u32 v1, v9, v1, s63
	v_and_b32_e32 v3, 0xffff0000, v3
	v_and_b32_e32 v2, 0xffff0000, v2
	v_or_b32_sdwa v3, v3, v1 dst_sel:DWORD dst_unused:UNUSED_PAD src0_sel:DWORD src1_sel:WORD_1
	v_or_b32_sdwa v2, v2, v4 dst_sel:DWORD dst_unused:UNUSED_PAD src0_sel:DWORD src1_sel:WORD_1
	ds_write_b64 v182, v[2:3]
	v_lshlrev_b64 v[2:3], 2, v[106:107]
	v_lshl_add_u64 v[4:5], s[20:21], 0, v[2:3]
	v_lshl_add_u64 v[2:3], s[22:23], 0, v[2:3]
	v_lshl_add_u64 v[10:11], v[2:3], 0, s[60:61]
	global_load_dwordx4 v[2:5], v[4:5], off
	s_nop 0
	global_load_dwordx4 v[6:9], v[10:11], off
	v_add_co_u32_e32 v20, vcc, 0x2800, v10
	s_nop 1
	v_addc_co_u32_e32 v21, vcc, 0, v11, vcc
	global_load_dwordx4 v[24:27], v[20:21], off
	v_add_co_u32_e32 v20, vcc, 0x5000, v10
	s_nop 1
	v_addc_co_u32_e32 v21, vcc, 0, v11, vcc
	global_load_dwordx4 v[28:31], v[20:21], off
	v_add_co_u32_e32 v20, vcc, 0x7800, v10
	s_nop 1
	v_addc_co_u32_e32 v21, vcc, 0, v11, vcc
	global_load_dwordx4 v[32:35], v[20:21], off
	v_lshlrev_b32_e32 v12, 16, v140
	v_lshlrev_b32_e32 v13, 16, v141
	s_waitcnt vmcnt(4)
	v_mov_b32_e32 v18, v2
	s_waitcnt vmcnt(3)
	v_mov_b32_e32 v17, v8
	v_mov_b32_e32 v19, v4
	v_mov_b32_e32 v8, v7
	v_mov_b32_e32 v4, v3
	v_mov_b32_e32 v16, v6
	v_pk_fma_f32 v[6:7], v[8:9], v[14:15], v[4:5]
	v_pk_fma_f32 v[12:13], v[16:17], v[12:13], v[18:19]
	v_lshlrev_b32_e32 v9, 16, v143
	v_lshlrev_b32_e32 v8, 16, v142
	s_waitcnt vmcnt(2)
	v_mov_b32_e32 v2, v24
	v_mov_b32_e32 v3, v25
	v_mov_b32_e32 v4, v26
	v_mov_b32_e32 v5, v27
	v_mov_b32_e32 v14, v2
	v_mov_b32_e32 v15, v4
	v_pk_fma_f32 v[12:13], v[14:15], v[8:9], v[12:13]
	v_and_b32_e32 v9, 0xffff0000, v143
	v_and_b32_e32 v8, 0xffff0000, v142
	v_mov_b32_e32 v4, v3
	v_pk_fma_f32 v[2:3], v[4:5], v[8:9], v[6:7]
	s_nop 1
	v_lshlrev_b32_e32 v5, 16, v145
	v_lshlrev_b32_e32 v4, 16, v144
	s_waitcnt vmcnt(1)
	v_mov_b32_e32 v6, v28
	v_mov_b32_e32 v7, v29
	v_mov_b32_e32 v8, v30
	v_mov_b32_e32 v9, v31
	v_mov_b32_e32 v14, v6
	v_mov_b32_e32 v15, v8
	v_pk_fma_f32 v[4:5], v[14:15], v[4:5], v[12:13]
	v_and_b32_e32 v13, 0xffff0000, v145
	v_and_b32_e32 v12, 0xffff0000, v144
	v_mov_b32_e32 v8, v7
	v_pk_fma_f32 v[2:3], v[8:9], v[12:13], v[2:3]
	v_lshlrev_b32_e32 v11, 16, v147
	v_lshlrev_b32_e32 v10, 16, v146
	s_waitcnt vmcnt(0)
	v_mov_b32_e32 v6, v32
	v_mov_b32_e32 v7, v33
	v_mov_b32_e32 v8, v34
	v_mov_b32_e32 v9, v35
	v_mov_b32_e32 v12, v6
	v_mov_b32_e32 v13, v8
	v_pk_fma_f32 v[4:5], v[12:13], v[10:11], v[4:5]
	v_and_b32_e32 v11, 0xffff0000, v147
	v_and_b32_e32 v10, 0xffff0000, v146
	v_mov_b32_e32 v8, v7
	v_pk_fma_f32 v[2:3], v[8:9], v[10:11], v[2:3]
	v_and_b32_sdwa v1, v5, v198 dst_sel:DWORD dst_unused:UNUSED_PAD src0_sel:WORD_1 src1_sel:DWORD
	v_and_b32_sdwa v6, v4, v198 dst_sel:DWORD dst_unused:UNUSED_PAD src0_sel:WORD_1 src1_sel:DWORD
	v_add3_u32 v4, v4, v6, s63
	v_add3_u32 v1, v5, v1, s63
	v_and_b32_sdwa v5, v3, v198 dst_sel:DWORD dst_unused:UNUSED_PAD src0_sel:WORD_1 src1_sel:DWORD
	v_and_b32_sdwa v6, v2, v198 dst_sel:DWORD dst_unused:UNUSED_PAD src0_sel:WORD_1 src1_sel:DWORD
	v_add3_u32 v3, v3, v5, s63
	v_add3_u32 v2, v2, v6, s63
	v_and_b32_e32 v3, 0xffff0000, v3
	v_and_b32_e32 v2, 0xffff0000, v2
	v_or_b32_sdwa v3, v3, v1 dst_sel:DWORD dst_unused:UNUSED_PAD src0_sel:DWORD src1_sel:WORD_1
	v_or_b32_sdwa v2, v2, v4 dst_sel:DWORD dst_unused:UNUSED_PAD src0_sel:DWORD src1_sel:WORD_1
	ds_write_b64 v184, v[2:3]
	s_waitcnt lgkmcnt(0)
	s_barrier
	s_branch .LBB0_102

; __device__ __forceinline__ float bflo(unsigned v) { return __uint_as_float(v << 16); }
; __device__ __forceinline__ float bfhi(unsigned v) { return __uint_as_float(v & 0xffff0000u); }
; __device__ __forceinline__ unsigned pack2(float a, float b) { return (unsigned)f2bf(a) | ((unsigned)f2bf(b) << 16); }
; __device__ void odd_tiles(int tid_, int bid_, int nblk_, const Params& p, int oi, int mode, bool skip_ctx, char* smem) {
;     ...
; #pragma unroll
;     for (int i = 0; i < 5; ++i) {
;       int e = tid + i * 256, t = e / 40, c4 = (e % 40) * 4;
;       float4 acc = *(const float4*)(p.od_conv_b + oi * DC + cb + c4);
; #pragma unroll
;       for (int j = 0; j < 4; ++j) {
;         uint2 xv = xr[i][j];
;         float4 wv = *(const float4*)(p.od_conv_w + ((size_t)oi * 4 + j) * DC + cb + c4);
;         acc.x += bflo(xv.x) * wv.x; acc.y += bfhi(xv.x) * wv.y; acc.z += bflo(xv.y) * wv.z; acc.w += bfhi(xv.y) * wv.w;
;       }
;       uint2 o;
;       o.x = pack2(acc.x, acc.y);
;       o.y = pack2(acc.z, acc.w);
;       *(uint2*)(sU + t * 168 + c4) = o;
;     }
.LBB0_229:
	s_and_b32 s28, s27, 15
	s_mul_i32 s0, s28, 0xa0
	s_lshl_b32 s22, s0, 2
	s_add_u32 s20, s25, s22
	v_readlane_b32 s64, v252, 33
	s_addc_u32 s21, s26, 0
	v_readlane_b32 s76, v252, 45
	v_readlane_b32 s77, v252, 46
	s_add_u32 s22, s76, s22
	v_lshlrev_b64 v[2:3], 2, v[98:99]
	s_addc_u32 s23, s77, 0
	v_lshl_add_u64 v[4:5], s[20:21], 0, v[2:3]
	v_lshl_add_u64 v[2:3], s[22:23], 0, v[2:3]
	s_mov_b32 s61, s1
	v_lshl_add_u64 v[10:11], v[2:3], 0, s[60:61]
	global_load_dwordx4 v[2:5], v[4:5], off
	s_nop 0
	global_load_dwordx4 v[6:9], v[10:11], off
	v_add_co_u32_e32 v20, vcc, 0x2800, v10
	s_nop 1
	v_addc_co_u32_e32 v21, vcc, 0, v11, vcc
	global_load_dwordx4 v[24:27], v[20:21], off
	v_add_co_u32_e32 v20, vcc, 0x5000, v10
	s_nop 1
	v_addc_co_u32_e32 v21, vcc, 0, v11, vcc
	global_load_dwordx4 v[28:31], v[20:21], off
	v_add_co_u32_e32 v20, vcc, 0x7800, v10
	s_nop 1
	v_addc_co_u32_e32 v21, vcc, 0, v11, vcc
	global_load_dwordx4 v[32:35], v[20:21], off
	s_movk_i32 s34, 0x2000
	v_and_b32_e32 v14, 0xffff0000, v70
	v_and_b32_e32 v15, 0xffff0000, v71
	v_lshlrev_b32_e32 v12, 16, v70
	v_lshlrev_b32_e32 v13, 16, v71
	s_movk_i32 s35, 0x5000
	s_movk_i32 s36, 0x7000
	s_movk_i32 s2, 0x2000
	v_readlane_b32 s65, v252, 34
	v_readlane_b32 s66, v252, 35
	v_readlane_b32 s67, v252, 36
	v_readlane_b32 s68, v252, 37
	v_readlane_b32 s69, v252, 38
	v_readlane_b32 s70, v252, 39
	v_readlane_b32 s71, v252, 40
	v_readlane_b32 s72, v252, 41
	v_readlane_b32 s73, v252, 42
	v_readlane_b32 s74, v252, 43
	v_readlane_b32 s75, v252, 44
	v_readlane_b32 s78, v252, 47
	v_readlane_b32 s79, v252, 48
	s_waitcnt vmcnt(4)
	v_mov_b32_e32 v18, v2
	s_waitcnt vmcnt(3)
	v_mov_b32_e32 v17, v8
	v_mov_b32_e32 v19, v4
	v_mov_b32_e32 v8, v7
	v_mov_b32_e32 v4, v3
	v_mov_b32_e32 v16, v6
	v_pk_fma_f32 v[6:7], v[8:9], v[14:15], v[4:5]
	v_pk_fma_f32 v[12:13], v[16:17], v[12:13], v[18:19]
	v_lshlrev_b32_e32 v9, 16, v73
	v_lshlrev_b32_e32 v8, 16, v72
	s_waitcnt vmcnt(2)
	v_mov_b32_e32 v2, v24
	v_mov_b32_e32 v3, v25
	v_mov_b32_e32 v4, v26
	v_mov_b32_e32 v5, v27
	v_mov_b32_e32 v14, v2
	v_mov_b32_e32 v15, v4
	v_pk_fma_f32 v[8:9], v[14:15], v[8:9], v[12:13]
	v_and_b32_e32 v13, 0xffff0000, v73
	v_and_b32_e32 v12, 0xffff0000, v72
	v_mov_b32_e32 v4, v3
	v_pk_fma_f32 v[6:7], v[4:5], v[12:13], v[6:7]
	v_lshlrev_b32_e32 v13, 16, v75
	v_lshlrev_b32_e32 v12, 16, v74
	s_waitcnt vmcnt(1)
	v_mov_b32_e32 v2, v28
	v_mov_b32_e32 v3, v29
	v_mov_b32_e32 v4, v30
	v_mov_b32_e32 v5, v31
	v_mov_b32_e32 v14, v2
	v_mov_b32_e32 v15, v4
	v_pk_fma_f32 v[8:9], v[14:15], v[12:13], v[8:9]
	v_and_b32_e32 v13, 0xffff0000, v75
	v_and_b32_e32 v12, 0xffff0000, v74
	v_mov_b32_e32 v4, v3
	v_pk_fma_f32 v[6:7], v[4:5], v[12:13], v[6:7]
	v_lshlrev_b32_e32 v11, 16, v77
	v_lshlrev_b32_e32 v10, 16, v76
	v_and_b32_e32 v14, 0xffff0000, v78
	v_and_b32_e32 v15, 0xffff0000, v79
	s_waitcnt vmcnt(0)
	v_mov_b32_e32 v2, v32
	v_mov_b32_e32 v3, v33
	v_mov_b32_e32 v4, v34
	v_mov_b32_e32 v5, v35
	v_mov_b32_e32 v12, v2
	v_mov_b32_e32 v13, v4
	v_pk_fma_f32 v[8:9], v[12:13], v[10:11], v[8:9]
	v_and_b32_e32 v11, 0xffff0000, v77
	v_and_b32_e32 v10, 0xffff0000, v76
	v_mov_b32_e32 v4, v3
	v_pk_fma_f32 v[2:3], v[4:5], v[10:11], v[6:7]
	v_and_b32_sdwa v1, v9, v198 dst_sel:DWORD dst_unused:UNUSED_PAD src0_sel:WORD_1 src1_sel:DWORD
	v_and_b32_sdwa v5, v3, v198 dst_sel:DWORD dst_unused:UNUSED_PAD src0_sel:WORD_1 src1_sel:DWORD
	v_and_b32_sdwa v6, v2, v198 dst_sel:DWORD dst_unused:UNUSED_PAD src0_sel:WORD_1 src1_sel:DWORD
	v_and_b32_sdwa v4, v8, v198 dst_sel:DWORD dst_unused:UNUSED_PAD src0_sel:WORD_1 src1_sel:DWORD
	v_add3_u32 v3, v3, v5, s63
	v_add3_u32 v2, v2, v6, s63
	v_add3_u32 v4, v8, v4, s63
	v_add3_u32 v1, v9, v1, s63
	v_and_b32_e32 v3, 0xffff0000, v3
	v_and_b32_e32 v2, 0xffff0000, v2
	v_or_b32_sdwa v3, v3, v1 dst_sel:DWORD dst_unused:UNUSED_PAD src0_sel:DWORD src1_sel:WORD_1
	v_or_b32_sdwa v2, v2, v4 dst_sel:DWORD dst_unused:UNUSED_PAD src0_sel:DWORD src1_sel:WORD_1
	ds_write_b64 v167, v[2:3]
	v_lshlrev_b64 v[2:3], 2, v[100:101]
	v_lshl_add_u64 v[4:5], s[20:21], 0, v[2:3]
	v_lshl_add_u64 v[2:3], s[22:23], 0, v[2:3]
	v_lshl_add_u64 v[10:11], v[2:3], 0, s[60:61]
	global_load_dwordx4 v[2:5], v[4:5], off
	s_nop 0
	global_load_dwordx4 v[6:9], v[10:11], off
	v_add_co_u32_e32 v20, vcc, 0x2800, v10
	s_nop 1
	v_addc_co_u32_e32 v21, vcc, 0, v11, vcc
	global_load_dwordx4 v[24:27], v[20:21], off
	v_add_co_u32_e32 v20, vcc, 0x5000, v10
	s_nop 1
	v_addc_co_u32_e32 v21, vcc, 0, v11, vcc
	global_load_dwordx4 v[28:31], v[20:21], off
	v_add_co_u32_e32 v20, vcc, 0x7800, v10
	s_nop 1
	v_addc_co_u32_e32 v21, vcc, 0, v11, vcc
	global_load_dwordx4 v[32:35], v[20:21], off
	v_lshlrev_b32_e32 v12, 16, v78
	v_lshlrev_b32_e32 v13, 16, v79
	s_waitcnt vmcnt(4)
	v_mov_b32_e32 v18, v2
	s_waitcnt vmcnt(3)
	v_mov_b32_e32 v17, v8
	v_mov_b32_e32 v19, v4
	v_mov_b32_e32 v8, v7
	v_mov_b32_e32 v4, v3
	v_mov_b32_e32 v16, v6
	v_pk_fma_f32 v[6:7], v[8:9], v[14:15], v[4:5]
	v_pk_fma_f32 v[12:13], v[16:17], v[12:13], v[18:19]
	v_lshlrev_b32_e32 v9, 16, v81
	v_lshlrev_b32_e32 v8, 16, v80
	s_waitcnt vmcnt(2)
	v_mov_b32_e32 v2, v24
	v_mov_b32_e32 v3, v25
	v_mov_b32_e32 v4, v26
	v_mov_b32_e32 v5, v27
	v_mov_b32_e32 v14, v2
	v_mov_b32_e32 v15, v4
	v_pk_fma_f32 v[8:9], v[14:15], v[8:9], v[12:13]
	v_and_b32_e32 v13, 0xffff0000, v81
	v_and_b32_e32 v12, 0xffff0000, v80
	v_mov_b32_e32 v4, v3
	v_pk_fma_f32 v[6:7], v[4:5], v[12:13], v[6:7]
	v_lshlrev_b32_e32 v13, 16, v83
	v_lshlrev_b32_e32 v12, 16, v82
	s_waitcnt vmcnt(1)
; __device__ __forceinline__ float bflo(unsigned v) { return __uint_as_float(v << 16); }
; __device__ __forceinline__ float bfhi(unsigned v) { return __uint_as_float(v & 0xffff0000u); }
; __device__ __forceinline__ unsigned pack2(float a, float b) { return (unsigned)f2bf(a) | ((unsigned)f2bf(b) << 16); }
; __device__ void odd_tiles(int tid_, int bid_, int nblk_, const Params& p, int oi, int mode, bool skip_ctx, char* smem) {
;     ...
; #pragma unroll
;     for (int i = 0; i < 5; ++i) {
;       int e = tid + i * 256, t = e / 40, c4 = (e % 40) * 4;
;       float4 acc = *(const float4*)(p.od_conv_b + oi * DC + cb + c4);
; #pragma unroll
;       for (int j = 0; j < 4; ++j) {
;         uint2 xv = xr[i][j];
;         float4 wv = *(const float4*)(p.od_conv_w + ((size_t)oi * 4 + j) * DC + cb + c4);
;         acc.x += bflo(xv.x) * wv.x; acc.y += bfhi(xv.x) * wv.y; acc.z += bflo(xv.y) * wv.z; acc.w += bfhi(xv.y) * wv.w;
;       }
;       uint2 o;
;       o.x = pack2(acc.x, acc.y);
;       o.y = pack2(acc.z, acc.w);
;       *(uint2*)(sU + t * 168 + c4) = o;
;     }
	v_mov_b32_e32 v2, v28
	v_mov_b32_e32 v3, v29
	v_mov_b32_e32 v4, v30
	v_mov_b32_e32 v5, v31
	v_mov_b32_e32 v14, v2
	v_mov_b32_e32 v15, v4
	v_pk_fma_f32 v[8:9], v[14:15], v[12:13], v[8:9]
	v_and_b32_e32 v13, 0xffff0000, v83
	v_and_b32_e32 v12, 0xffff0000, v82
	v_mov_b32_e32 v4, v3
	v_pk_fma_f32 v[6:7], v[4:5], v[12:13], v[6:7]
	v_lshlrev_b32_e32 v11, 16, v85
	v_lshlrev_b32_e32 v10, 16, v84
	v_and_b32_e32 v14, 0xffff0000, v86
	v_and_b32_e32 v15, 0xffff0000, v87
	s_waitcnt vmcnt(0)
	v_mov_b32_e32 v2, v32
	v_mov_b32_e32 v3, v33
	v_mov_b32_e32 v4, v34
	v_mov_b32_e32 v5, v35
	v_mov_b32_e32 v12, v2
	v_mov_b32_e32 v13, v4
	v_pk_fma_f32 v[8:9], v[12:13], v[10:11], v[8:9]
	v_and_b32_e32 v11, 0xffff0000, v85
	v_and_b32_e32 v10, 0xffff0000, v84
	v_mov_b32_e32 v4, v3
	v_pk_fma_f32 v[2:3], v[4:5], v[10:11], v[6:7]
	v_and_b32_sdwa v1, v9, v198 dst_sel:DWORD dst_unused:UNUSED_PAD src0_sel:WORD_1 src1_sel:DWORD
	v_and_b32_sdwa v5, v3, v198 dst_sel:DWORD dst_unused:UNUSED_PAD src0_sel:WORD_1 src1_sel:DWORD
	v_and_b32_sdwa v6, v2, v198 dst_sel:DWORD dst_unused:UNUSED_PAD src0_sel:WORD_1 src1_sel:DWORD
	v_and_b32_sdwa v4, v8, v198 dst_sel:DWORD dst_unused:UNUSED_PAD src0_sel:WORD_1 src1_sel:DWORD
	v_add3_u32 v3, v3, v5, s63
	v_add3_u32 v2, v2, v6, s63
	v_add3_u32 v4, v8, v4, s63
	v_add3_u32 v1, v9, v1, s63
	v_and_b32_e32 v3, 0xffff0000, v3
	v_and_b32_e32 v2, 0xffff0000, v2
	v_or_b32_sdwa v3, v3, v1 dst_sel:DWORD dst_unused:UNUSED_PAD src0_sel:DWORD src1_sel:WORD_1
	v_or_b32_sdwa v2, v2, v4 dst_sel:DWORD dst_unused:UNUSED_PAD src0_sel:DWORD src1_sel:WORD_1
	ds_write_b64 v169, v[2:3]
	v_lshlrev_b64 v[2:3], 2, v[102:103]
	v_lshl_add_u64 v[4:5], s[20:21], 0, v[2:3]
	v_lshl_add_u64 v[2:3], s[22:23], 0, v[2:3]
	v_lshl_add_u64 v[2:3], v[2:3], 0, s[60:61]
	global_load_dwordx4 v[4:7], v[4:5], off
	s_nop 0
	global_load_dwordx4 v[8:11], v[2:3], off
	v_add_co_u32_e32 v20, vcc, 0x2800, v2
	s_nop 1
	v_addc_co_u32_e32 v21, vcc, 0, v3, vcc
	global_load_dwordx4 v[24:27], v[20:21], off
	v_add_co_u32_e32 v20, vcc, 0x5000, v2
	s_nop 1
	v_addc_co_u32_e32 v21, vcc, 0, v3, vcc
	global_load_dwordx4 v[28:31], v[20:21], off
	v_add_co_u32_e32 v20, vcc, 0x7800, v2
	s_nop 1
	v_addc_co_u32_e32 v21, vcc, 0, v3, vcc
	global_load_dwordx4 v[32:35], v[20:21], off
	v_lshlrev_b32_e32 v12, 16, v86
	v_lshlrev_b32_e32 v13, 16, v87
	s_waitcnt vmcnt(4)
	v_mov_b32_e32 v18, v4
	s_waitcnt vmcnt(3)
	v_mov_b32_e32 v17, v10
	v_mov_b32_e32 v19, v6
	v_mov_b32_e32 v10, v9
	v_mov_b32_e32 v6, v5
	v_mov_b32_e32 v16, v8
	v_pk_fma_f32 v[8:9], v[10:11], v[14:15], v[6:7]
	v_pk_fma_f32 v[12:13], v[16:17], v[12:13], v[18:19]
	v_lshlrev_b32_e32 v11, 16, v89
	v_lshlrev_b32_e32 v10, 16, v88
	s_waitcnt vmcnt(2)
	v_mov_b32_e32 v4, v24
	v_mov_b32_e32 v5, v25
	v_mov_b32_e32 v6, v26
	v_mov_b32_e32 v7, v27
	v_mov_b32_e32 v14, v4
	v_mov_b32_e32 v15, v6
	v_pk_fma_f32 v[10:11], v[14:15], v[10:11], v[12:13]
	v_and_b32_e32 v13, 0xffff0000, v89
	v_and_b32_e32 v12, 0xffff0000, v88
	v_mov_b32_e32 v6, v5
	v_pk_fma_f32 v[8:9], v[6:7], v[12:13], v[8:9]
	v_lshlrev_b32_e32 v13, 16, v91
	s_nop 0
	v_lshlrev_b32_e32 v12, 16, v90
	s_waitcnt vmcnt(1)
	v_mov_b32_e32 v4, v28
	v_mov_b32_e32 v5, v29
	v_mov_b32_e32 v6, v30
	v_mov_b32_e32 v7, v31
	v_mov_b32_e32 v14, v4
	v_mov_b32_e32 v15, v6
	v_mov_b32_e32 v6, v5
	v_pk_fma_f32 v[10:11], v[14:15], v[12:13], v[10:11]
	v_and_b32_e32 v13, 0xffff0000, v91
	v_and_b32_e32 v12, 0xffff0000, v90
	v_pk_fma_f32 v[6:7], v[6:7], v[12:13], v[8:9]
	v_lshlrev_b32_e32 v9, 16, v93
	v_lshlrev_b32_e32 v8, 16, v92
	v_and_b32_e32 v14, 0xffff0000, v104
	v_and_b32_e32 v15, 0xffff0000, v105
	s_waitcnt vmcnt(0)
	v_mov_b32_e32 v2, v32
	v_mov_b32_e32 v3, v33
	v_mov_b32_e32 v4, v34
	v_mov_b32_e32 v5, v35
	v_mov_b32_e32 v12, v2
	v_mov_b32_e32 v13, v4
	v_pk_fma_f32 v[8:9], v[12:13], v[8:9], v[10:11]
	v_and_b32_e32 v11, 0xffff0000, v93
	v_and_b32_e32 v10, 0xffff0000, v92
	v_mov_b32_e32 v4, v3
	v_pk_fma_f32 v[2:3], v[4:5], v[10:11], v[6:7]
	v_and_b32_sdwa v1, v9, v198 dst_sel:DWORD dst_unused:UNUSED_PAD src0_sel:WORD_1 src1_sel:DWORD
	v_and_b32_sdwa v5, v3, v198 dst_sel:DWORD dst_unused:UNUSED_PAD src0_sel:WORD_1 src1_sel:DWORD
	v_and_b32_sdwa v6, v2, v198 dst_sel:DWORD dst_unused:UNUSED_PAD src0_sel:WORD_1 src1_sel:DWORD
	v_and_b32_sdwa v4, v8, v198 dst_sel:DWORD dst_unused:UNUSED_PAD src0_sel:WORD_1 src1_sel:DWORD
	v_add3_u32 v3, v3, v5, s63
	v_add3_u32 v2, v2, v6, s63
	v_add3_u32 v4, v8, v4, s63
	v_add3_u32 v1, v9, v1, s63
	v_and_b32_e32 v3, 0xffff0000, v3
	v_and_b32_e32 v2, 0xffff0000, v2
	v_or_b32_sdwa v3, v3, v1 dst_sel:DWORD dst_unused:UNUSED_PAD src0_sel:DWORD src1_sel:WORD_1
	v_or_b32_sdwa v2, v2, v4 dst_sel:DWORD dst_unused:UNUSED_PAD src0_sel:DWORD src1_sel:WORD_1
	ds_write_b64 v171, v[2:3]
	v_lshlrev_b64 v[2:3], 2, v[106:107]
	v_lshl_add_u64 v[4:5], s[20:21], 0, v[2:3]
	v_lshl_add_u64 v[2:3], s[22:23], 0, v[2:3]
	v_lshl_add_u64 v[10:11], v[2:3], 0, s[60:61]
	global_load_dwordx4 v[2:5], v[4:5], off
	s_nop 0
	global_load_dwordx4 v[6:9], v[10:11], off
	v_add_co_u32_e32 v20, vcc, 0x2800, v10
	s_nop 1
	v_addc_co_u32_e32 v21, vcc, 0, v11, vcc
	global_load_dwordx4 v[24:27], v[20:21], off
	v_add_co_u32_e32 v20, vcc, 0x5000, v10
	s_nop 1
	v_addc_co_u32_e32 v21, vcc, 0, v11, vcc
	global_load_dwordx4 v[28:31], v[20:21], off
	v_add_co_u32_e32 v20, vcc, 0x7800, v10
	s_nop 1
	v_addc_co_u32_e32 v21, vcc, 0, v11, vcc
	global_load_dwordx4 v[32:35], v[20:21], off
	v_lshlrev_b32_e32 v12, 16, v104
	v_lshlrev_b32_e32 v13, 16, v105
	s_waitcnt vmcnt(4)
	v_mov_b32_e32 v18, v2
	s_waitcnt vmcnt(3)
; __device__ __forceinline__ float bflo(unsigned v) { return __uint_as_float(v << 16); }
; __device__ __forceinline__ float bfhi(unsigned v) { return __uint_as_float(v & 0xffff0000u); }
; __device__ __forceinline__ unsigned pack2(float a, float b) { return (unsigned)f2bf(a) | ((unsigned)f2bf(b) << 16); }
; __device__ void odd_tiles(int tid_, int bid_, int nblk_, const Params& p, int oi, int mode, bool skip_ctx, char* smem) {
;     ...
; #pragma unroll
;     for (int i = 0; i < 5; ++i) {
;       int e = tid + i * 256, t = e / 40, c4 = (e % 40) * 4;
;       float4 acc = *(const float4*)(p.od_conv_b + oi * DC + cb + c4);
; #pragma unroll
;       for (int j = 0; j < 4; ++j) {
;         uint2 xv = xr[i][j];
;         float4 wv = *(const float4*)(p.od_conv_w + ((size_t)oi * 4 + j) * DC + cb + c4);
;         acc.x += bflo(xv.x) * wv.x; acc.y += bfhi(xv.x) * wv.y; acc.z += bflo(xv.y) * wv.z; acc.w += bfhi(xv.y) * wv.w;
;       }
;       uint2 o;
;       o.x = pack2(acc.x, acc.y);
;       o.y = pack2(acc.z, acc.w);
;       *(uint2*)(sU + t * 168 + c4) = o;
;     }
;     lds_barrier();
;     int nxt = tile + nblk_;
;     while (nxt < ntiles && skip_ctx && ((nxt >> 4) % NCH) < 8) nxt += nblk_;
;     if (nxt < ntiles) ODD_PREFETCH(nxt)
	v_mov_b32_e32 v17, v8
	v_mov_b32_e32 v19, v4
	v_mov_b32_e32 v8, v7
	v_mov_b32_e32 v4, v3
	v_mov_b32_e32 v16, v6
	v_pk_fma_f32 v[6:7], v[8:9], v[14:15], v[4:5]
	v_pk_fma_f32 v[12:13], v[16:17], v[12:13], v[18:19]
	v_lshlrev_b32_e32 v9, 16, v111
	v_lshlrev_b32_e32 v8, 16, v110
	s_waitcnt vmcnt(2)
	v_mov_b32_e32 v2, v24
	v_mov_b32_e32 v3, v25
	v_mov_b32_e32 v4, v26
	v_mov_b32_e32 v5, v27
	v_mov_b32_e32 v14, v2
	v_mov_b32_e32 v15, v4
	v_pk_fma_f32 v[8:9], v[14:15], v[8:9], v[12:13]
	v_and_b32_e32 v13, 0xffff0000, v111
	v_and_b32_e32 v12, 0xffff0000, v110
	v_mov_b32_e32 v4, v3
	v_pk_fma_f32 v[6:7], v[4:5], v[12:13], v[6:7]
	v_lshlrev_b32_e32 v13, 16, v123
	v_lshlrev_b32_e32 v12, 16, v122
	s_waitcnt vmcnt(1)
	v_mov_b32_e32 v2, v28
	v_mov_b32_e32 v3, v29
	v_mov_b32_e32 v4, v30
	v_mov_b32_e32 v5, v31
	v_mov_b32_e32 v14, v2
	v_mov_b32_e32 v15, v4
	v_pk_fma_f32 v[8:9], v[14:15], v[12:13], v[8:9]
	v_and_b32_e32 v13, 0xffff0000, v123
	v_and_b32_e32 v12, 0xffff0000, v122
	v_mov_b32_e32 v4, v3
	v_pk_fma_f32 v[6:7], v[4:5], v[12:13], v[6:7]
	v_lshlrev_b32_e32 v11, 16, v137
	v_lshlrev_b32_e32 v10, 16, v136
	v_and_b32_e32 v14, 0xffff0000, v138
	v_and_b32_e32 v15, 0xffff0000, v139
	s_waitcnt vmcnt(0)
	v_mov_b32_e32 v2, v32
	v_mov_b32_e32 v3, v33
	v_mov_b32_e32 v4, v34
	v_mov_b32_e32 v5, v35
	v_mov_b32_e32 v12, v2
	v_mov_b32_e32 v13, v4
	v_pk_fma_f32 v[8:9], v[12:13], v[10:11], v[8:9]
	v_and_b32_e32 v11, 0xffff0000, v137
	v_and_b32_e32 v10, 0xffff0000, v136
	v_mov_b32_e32 v4, v3
	v_pk_fma_f32 v[2:3], v[4:5], v[10:11], v[6:7]
	v_and_b32_sdwa v1, v9, v198 dst_sel:DWORD dst_unused:UNUSED_PAD src0_sel:WORD_1 src1_sel:DWORD
	v_and_b32_sdwa v5, v3, v198 dst_sel:DWORD dst_unused:UNUSED_PAD src0_sel:WORD_1 src1_sel:DWORD
	v_and_b32_sdwa v6, v2, v198 dst_sel:DWORD dst_unused:UNUSED_PAD src0_sel:WORD_1 src1_sel:DWORD
	v_and_b32_sdwa v4, v8, v198 dst_sel:DWORD dst_unused:UNUSED_PAD src0_sel:WORD_1 src1_sel:DWORD
	v_add3_u32 v3, v3, v5, s63
	v_add3_u32 v2, v2, v6, s63
	v_add3_u32 v4, v8, v4, s63
	v_add3_u32 v1, v9, v1, s63
	v_and_b32_e32 v3, 0xffff0000, v3
	v_and_b32_e32 v2, 0xffff0000, v2
	v_or_b32_sdwa v3, v3, v1 dst_sel:DWORD dst_unused:UNUSED_PAD src0_sel:DWORD src1_sel:WORD_1
	v_or_b32_sdwa v2, v2, v4 dst_sel:DWORD dst_unused:UNUSED_PAD src0_sel:DWORD src1_sel:WORD_1
	ds_write_b64 v173, v[2:3]
	v_lshlrev_b64 v[2:3], 2, v[108:109]
	v_lshl_add_u64 v[4:5], s[20:21], 0, v[2:3]
	v_lshl_add_u64 v[2:3], s[22:23], 0, v[2:3]
	v_lshl_add_u64 v[10:11], v[2:3], 0, s[60:61]
	global_load_dwordx4 v[2:5], v[4:5], off
	s_nop 0
	global_load_dwordx4 v[6:9], v[10:11], off
	v_add_co_u32_e32 v20, vcc, 0x2800, v10
	s_nop 1
	v_addc_co_u32_e32 v21, vcc, 0, v11, vcc
	global_load_dwordx4 v[24:27], v[20:21], off
	v_add_co_u32_e32 v20, vcc, 0x5000, v10
	s_nop 1
	v_addc_co_u32_e32 v21, vcc, 0, v11, vcc
	global_load_dwordx4 v[28:31], v[20:21], off
	v_add_co_u32_e32 v20, vcc, 0x7800, v10
	s_nop 1
	v_addc_co_u32_e32 v21, vcc, 0, v11, vcc
	global_load_dwordx4 v[32:35], v[20:21], off
	v_lshlrev_b32_e32 v12, 16, v138
	v_lshlrev_b32_e32 v13, 16, v139
	v_readlane_b32 s20, v252, 13
	v_readlane_b32 s22, v252, 15
	s_add_i32 s27, s27, s22
	s_cmpk_gt_i32 s27, 0x21ff
	s_cselect_b64 s[86:87], -1, 0
	v_readlane_b32 s21, v252, 14
	v_readlane_b32 s23, v252, 16
	s_waitcnt vmcnt(4)
	v_mov_b32_e32 v18, v2
	s_waitcnt vmcnt(3)
	v_mov_b32_e32 v17, v8
	v_mov_b32_e32 v19, v4
	v_mov_b32_e32 v8, v7
	v_mov_b32_e32 v4, v3
	v_mov_b32_e32 v16, v6
	v_pk_fma_f32 v[6:7], v[8:9], v[14:15], v[4:5]
	v_pk_fma_f32 v[12:13], v[16:17], v[12:13], v[18:19]
	v_lshlrev_b32_e32 v9, 16, v141
	v_lshlrev_b32_e32 v8, 16, v140
	s_waitcnt vmcnt(2)
	v_mov_b32_e32 v2, v24
	v_mov_b32_e32 v3, v25
	v_mov_b32_e32 v4, v26
	v_mov_b32_e32 v5, v27
	v_mov_b32_e32 v14, v2
	v_mov_b32_e32 v15, v4
	v_pk_fma_f32 v[12:13], v[14:15], v[8:9], v[12:13]
	v_and_b32_e32 v9, 0xffff0000, v141
	v_and_b32_e32 v8, 0xffff0000, v140
	v_mov_b32_e32 v4, v3
	v_pk_fma_f32 v[2:3], v[4:5], v[8:9], v[6:7]
	s_nop 1
	v_lshlrev_b32_e32 v5, 16, v143
	v_lshlrev_b32_e32 v4, 16, v142
	s_waitcnt vmcnt(1)
	v_mov_b32_e32 v6, v28
	v_mov_b32_e32 v7, v29
	v_mov_b32_e32 v8, v30
	v_mov_b32_e32 v9, v31
	v_mov_b32_e32 v14, v6
	v_mov_b32_e32 v15, v8
	v_pk_fma_f32 v[4:5], v[14:15], v[4:5], v[12:13]
	v_and_b32_e32 v13, 0xffff0000, v143
	v_and_b32_e32 v12, 0xffff0000, v142
	v_mov_b32_e32 v8, v7
	v_pk_fma_f32 v[2:3], v[8:9], v[12:13], v[2:3]
	v_lshlrev_b32_e32 v11, 16, v145
	v_lshlrev_b32_e32 v10, 16, v144
	s_and_b64 vcc, exec, s[86:87]
	s_waitcnt vmcnt(0)
	v_mov_b32_e32 v6, v32
	v_mov_b32_e32 v7, v33
	v_mov_b32_e32 v8, v34
	v_mov_b32_e32 v9, v35
	v_mov_b32_e32 v12, v6
	v_mov_b32_e32 v13, v8
	v_pk_fma_f32 v[4:5], v[12:13], v[10:11], v[4:5]
	v_and_b32_e32 v11, 0xffff0000, v145
	v_and_b32_e32 v10, 0xffff0000, v144
	v_mov_b32_e32 v8, v7
	v_pk_fma_f32 v[2:3], v[8:9], v[10:11], v[2:3]
	v_and_b32_sdwa v1, v5, v198 dst_sel:DWORD dst_unused:UNUSED_PAD src0_sel:WORD_1 src1_sel:DWORD
	v_and_b32_sdwa v6, v4, v198 dst_sel:DWORD dst_unused:UNUSED_PAD src0_sel:WORD_1 src1_sel:DWORD
	v_add3_u32 v4, v4, v6, s63
	v_add3_u32 v1, v5, v1, s63
	v_and_b32_sdwa v5, v3, v198 dst_sel:DWORD dst_unused:UNUSED_PAD src0_sel:WORD_1 src1_sel:DWORD
	v_and_b32_sdwa v6, v2, v198 dst_sel:DWORD dst_unused:UNUSED_PAD src0_sel:WORD_1 src1_sel:DWORD
	v_add3_u32 v3, v3, v5, s63
	v_add3_u32 v2, v2, v6, s63
	v_and_b32_e32 v3, 0xffff0000, v3
	v_and_b32_e32 v2, 0xffff0000, v2
	v_or_b32_sdwa v3, v3, v1 dst_sel:DWORD dst_unused:UNUSED_PAD src0_sel:DWORD src1_sel:WORD_1
	v_or_b32_sdwa v2, v2, v4 dst_sel:DWORD dst_unused:UNUSED_PAD src0_sel:DWORD src1_sel:WORD_1
	ds_write_b64 v175, v[2:3]
	s_waitcnt lgkmcnt(0)
	s_barrier
	s_cbranch_vccnz .LBB0_275
	s_ashr_i32 s20, s27, 4
	s_mul_hi_i32 s21, s20, 0x78787879
	s_lshr_b32 s22, s21, 31
	s_ashr_i32 s21, s21, 6
	s_add_i32 s22, s21, s22
	s_mul_i32 s21, s22, 0x88
	s_sub_i32 s23, s20, s21
	s_cmp_gt_i32 s23, 7
	s_mov_b64 s[20:21], -1
	s_cbranch_scc0 .LBB0_232
	s_lshl_b32 s20, s23, 5
	s_lshl_b32 s34, s22, 12
	s_add_i32 s36, s20, 0xffffff00
	s_mov_b64 s[20:21], 0

; __device__ void norm_phase(int tid_, int bid_, int nblk_, const Params& p, int lprev, int lnext) {
;     ...
;   for (int row = gw; row < MTOT; row += nw) {
;     const bool isctx = row >= MLAT;
;     if (isctx && lprev == 3) continue;
;     const int mrow = isctx ? 4 : row / SEQ;
;     const float* xold;
;     float* xnew;
;     if (!isctx) {
;       xold = (lprev <= 0 ? p.x : p.out) + (size_t)row * D;
;       xnew = p.out + (size_t)row * D;
;     } else {
;       int cr = row - MLAT;
;       xold = (lprev <= 0 ? p.ctx : p.xc) + (size_t)cr * D;
;       xnew = p.xc + (size_t)cr * D;
;     }
;     float xv[32];
; #pragma unroll
;     for (int i = 0; i < 8; ++i) {
;       float4 v = *(const float4*)(xold + i * 256 + lane * 4);
;       xv[i * 4 + 0] = v.x; xv[i * 4 + 1] = v.y; xv[i * 4 + 2] = v.z; xv[i * 4 + 3] = v.w;
;     }
;     if (lprev >= 0) {
;       const float* zr = p.z + (size_t)row * D;
;       float zv[32];
;       float ss = 0.f;
; #pragma unroll
;       for (int i = 0; i < 8; ++i) {
;         float4 v = *(const float4*)(zr + i * 256 + lane * 4);
;         zv[i * 4 + 0] = v.x; zv[i * 4 + 1] = v.y; zv[i * 4 + 2] = v.z; zv[i * 4 + 3] = v.w;
;         ss += v.x * v.x + v.y * v.y + v.z * v.z + v.w * v.w;
;       }
;       ss = wave_sum(ss);
;       float rs = rsqrtf(ss * (1.f / 2048.f) + 1e-6f);
;       const float* gate = p.mod + (lprev * 5 + mrow) * 6144 + 4096;
;       const float* np = p.norm_post + lprev * D;
; #pragma unroll
;       for (int i = 0; i < 8; ++i) {
;         int idx = i * 256 + lane * 4;
;         float4 g4 = *(const float4*)(gate + idx);
;         float4 n4 = *(const float4*)(np + idx);
;         xv[i * 4 + 0] += g4.x * (zv[i * 4 + 0] * rs * n4.x);
;         xv[i * 4 + 1] += g4.y * (zv[i * 4 + 1] * rs * n4.y);
;         xv[i * 4 + 2] += g4.z * (zv[i * 4 + 2] * rs * n4.z);
;         xv[i * 4 + 3] += g4.w * (zv[i * 4 + 3] * rs * n4.w);
;         float4 o;
;         o.x = xv[i * 4 + 0]; o.y = xv[i * 4 + 1]; o.z = xv[i * 4 + 2]; o.w = xv[i * 4 + 3];
;         *(float4*)(xnew + idx) = o;
.LBB0_328:
	s_cmpk_gt_i32 s42, 0x3fff
	s_cselect_b64 s[20:21], -1, 0
	s_and_b64 s[22:23], s[38:39], s[20:21]
	s_and_b64 vcc, exec, s[22:23]
	s_cbranch_vccnz .LBB0_327
	global_load_dwordx4 v[30:33], v[70:71], off offset:-4096
	global_load_dwordx4 v[26:29], v[70:71], off offset:-3072
	global_load_dwordx4 v[22:25], v[70:71], off offset:-2048
	global_load_dwordx4 v[18:21], v[70:71], off offset:-1024
	global_load_dwordx4 v[14:17], v[70:71], off
	global_load_dwordx4 v[10:13], v[70:71], off offset:1024
	v_cmp_lt_i32_e32 vcc, v202, v201
	s_ashr_i32 s0, s42, 31
	s_lshr_b32 s0, s0, 20
	v_cndmask_b32_e32 v35, v199, v202, vcc
	v_lshlrev_b32_e32 v35, 2, v35
	v_cmp_lt_i32_e32 vcc, v203, v201
	s_add_i32 s0, s42, s0
	s_ashr_i32 s0, s0, 12
	s_and_b64 s[22:23], s[20:21], exec
	s_cselect_b32 s0, 4, s0
	s_add_i32 s22, s42, 0xffffc000
	s_and_b64 s[20:21], s[20:21], exec
	v_readlane_b32 s44, v254, 40
	s_cselect_b32 s21, 0, s43
	s_cselect_b32 s20, s22, s42
	v_readlane_b32 s56, v254, 52
	v_readlane_b32 s57, v254, 53
	s_cselect_b32 s22, s15, s57
	s_cselect_b32 s23, s14, s56
	s_lshl_b64 s[20:21], s[20:21], 13
	s_add_u32 s44, s23, s20
	v_readlane_b32 s20, v254, 62
	v_readlane_b32 s45, v254, 41
	s_mul_i32 s20, s20, 5
	v_readlane_b32 s46, v254, 42
	s_addc_u32 s45, s22, s21
	s_add_i32 s0, s0, s20
	v_readlane_b32 s47, v254, 43
	s_mul_i32 s46, s0, 0x1800
	s_ashr_i32 s47, s46, 31
	s_lshl_b64 s[20:21], s[46:47], 2
	s_add_u32 s0, s12, s20
	s_addc_u32 s21, s13, s21
	v_lshlrev_b32_e32 v74, 2, v34
	s_add_u32 s20, s0, 0x4000
	s_addc_u32 s21, s21, 0
	v_lshlrev_b32_e32 v49, 2, v40
	v_mov_b32_e32 v75, v0
	v_lshl_add_u64 v[78:79], s[44:45], 0, v[74:75]
	s_movk_i32 s0, 0x1000
	v_lshlrev_b32_e32 v75, 2, v42
	v_readlane_b32 s48, v254, 44
	v_readlane_b32 s49, v254, 45
	v_readlane_b32 s50, v254, 46
	v_readlane_b32 s51, v254, 47
	v_readlane_b32 s52, v254, 48
	v_readlane_b32 s53, v254, 49
	v_readlane_b32 s54, v254, 50
	v_readlane_b32 s55, v254, 51
	v_readlane_b32 s58, v254, 54
	v_readlane_b32 s59, v254, 55
	s_waitcnt vmcnt(5)
	v_mul_f32_e32 v1, v31, v31
	s_waitcnt vmcnt(4)
	v_mul_f32_e32 v2, v27, v27
	v_fmac_f32_e32 v1, v30, v30
	v_fmac_f32_e32 v2, v26, v26
	v_fmac_f32_e32 v1, v32, v32
	v_fmac_f32_e32 v2, v28, v28
	v_fmac_f32_e32 v1, v33, v33
	v_fmac_f32_e32 v2, v29, v29
	v_add_f32_e32 v1, v1, v2
	s_waitcnt vmcnt(3)
	v_mul_f32_e32 v2, v23, v23
	v_fmac_f32_e32 v2, v22, v22
	v_fmac_f32_e32 v2, v24, v24
	v_fmac_f32_e32 v2, v25, v25
	v_add_f32_e32 v1, v1, v2
	s_waitcnt vmcnt(2)
	v_mul_f32_e32 v2, v19, v19
	v_fmac_f32_e32 v2, v18, v18
	v_fmac_f32_e32 v2, v20, v20
	v_fmac_f32_e32 v2, v21, v21
	s_waitcnt vmcnt(1)
	v_mov_b32_e32 v4, v15
	s_waitcnt vmcnt(0)
	v_mov_b32_e32 v5, v11
	v_add_f32_e32 v1, v1, v2
	v_mov_b32_e32 v2, v14
	v_mov_b32_e32 v3, v10
	v_pk_mul_f32 v[4:5], v[4:5], v[4:5]
	v_mov_b32_e32 v84, v30
	v_pk_fma_f32 v[2:3], v[2:3], v[2:3], v[4:5]
	v_mov_b32_e32 v4, v16
	v_mov_b32_e32 v5, v12
	v_pk_fma_f32 v[2:3], v[4:5], v[4:5], v[2:3]
	v_mov_b32_e32 v4, v17
	v_mov_b32_e32 v5, v13
	v_pk_fma_f32 v[2:3], v[4:5], v[4:5], v[2:3]
	v_mov_b32_e32 v85, v32
	v_add_f32_e32 v1, v1, v2
	v_add_f32_e32 v1, v1, v3
	global_load_dwordx4 v[6:9], v[70:71], off offset:2048
	global_load_dwordx4 v[2:5], v[70:71], off offset:3072
	v_mov_b32_e32 v32, v31
	s_waitcnt vmcnt(1)
	v_mov_b32_e32 v80, v7
	s_waitcnt vmcnt(0)
	v_mov_b32_e32 v81, v3
	v_mov_b32_e32 v76, v6
	v_mov_b32_e32 v77, v2
	v_pk_mul_f32 v[80:81], v[80:81], v[80:81]
	s_nop 0
	v_pk_fma_f32 v[76:77], v[76:77], v[76:77], v[80:81]
	v_mov_b32_e32 v80, v8
	v_mov_b32_e32 v81, v4
	v_pk_fma_f32 v[76:77], v[80:81], v[80:81], v[76:77]
	v_mov_b32_e32 v80, v9
	v_mov_b32_e32 v81, v5
	v_pk_fma_f32 v[76:77], v[80:81], v[80:81], v[76:77]
	global_load_dwordx4 v[80:83], v[50:51], off
	v_add_f32_e32 v1, v1, v76
	v_add_f32_e32 v1, v1, v77
	ds_bpermute_b32 v37, v35, v1
	s_waitcnt lgkmcnt(0)
	v_add_f32_e32 v1, v1, v37
	v_cndmask_b32_e32 v37, v199, v203, vcc
	v_lshlrev_b32_e32 v37, 2, v37
	ds_bpermute_b32 v39, v37, v1
	v_cmp_lt_i32_e32 vcc, v204, v201
	s_waitcnt lgkmcnt(0)
	v_add_f32_e32 v1, v1, v39
	v_cndmask_b32_e32 v39, v199, v204, vcc
	v_lshlrev_b32_e32 v39, 2, v39
	ds_bpermute_b32 v41, v39, v1
	v_cmp_lt_i32_e32 vcc, v205, v201
	s_waitcnt lgkmcnt(0)
	v_add_f32_e32 v1, v1, v41
	v_cndmask_b32_e32 v41, v199, v205, vcc
	v_lshlrev_b32_e32 v41, 2, v41
	ds_bpermute_b32 v43, v41, v1
	v_cmp_lt_i32_e32 vcc, v206, v201
	s_waitcnt lgkmcnt(0)
	v_add_f32_e32 v1, v1, v43
	v_cndmask_b32_e32 v43, v199, v206, vcc
	v_lshlrev_b32_e32 v43, 2, v43
	ds_bpermute_b32 v45, v43, v1
	v_cmp_lt_i32_e32 vcc, v207, v201
	s_waitcnt lgkmcnt(0)
	v_add_f32_e32 v1, v1, v45
	v_cndmask_b32_e32 v45, v199, v207, vcc
	v_lshlrev_b32_e32 v45, 2, v45
	ds_bpermute_b32 v47, v45, v1
	s_waitcnt lgkmcnt(0)
	v_add_f32_e32 v1, v1, v47
	v_fmamk_f32 v1, v1, 0x3a000000, v193
	v_cmp_gt_f32_e32 vcc, s62, v1
	v_mul_f32_e32 v47, 0x4b800000, v1
	s_waitcnt vmcnt(0)
	v_mov_b32_e32 v86, v80
	v_cndmask_b32_e32 v1, v1, v47, vcc
	v_rsq_f32_e32 v1, v1
	v_mov_b32_e32 v87, v82
	v_mov_b32_e32 v82, v81
	v_mul_f32_e32 v47, 0x45800000, v1
	v_cndmask_b32_e32 v76, v1, v47, vcc
	v_pk_mul_f32 v[84:85], v[84:85], v[76:77] op_sel_hi:[1,0]
	v_pk_mul_f32 v[30:31], v[32:33], v[76:77] op_sel_hi:[1,0]
	v_pk_mul_f32 v[88:89], v[86:87], v[84:85]
	v_pk_mul_f32 v[30:31], v[82:83], v[30:31]
	global_load_dwordx4 v[80:83], v74, s[44:45]
	global_load_dwordx4 v[84:87], v74, s[20:21]
	v_lshlrev_b32_e32 v1, 2, v36
	v_lshlrev_b32_e32 v47, 2, v38
	v_add_co_u32_e32 v78, vcc, s0, v78
	s_nop 1
	v_addc_co_u32_e32 v79, vcc, 0, v79, vcc
	s_waitcnt vmcnt(1)
	v_mov_b32_e32 v90, v80
	s_waitcnt vmcnt(0)
; __device__ void norm_phase(int tid_, int bid_, int nblk_, const Params& p, int lprev, int lnext) {
;     ...
; #pragma unroll
;       for (int i = 0; i < 8; ++i) {
;         int idx = i * 256 + lane * 4;
;         float4 g4 = *(const float4*)(gate + idx);
;         float4 n4 = *(const float4*)(np + idx);
;         xv[i * 4 + 0] += g4.x * (zv[i * 4 + 0] * rs * n4.x);
;         xv[i * 4 + 1] += g4.y * (zv[i * 4 + 1] * rs * n4.y);
;         xv[i * 4 + 2] += g4.z * (zv[i * 4 + 2] * rs * n4.z);
;         xv[i * 4 + 3] += g4.w * (zv[i * 4 + 3] * rs * n4.w);
;         float4 o;
;         o.x = xv[i * 4 + 0]; o.y = xv[i * 4 + 1]; o.z = xv[i * 4 + 2]; o.w = xv[i * 4 + 3];
;         *(float4*)(xnew + idx) = o;
	v_mov_b32_e32 v32, v84
	v_mov_b32_e32 v33, v86
	v_mov_b32_e32 v91, v82
	v_mov_b32_e32 v86, v85
	v_mov_b32_e32 v82, v81
	v_pk_fma_f32 v[32:33], v[32:33], v[88:89], v[90:91]
	v_pk_fma_f32 v[30:31], v[86:87], v[30:31], v[82:83]
	v_mov_b32_e32 v80, v32
	v_mov_b32_e32 v81, v30
	v_mov_b32_e32 v82, v33
	v_mov_b32_e32 v83, v31
	global_store_dwordx4 v74, v[80:83], s[44:45]
	v_lshlrev_b32_e32 v112, 2, v44
	v_lshlrev_b32_e32 v113, 2, v46
	v_lshlrev_b32_e32 v114, 2, v48
	global_load_dwordx4 v[120:123], v[50:51], off offset:1024
	global_load_dwordx4 v[124:127], v74, s[44:45] offset:1024
	global_load_dwordx4 v[128:131], v1, s[20:21]
	global_load_dwordx4 v[132:135], v[50:51], off offset:2048
	global_load_dwordx4 v[136:139], v74, s[44:45] offset:2048
	global_load_dwordx4 v[140:143], v47, s[20:21]
	global_load_dwordx4 v[144:147], v[50:51], off offset:3072
	global_load_dwordx4 v[148:151], v74, s[44:45] offset:3072
	global_load_dwordx4 v[152:155], v49, s[20:21]
	v_mov_b32_e32 v80, v26
	v_mov_b32_e32 v81, v28
	v_mov_b32_e32 v28, v27
	v_pk_mul_f32 v[80:81], v[80:81], v[76:77] op_sel_hi:[1,0]
	v_pk_mul_f32 v[26:27], v[28:29], v[76:77] op_sel_hi:[1,0]
	s_andn2_b64 vcc, exec, s[40:41]
	s_waitcnt vmcnt(8)
	v_mov_b32_e32 v82, v120
	v_mov_b32_e32 v83, v121
	v_mov_b32_e32 v84, v122
	v_mov_b32_e32 v85, v123
	v_mov_b32_e32 v86, v82
	v_mov_b32_e32 v87, v84
	v_mov_b32_e32 v84, v83
	v_pk_mul_f32 v[80:81], v[80:81], v[86:87]
	v_pk_mul_f32 v[26:27], v[26:27], v[84:85]
	s_waitcnt vmcnt(6)
	v_mov_b32_e32 v82, v124
	v_mov_b32_e32 v83, v125
	v_mov_b32_e32 v84, v126
	v_mov_b32_e32 v85, v127
	v_mov_b32_e32 v86, v128
	v_mov_b32_e32 v87, v129
	v_mov_b32_e32 v88, v130
	v_mov_b32_e32 v89, v131
	v_mov_b32_e32 v90, v82
	s_waitcnt vmcnt(6)
	v_mov_b32_e32 v28, v86
	v_mov_b32_e32 v29, v88
	v_mov_b32_e32 v91, v84
	v_mov_b32_e32 v88, v87
	v_mov_b32_e32 v84, v83
	v_pk_fma_f32 v[28:29], v[28:29], v[80:81], v[90:91]
	v_pk_fma_f32 v[26:27], v[88:89], v[26:27], v[84:85]
	v_mov_b32_e32 v80, v28
	v_mov_b32_e32 v81, v26
	v_mov_b32_e32 v82, v29
	v_mov_b32_e32 v83, v27
	global_store_dwordx4 v74, v[80:83], s[44:45] offset:1024
	v_mov_b32_e32 v84, v22
	v_mov_b32_e32 v85, v24
	v_mov_b32_e32 v24, v23
	v_pk_mul_f32 v[84:85], v[84:85], v[76:77] op_sel_hi:[1,0]
	v_pk_mul_f32 v[22:23], v[24:25], v[76:77] op_sel_hi:[1,0]
	s_waitcnt vmcnt(6)
	v_mov_b32_e32 v80, v132
	v_mov_b32_e32 v81, v133
	v_mov_b32_e32 v82, v134
	v_mov_b32_e32 v83, v135
	v_mov_b32_e32 v86, v80
	v_mov_b32_e32 v87, v82
	v_mov_b32_e32 v82, v81
	v_pk_mul_f32 v[88:89], v[84:85], v[86:87]
	v_pk_mul_f32 v[22:23], v[22:23], v[82:83]
	s_waitcnt vmcnt(4)
	v_mov_b32_e32 v80, v136
	v_mov_b32_e32 v81, v137
	v_mov_b32_e32 v82, v138
	v_mov_b32_e32 v83, v139
	v_mov_b32_e32 v84, v140
	v_mov_b32_e32 v85, v141
	v_mov_b32_e32 v86, v142
	v_mov_b32_e32 v87, v143
	v_mov_b32_e32 v90, v80
	s_waitcnt vmcnt(4)
	v_mov_b32_e32 v24, v84
	v_mov_b32_e32 v25, v86
	v_mov_b32_e32 v91, v82
	v_mov_b32_e32 v86, v85
	v_mov_b32_e32 v82, v81
	v_pk_fma_f32 v[24:25], v[24:25], v[88:89], v[90:91]
	v_pk_fma_f32 v[22:23], v[86:87], v[22:23], v[82:83]
	v_mov_b32_e32 v80, v24
	v_mov_b32_e32 v81, v22
	v_mov_b32_e32 v82, v25
	v_mov_b32_e32 v83, v23
	global_store_dwordx4 v74, v[80:83], s[44:45] offset:2048
	v_mov_b32_e32 v84, v18
	v_mov_b32_e32 v85, v20
	v_mov_b32_e32 v20, v19
	v_pk_mul_f32 v[84:85], v[84:85], v[76:77] op_sel_hi:[1,0]
	v_pk_mul_f32 v[18:19], v[20:21], v[76:77] op_sel_hi:[1,0]
	s_waitcnt vmcnt(4)
	v_mov_b32_e32 v80, v144
	v_mov_b32_e32 v81, v145
	v_mov_b32_e32 v82, v146
	v_mov_b32_e32 v83, v147
	v_mov_b32_e32 v86, v80
	v_mov_b32_e32 v87, v82
	v_mov_b32_e32 v82, v81
	v_pk_mul_f32 v[88:89], v[84:85], v[86:87]
	v_pk_mul_f32 v[18:19], v[18:19], v[82:83]
	s_waitcnt vmcnt(2)
	v_mov_b32_e32 v80, v148
	v_mov_b32_e32 v81, v149
	v_mov_b32_e32 v82, v150
	v_mov_b32_e32 v83, v151
	v_mov_b32_e32 v84, v152
	v_mov_b32_e32 v85, v153
	v_mov_b32_e32 v86, v154
	v_mov_b32_e32 v87, v155
	v_mov_b32_e32 v90, v80
	s_waitcnt vmcnt(2)
	v_mov_b32_e32 v20, v84
	v_mov_b32_e32 v21, v86
	v_mov_b32_e32 v91, v82
	v_mov_b32_e32 v86, v85
	v_mov_b32_e32 v82, v81
	v_pk_fma_f32 v[20:21], v[20:21], v[88:89], v[90:91]
	v_pk_fma_f32 v[18:19], v[86:87], v[18:19], v[82:83]
	v_mov_b32_e32 v80, v20
	v_mov_b32_e32 v81, v18
	v_mov_b32_e32 v82, v21
	v_mov_b32_e32 v83, v19
	global_store_dwordx4 v74, v[80:83], s[44:45] offset:3072
	global_load_dwordx4 v[156:159], v[52:53], off
	global_load_dwordx4 v[160:163], v[78:79], off
	global_load_dwordx4 v[164:167], v75, s[20:21]
	global_load_dwordx4 v[168:171], v[54:55], off
	global_load_dwordx4 v[172:175], v[78:79], off offset:1024
	global_load_dwordx4 v[176:179], v112, s[20:21]
	global_load_dwordx4 v[180:183], v[56:57], off
	global_load_dwordx4 v[184:187], v[78:79], off offset:2048
	global_load_dwordx4 v[188:191], v113, s[20:21]
	v_mov_b32_e32 v84, v14
	v_mov_b32_e32 v85, v16
	v_mov_b32_e32 v16, v15
	v_pk_mul_f32 v[84:85], v[84:85], v[76:77] op_sel_hi:[1,0]
	v_pk_mul_f32 v[14:15], v[16:17], v[76:77] op_sel_hi:[1,0]
	v_lshlrev_b32_e32 v77, 2, v44
	s_waitcnt vmcnt(8)
	v_mov_b32_e32 v80, v156
	v_mov_b32_e32 v81, v157
	v_mov_b32_e32 v82, v158
	v_mov_b32_e32 v83, v159
	v_mov_b32_e32 v86, v80
	v_mov_b32_e32 v87, v82
	v_mov_b32_e32 v82, v81
	v_pk_mul_f32 v[88:89], v[84:85], v[86:87]
	v_pk_mul_f32 v[14:15], v[14:15], v[82:83]
	s_waitcnt vmcnt(6)
	v_mov_b32_e32 v80, v160
	v_mov_b32_e32 v81, v161
	v_mov_b32_e32 v82, v162
	v_mov_b32_e32 v83, v163
	v_mov_b32_e32 v84, v164
	v_mov_b32_e32 v85, v165
	v_mov_b32_e32 v86, v166
	v_mov_b32_e32 v87, v167
	v_mov_b32_e32 v90, v80
	s_waitcnt vmcnt(6)
; __device__ __forceinline__ unsigned pack2(float a, float b) { return (unsigned)f2bf(a) | ((unsigned)f2bf(b) << 16); }
; __device__ void norm_phase(int tid_, int bid_, int nblk_, const Params& p, int lprev, int lnext) {
;     ...
; #pragma unroll
;       for (int i = 0; i < 8; ++i) {
;         int idx = i * 256 + lane * 4;
;         float4 g4 = *(const float4*)(gate + idx);
;         float4 n4 = *(const float4*)(np + idx);
;         xv[i * 4 + 0] += g4.x * (zv[i * 4 + 0] * rs * n4.x);
;         xv[i * 4 + 1] += g4.y * (zv[i * 4 + 1] * rs * n4.y);
;         xv[i * 4 + 2] += g4.z * (zv[i * 4 + 2] * rs * n4.z);
;         xv[i * 4 + 3] += g4.w * (zv[i * 4 + 3] * rs * n4.w);
;         float4 o;
;         o.x = xv[i * 4 + 0]; o.y = xv[i * 4 + 1]; o.z = xv[i * 4 + 2]; o.w = xv[i * 4 + 3];
;         *(float4*)(xnew + idx) = o;
;       }
;     }
;     if (lnext <= 3) {
;       float ss = 0.f;
; #pragma unroll
;       for (int i = 0; i < 32; ++i) ss += xv[i] * xv[i];
;       ss = wave_sum(ss);
;       float rs = rsqrtf(ss * (1.f / 2048.f) + 1e-6f);
;       const float* shift = p.mod + (lnext * 5 + mrow) * 6144;
;       const float* scale = shift + 2048;
;       const float* npre = p.norm_pre + lnext * D;
;       u16* hr = p.h + (size_t)row * D;
; #pragma unroll
;       for (int i = 0; i < 8; ++i) {
;         int idx = i * 256 + lane * 4;
;         float4 s4 = *(const float4*)(shift + idx);
;         float4 c4 = *(const float4*)(scale + idx);
;         float4 n4 = *(const float4*)(npre + idx);
;         float h0 = xv[i * 4 + 0] * rs * n4.x * (1.f + c4.x) + s4.x;
;         float h1 = xv[i * 4 + 1] * rs * n4.y * (1.f + c4.y) + s4.y;
;         float h2 = xv[i * 4 + 2] * rs * n4.z * (1.f + c4.z) + s4.z;
;         float h3 = xv[i * 4 + 3] * rs * n4.w * (1.f + c4.w) + s4.w;
;         uint2 o;
;         o.x = pack2(h0, h1);
;         o.y = pack2(h2, h3);
;         *(uint2*)(hr + idx) = o;
;       }
	v_mov_b32_e32 v16, v84
	v_mov_b32_e32 v17, v86
	v_mov_b32_e32 v91, v82
	v_mov_b32_e32 v86, v85
	v_mov_b32_e32 v82, v81
	v_pk_fma_f32 v[16:17], v[16:17], v[88:89], v[90:91]
	v_pk_fma_f32 v[14:15], v[86:87], v[14:15], v[82:83]
	v_mov_b32_e32 v80, v16
	v_mov_b32_e32 v81, v14
	v_mov_b32_e32 v82, v17
	v_mov_b32_e32 v83, v15
	global_store_dwordx4 v75, v[80:83], s[44:45]
	v_mov_b32_e32 v84, v10
	v_mov_b32_e32 v85, v12
	v_mov_b32_e32 v12, v11
	v_pk_mul_f32 v[84:85], v[84:85], v[76:77] op_sel_hi:[1,0]
	v_pk_mul_f32 v[10:11], v[12:13], v[76:77] op_sel_hi:[1,0]
	s_waitcnt vmcnt(6)
	v_mov_b32_e32 v80, v168
	v_mov_b32_e32 v81, v169
	v_mov_b32_e32 v82, v170
	v_mov_b32_e32 v83, v171
	v_mov_b32_e32 v86, v80
	v_mov_b32_e32 v87, v82
	v_mov_b32_e32 v82, v81
	v_pk_mul_f32 v[88:89], v[84:85], v[86:87]
	v_pk_mul_f32 v[10:11], v[10:11], v[82:83]
	s_waitcnt vmcnt(4)
	v_mov_b32_e32 v80, v172
	v_mov_b32_e32 v81, v173
	v_mov_b32_e32 v82, v174
	v_mov_b32_e32 v83, v175
	v_mov_b32_e32 v84, v176
	v_mov_b32_e32 v85, v177
	v_mov_b32_e32 v86, v178
	v_mov_b32_e32 v87, v179
	v_mov_b32_e32 v90, v80
	s_waitcnt vmcnt(4)
	v_mov_b32_e32 v12, v84
	v_mov_b32_e32 v13, v86
	v_mov_b32_e32 v91, v82
	v_mov_b32_e32 v86, v85
	v_mov_b32_e32 v82, v81
	v_pk_fma_f32 v[12:13], v[12:13], v[88:89], v[90:91]
	v_pk_fma_f32 v[10:11], v[86:87], v[10:11], v[82:83]
	v_mov_b32_e32 v80, v12
	v_mov_b32_e32 v81, v10
	v_mov_b32_e32 v82, v13
	v_mov_b32_e32 v83, v11
	global_store_dwordx4 v77, v[80:83], s[44:45]
	v_mov_b32_e32 v86, v6
	v_mov_b32_e32 v87, v8
	v_mov_b32_e32 v8, v7
	v_pk_mul_f32 v[86:87], v[86:87], v[76:77] op_sel_hi:[1,0]
	v_pk_mul_f32 v[6:7], v[8:9], v[76:77] op_sel_hi:[1,0]
	v_lshlrev_b32_e32 v80, 2, v46
	v_lshlrev_b32_e32 v81, 2, v48
	s_waitcnt vmcnt(4)
	v_mov_b32_e32 v82, v180
	v_mov_b32_e32 v83, v181
	v_mov_b32_e32 v84, v182
	v_mov_b32_e32 v85, v183
	v_mov_b32_e32 v88, v82
	v_mov_b32_e32 v89, v84
	v_mov_b32_e32 v84, v83
	v_pk_mul_f32 v[90:91], v[86:87], v[88:89]
	v_pk_mul_f32 v[6:7], v[6:7], v[84:85]
	s_waitcnt vmcnt(2)
	v_mov_b32_e32 v82, v184
	v_mov_b32_e32 v83, v185
	v_mov_b32_e32 v84, v186
	v_mov_b32_e32 v85, v187
	v_mov_b32_e32 v86, v188
	v_mov_b32_e32 v87, v189
	v_mov_b32_e32 v88, v190
	v_mov_b32_e32 v89, v191
	v_mov_b32_e32 v92, v82
	s_waitcnt vmcnt(2)
	v_mov_b32_e32 v8, v86
	v_mov_b32_e32 v9, v88
	v_mov_b32_e32 v93, v84
	v_mov_b32_e32 v88, v87
	v_mov_b32_e32 v84, v83
	v_pk_fma_f32 v[8:9], v[8:9], v[90:91], v[92:93]
	v_pk_fma_f32 v[6:7], v[88:89], v[6:7], v[84:85]
	v_mov_b32_e32 v82, v8
	v_mov_b32_e32 v83, v6
	v_mov_b32_e32 v84, v9
	v_mov_b32_e32 v85, v7
	global_store_dwordx4 v80, v[82:85], s[44:45]
	global_load_dwordx4 v[120:123], v[58:59], off
	global_load_dwordx4 v[124:127], v[78:79], off offset:3072
	global_load_dwordx4 v[128:131], v114, s[20:21]
	v_mov_b32_e32 v86, v2
	v_mov_b32_e32 v87, v4
	v_mov_b32_e32 v4, v3
	v_pk_mul_f32 v[86:87], v[86:87], v[76:77] op_sel_hi:[1,0]
	v_pk_mul_f32 v[2:3], v[4:5], v[76:77] op_sel_hi:[1,0]
	s_waitcnt vmcnt(2)
	v_mov_b32_e32 v82, v120
	v_mov_b32_e32 v83, v121
	v_mov_b32_e32 v84, v122
	v_mov_b32_e32 v85, v123
	v_mov_b32_e32 v88, v82
	v_mov_b32_e32 v89, v84
	v_mov_b32_e32 v84, v83
	v_pk_mul_f32 v[90:91], v[86:87], v[88:89]
	v_pk_mul_f32 v[2:3], v[2:3], v[84:85]
	s_waitcnt vmcnt(0)
	v_mov_b32_e32 v82, v124
	v_mov_b32_e32 v83, v125
	v_mov_b32_e32 v84, v126
	v_mov_b32_e32 v85, v127
	v_mov_b32_e32 v86, v128
	v_mov_b32_e32 v87, v129
	v_mov_b32_e32 v88, v130
	v_mov_b32_e32 v89, v131
	v_mov_b32_e32 v78, v82
	s_waitcnt vmcnt(0)
	v_mov_b32_e32 v4, v86
	v_mov_b32_e32 v5, v88
	v_mov_b32_e32 v79, v84
	v_mov_b32_e32 v88, v87
	v_mov_b32_e32 v84, v83
	v_pk_fma_f32 v[4:5], v[4:5], v[90:91], v[78:79]
	v_pk_fma_f32 v[2:3], v[88:89], v[2:3], v[84:85]
	v_mov_b32_e32 v82, v4
	v_mov_b32_e32 v83, v2
	v_mov_b32_e32 v84, v5
	v_mov_b32_e32 v85, v3
	global_store_dwordx4 v81, v[82:85], s[44:45]
	s_cbranch_vccnz .LBB0_327
	s_nop 0
	v_pk_mul_f32 v[84:85], v[32:33], v[32:33]
	v_pk_mul_f32 v[86:87], v[30:31], v[30:31]
	v_pk_mul_f32 v[88:89], v[28:29], v[28:29]
	v_add_f32_e32 v76, v84, v86
	v_add_f32_e32 v76, v85, v76
	v_add_f32_e32 v76, v87, v76
	v_pk_mul_f32 v[90:91], v[26:27], v[26:27]
	v_add_f32_e32 v76, v76, v88
	v_add_f32_e32 v76, v76, v90
	v_add_f32_e32 v76, v76, v89
	v_pk_mul_f32 v[92:93], v[24:25], v[24:25]
	v_add_f32_e32 v76, v76, v91
	v_pk_mul_f32 v[94:95], v[22:23], v[22:23]
	v_add_f32_e32 v76, v76, v92
	v_add_f32_e32 v76, v76, v94
	v_add_f32_e32 v76, v76, v93
	v_pk_mul_f32 v[96:97], v[20:21], v[20:21]
	v_add_f32_e32 v76, v76, v95
	v_pk_mul_f32 v[98:99], v[18:19], v[18:19]
	v_add_f32_e32 v76, v76, v96
	v_add_f32_e32 v76, v76, v98
	v_add_f32_e32 v76, v76, v97
	v_pk_mul_f32 v[100:101], v[16:17], v[16:17]
	v_add_f32_e32 v76, v76, v99
	v_pk_mul_f32 v[102:103], v[14:15], v[14:15]
	v_add_f32_e32 v76, v76, v100
	v_add_f32_e32 v76, v76, v102
	v_add_f32_e32 v76, v76, v101
	v_pk_mul_f32 v[104:105], v[12:13], v[12:13]
	v_add_f32_e32 v76, v76, v103
	v_pk_mul_f32 v[106:107], v[10:11], v[10:11]
	v_add_f32_e32 v76, v76, v104
	v_add_f32_e32 v76, v76, v106
	v_add_f32_e32 v76, v76, v105
	v_pk_mul_f32 v[108:109], v[8:9], v[8:9]
	v_add_f32_e32 v76, v76, v107
	v_pk_mul_f32 v[110:111], v[6:7], v[6:7]
	v_add_f32_e32 v76, v76, v108
	v_add_f32_e32 v76, v76, v110
	s_add_i32 s20, s46, 0x7800
	v_mov_b32_e32 v78, v4
	v_mov_b32_e32 v79, v2
	v_add_f32_e32 v76, v76, v109
	s_ashr_i32 s21, s20, 31
	v_pk_mul_f32 v[78:79], v[78:79], v[78:79]
	v_add_f32_e32 v76, v76, v111
	s_lshl_b64 s[20:21], s[20:21], 2
	v_mov_b32_e32 v82, v5
	v_mov_b32_e32 v83, v3
	v_add_f32_e32 v76, v76, v78
	s_add_u32 s20, s12, s20
	v_pk_mul_f32 v[82:83], v[82:83], v[82:83]
	v_add_f32_e32 v76, v76, v79
	s_addc_u32 s21, s13, s21
	v_add_f32_e32 v76, v76, v82
	s_add_u32 s22, s20, 0x2000
	v_add_f32_e32 v76, v76, v83
	s_addc_u32 s23, s21, 0
	global_load_dwordx4 v[120:123], v74, s[20:21]
	global_load_dwordx4 v[124:127], v74, s[22:23]
	global_load_dwordx4 v[128:131], v[60:61], off
	global_load_dwordx4 v[132:135], v74, s[20:21] offset:1024
	global_load_dwordx4 v[136:139], v1, s[22:23]
	global_load_dwordx4 v[140:143], v[60:61], off offset:1024
	global_load_dwordx4 v[144:147], v74, s[20:21] offset:2048
	global_load_dwordx4 v[148:151], v47, s[22:23]
	global_load_dwordx4 v[152:155], v[60:61], off offset:2048
	ds_bpermute_b32 v35, v35, v76
	s_waitcnt lgkmcnt(0)
; __device__ __forceinline__ unsigned pack2(float a, float b) { return (unsigned)f2bf(a) | ((unsigned)f2bf(b) << 16); }
; __device__ void norm_phase(int tid_, int bid_, int nblk_, const Params& p, int lprev, int lnext) {
;     ...
;       float ss = 0.f;
; #pragma unroll
;       for (int i = 0; i < 32; ++i) ss += xv[i] * xv[i];
;       ss = wave_sum(ss);
;       float rs = rsqrtf(ss * (1.f / 2048.f) + 1e-6f);
;       const float* shift = p.mod + (lnext * 5 + mrow) * 6144;
;       const float* scale = shift + 2048;
;       const float* npre = p.norm_pre + lnext * D;
;       u16* hr = p.h + (size_t)row * D;
; #pragma unroll
;       for (int i = 0; i < 8; ++i) {
;         int idx = i * 256 + lane * 4;
;         float4 s4 = *(const float4*)(shift + idx);
;         float4 c4 = *(const float4*)(scale + idx);
;         float4 n4 = *(const float4*)(npre + idx);
;         float h0 = xv[i * 4 + 0] * rs * n4.x * (1.f + c4.x) + s4.x;
;         float h1 = xv[i * 4 + 1] * rs * n4.y * (1.f + c4.y) + s4.y;
;         float h2 = xv[i * 4 + 2] * rs * n4.z * (1.f + c4.z) + s4.z;
;         float h3 = xv[i * 4 + 3] * rs * n4.w * (1.f + c4.w) + s4.w;
;         uint2 o;
;         o.x = pack2(h0, h1);
;         o.y = pack2(h2, h3);
;         *(uint2*)(hr + idx) = o;
;       }
	v_add_f32_e32 v35, v76, v35
	ds_bpermute_b32 v37, v37, v35
	s_waitcnt lgkmcnt(0)
	v_add_f32_e32 v35, v35, v37
	ds_bpermute_b32 v37, v39, v35
	s_waitcnt lgkmcnt(0)
	v_add_f32_e32 v35, v35, v37
	ds_bpermute_b32 v37, v41, v35
	s_waitcnt lgkmcnt(0)
	v_add_f32_e32 v35, v35, v37
	ds_bpermute_b32 v37, v43, v35
	s_waitcnt lgkmcnt(0)
	v_add_f32_e32 v35, v35, v37
	ds_bpermute_b32 v37, v45, v35
	s_waitcnt lgkmcnt(0)
	v_add_f32_e32 v35, v35, v37
	v_fmamk_f32 v35, v35, 0x3a000000, v193
	v_cmp_gt_f32_e32 vcc, s62, v35
	v_mul_f32_e32 v37, 0x4b800000, v35
	s_waitcnt vmcnt(6)
	v_mov_b32_e32 v94, v120
	v_cndmask_b32_e32 v35, v35, v37, vcc
	v_rsq_f32_e32 v35, v35
	s_waitcnt vmcnt(6)
	v_mov_b32_e32 v78, v128
	v_mov_b32_e32 v79, v130
	v_mov_b32_e32 v95, v122
	v_mul_f32_e32 v37, 0x45800000, v35
	v_cndmask_b32_e32 v76, v35, v37, vcc
	v_pk_mul_f32 v[32:33], v[32:33], v[76:77] op_sel_hi:[1,0]
	v_pk_mul_f32 v[30:31], v[30:31], v[76:77] op_sel_hi:[1,0]
	v_pk_mul_f32 v[32:33], v[78:79], v[32:33]
	v_mov_b32_e32 v78, v124
	v_mov_b32_e32 v79, v126
	v_pk_add_f32 v[78:79], v[78:79], 1.0 op_sel_hi:[1,0]
	v_mov_b32_e32 v130, v129
	v_mov_b32_e32 v126, v125
	v_pk_fma_f32 v[32:33], v[78:79], v[32:33], v[94:95]
	v_pk_mul_f32 v[30:31], v[130:131], v[30:31]
	v_pk_add_f32 v[78:79], v[126:127], 1.0 op_sel_hi:[1,0]
	v_mov_b32_e32 v122, v121
	v_pk_fma_f32 v[30:31], v[78:79], v[30:31], v[122:123]
	v_and_b32_sdwa v35, v33, v198 dst_sel:DWORD dst_unused:UNUSED_PAD src0_sel:WORD_1 src1_sel:DWORD
	v_and_b32_sdwa v37, v32, v198 dst_sel:DWORD dst_unused:UNUSED_PAD src0_sel:WORD_1 src1_sel:DWORD
	v_add3_u32 v32, v32, v37, s63
	v_add3_u32 v33, v33, v35, s63
	v_and_b32_sdwa v35, v31, v198 dst_sel:DWORD dst_unused:UNUSED_PAD src0_sel:WORD_1 src1_sel:DWORD
	v_and_b32_sdwa v37, v30, v198 dst_sel:DWORD dst_unused:UNUSED_PAD src0_sel:WORD_1 src1_sel:DWORD
	v_add3_u32 v31, v31, v35, s63
	v_add3_u32 v30, v30, v37, s63
	v_and_b32_e32 v31, 0xffff0000, v31
	v_and_b32_e32 v30, 0xffff0000, v30
	v_or_b32_sdwa v31, v31, v33 dst_sel:DWORD dst_unused:UNUSED_PAD src0_sel:DWORD src1_sel:WORD_1
	v_or_b32_sdwa v30, v30, v32 dst_sel:DWORD dst_unused:UNUSED_PAD src0_sel:DWORD src1_sel:WORD_1
	global_store_dwordx2 v[72:73], v[30:31], off offset:-2048
	s_nop 0
	v_pk_mul_f32 v[28:29], v[28:29], v[76:77] op_sel_hi:[1,0]
	v_pk_mul_f32 v[26:27], v[26:27], v[76:77] op_sel_hi:[1,0]
	v_pk_mul_f32 v[24:25], v[24:25], v[76:77] op_sel_hi:[1,0]
	v_pk_mul_f32 v[22:23], v[22:23], v[76:77] op_sel_hi:[1,0]
	v_pk_mul_f32 v[20:21], v[20:21], v[76:77] op_sel_hi:[1,0]
	v_pk_mul_f32 v[18:19], v[18:19], v[76:77] op_sel_hi:[1,0]
	v_pk_mul_f32 v[16:17], v[16:17], v[76:77] op_sel_hi:[1,0]
	v_pk_mul_f32 v[14:15], v[14:15], v[76:77] op_sel_hi:[1,0]
	v_pk_mul_f32 v[12:13], v[12:13], v[76:77] op_sel_hi:[1,0]
	v_pk_mul_f32 v[10:11], v[10:11], v[76:77] op_sel_hi:[1,0]
	v_pk_mul_f32 v[8:9], v[8:9], v[76:77] op_sel_hi:[1,0]
	v_pk_mul_f32 v[6:7], v[6:7], v[76:77] op_sel_hi:[1,0]
	v_pk_mul_f32 v[4:5], v[4:5], v[76:77] op_sel_hi:[1,0]
	v_pk_mul_f32 v[2:3], v[2:3], v[76:77] op_sel_hi:[1,0]
	s_waitcnt vmcnt(4)
	v_mov_b32_e32 v128, v132
	v_mov_b32_e32 v129, v134
	s_waitcnt vmcnt(4)
	v_mov_b32_e32 v78, v140
	v_mov_b32_e32 v79, v142
	v_pk_mul_f32 v[28:29], v[28:29], v[78:79]
	v_mov_b32_e32 v78, v136
	v_mov_b32_e32 v79, v138
	v_pk_add_f32 v[78:79], v[78:79], 1.0 op_sel_hi:[1,0]
	v_mov_b32_e32 v142, v141
	v_mov_b32_e32 v138, v137
	v_pk_fma_f32 v[28:29], v[78:79], v[28:29], v[128:129]
	v_pk_mul_f32 v[26:27], v[26:27], v[142:143]
	v_pk_add_f32 v[78:79], v[138:139], 1.0 op_sel_hi:[1,0]
	v_mov_b32_e32 v134, v133
	v_pk_fma_f32 v[26:27], v[78:79], v[26:27], v[134:135]
	v_and_b32_sdwa v1, v29, v198 dst_sel:DWORD dst_unused:UNUSED_PAD src0_sel:WORD_1 src1_sel:DWORD
	v_and_b32_sdwa v132, v28, v198 dst_sel:DWORD dst_unused:UNUSED_PAD src0_sel:WORD_1 src1_sel:DWORD
	v_add3_u32 v28, v28, v132, s63
	v_add3_u32 v1, v29, v1, s63
	v_and_b32_sdwa v29, v27, v198 dst_sel:DWORD dst_unused:UNUSED_PAD src0_sel:WORD_1 src1_sel:DWORD
	v_and_b32_sdwa v132, v26, v198 dst_sel:DWORD dst_unused:UNUSED_PAD src0_sel:WORD_1 src1_sel:DWORD
	v_add3_u32 v27, v27, v29, s63
	v_add3_u32 v26, v26, v132, s63
	v_and_b32_e32 v27, 0xffff0000, v27
	v_and_b32_e32 v26, 0xffff0000, v26
	v_or_b32_sdwa v27, v27, v1 dst_sel:DWORD dst_unused:UNUSED_PAD src0_sel:DWORD src1_sel:WORD_1
	v_or_b32_sdwa v26, v26, v28 dst_sel:DWORD dst_unused:UNUSED_PAD src0_sel:DWORD src1_sel:WORD_1
	global_store_dwordx2 v[72:73], v[26:27], off offset:-1536
	s_nop 0
	s_waitcnt vmcnt(2)
	v_mov_b32_e32 v140, v144
	v_mov_b32_e32 v141, v146
	s_waitcnt vmcnt(2)
	v_mov_b32_e32 v78, v152
	v_mov_b32_e32 v79, v154
	v_pk_mul_f32 v[24:25], v[24:25], v[78:79]
	v_mov_b32_e32 v78, v148
	v_mov_b32_e32 v79, v150
	v_pk_add_f32 v[78:79], v[78:79], 1.0 op_sel_hi:[1,0]
	v_mov_b32_e32 v154, v153
	v_mov_b32_e32 v150, v149
	v_pk_fma_f32 v[24:25], v[78:79], v[24:25], v[140:141]
	v_pk_mul_f32 v[22:23], v[22:23], v[154:155]
	v_pk_add_f32 v[148:149], v[150:151], 1.0 op_sel_hi:[1,0]
	v_mov_b32_e32 v146, v145
	v_pk_fma_f32 v[22:23], v[148:149], v[22:23], v[146:147]
	v_and_b32_sdwa v1, v25, v198 dst_sel:DWORD dst_unused:UNUSED_PAD src0_sel:WORD_1 src1_sel:DWORD
	v_and_b32_sdwa v144, v24, v198 dst_sel:DWORD dst_unused:UNUSED_PAD src0_sel:WORD_1 src1_sel:DWORD
	v_add3_u32 v24, v24, v144, s63
	v_add3_u32 v1, v25, v1, s63
	v_and_b32_sdwa v25, v23, v198 dst_sel:DWORD dst_unused:UNUSED_PAD src0_sel:WORD_1 src1_sel:DWORD
	v_and_b32_sdwa v144, v22, v198 dst_sel:DWORD dst_unused:UNUSED_PAD src0_sel:WORD_1 src1_sel:DWORD
	v_add3_u32 v23, v23, v25, s63
	v_add3_u32 v22, v22, v144, s63
	v_and_b32_e32 v23, 0xffff0000, v23
	v_and_b32_e32 v22, 0xffff0000, v22
	v_or_b32_sdwa v23, v23, v1 dst_sel:DWORD dst_unused:UNUSED_PAD src0_sel:DWORD src1_sel:WORD_1
	v_or_b32_sdwa v22, v22, v24 dst_sel:DWORD dst_unused:UNUSED_PAD src0_sel:DWORD src1_sel:WORD_1
	global_store_dwordx2 v[72:73], v[22:23], off offset:-1024
	global_load_dwordx4 v[156:159], v74, s[20:21] offset:3072
	global_load_dwordx4 v[160:163], v49, s[22:23]
	global_load_dwordx4 v[164:167], v[60:61], off offset:3072
	global_load_dwordx4 v[168:171], v75, s[20:21]
	global_load_dwordx4 v[172:175], v75, s[22:23]
	global_load_dwordx4 v[176:179], v[62:63], off
	global_load_dwordx4 v[180:183], v77, s[20:21]
	global_load_dwordx4 v[184:187], v77, s[22:23]
	global_load_dwordx4 v[188:191], v[64:65], off
	s_nop 0
	s_waitcnt vmcnt(6)
; __device__ __forceinline__ unsigned pack2(float a, float b) { return (unsigned)f2bf(a) | ((unsigned)f2bf(b) << 16); }
; __device__ void norm_phase(int tid_, int bid_, int nblk_, const Params& p, int lprev, int lnext) {
;     ...
; #pragma unroll
;       for (int i = 0; i < 8; ++i) {
;         int idx = i * 256 + lane * 4;
;         float4 s4 = *(const float4*)(shift + idx);
;         float4 c4 = *(const float4*)(scale + idx);
;         float4 n4 = *(const float4*)(npre + idx);
;         float h0 = xv[i * 4 + 0] * rs * n4.x * (1.f + c4.x) + s4.x;
;         float h1 = xv[i * 4 + 1] * rs * n4.y * (1.f + c4.y) + s4.y;
;         float h2 = xv[i * 4 + 2] * rs * n4.z * (1.f + c4.z) + s4.z;
;         float h3 = xv[i * 4 + 3] * rs * n4.w * (1.f + c4.w) + s4.w;
;         uint2 o;
;         o.x = pack2(h0, h1);
;         o.y = pack2(h2, h3);
;         *(uint2*)(hr + idx) = o;
;       }
	v_mov_b32_e32 v152, v156
	v_mov_b32_e32 v153, v158
	s_waitcnt vmcnt(6)
	v_mov_b32_e32 v78, v164
	v_mov_b32_e32 v79, v166
	v_pk_mul_f32 v[20:21], v[20:21], v[78:79]
	v_mov_b32_e32 v78, v160
	v_mov_b32_e32 v79, v162
	v_pk_add_f32 v[78:79], v[78:79], 1.0 op_sel_hi:[1,0]
	v_mov_b32_e32 v166, v165
	v_mov_b32_e32 v162, v161
	v_pk_fma_f32 v[20:21], v[78:79], v[20:21], v[152:153]
	v_pk_mul_f32 v[18:19], v[18:19], v[166:167]
	v_pk_add_f32 v[160:161], v[162:163], 1.0 op_sel_hi:[1,0]
	v_mov_b32_e32 v158, v157
	v_pk_fma_f32 v[18:19], v[160:161], v[18:19], v[158:159]
	v_and_b32_sdwa v1, v21, v198 dst_sel:DWORD dst_unused:UNUSED_PAD src0_sel:WORD_1 src1_sel:DWORD
	v_and_b32_sdwa v156, v20, v198 dst_sel:DWORD dst_unused:UNUSED_PAD src0_sel:WORD_1 src1_sel:DWORD
	v_add3_u32 v20, v20, v156, s63
	v_add3_u32 v1, v21, v1, s63
	v_and_b32_sdwa v21, v19, v198 dst_sel:DWORD dst_unused:UNUSED_PAD src0_sel:WORD_1 src1_sel:DWORD
	v_and_b32_sdwa v156, v18, v198 dst_sel:DWORD dst_unused:UNUSED_PAD src0_sel:WORD_1 src1_sel:DWORD
	v_add3_u32 v19, v19, v21, s63
	v_add3_u32 v18, v18, v156, s63
	v_and_b32_e32 v19, 0xffff0000, v19
	v_and_b32_e32 v18, 0xffff0000, v18
	v_or_b32_sdwa v19, v19, v1 dst_sel:DWORD dst_unused:UNUSED_PAD src0_sel:DWORD src1_sel:WORD_1
	v_or_b32_sdwa v18, v18, v20 dst_sel:DWORD dst_unused:UNUSED_PAD src0_sel:DWORD src1_sel:WORD_1
	global_store_dwordx2 v[72:73], v[18:19], off offset:-512
	s_nop 0
	s_waitcnt vmcnt(4)
	v_mov_b32_e32 v166, v168
	v_mov_b32_e32 v167, v170
	s_waitcnt vmcnt(4)
	v_mov_b32_e32 v164, v176
	v_mov_b32_e32 v165, v178
	v_pk_mul_f32 v[16:17], v[16:17], v[164:165]
	v_mov_b32_e32 v164, v172
	v_mov_b32_e32 v165, v174
	v_pk_add_f32 v[164:165], v[164:165], 1.0 op_sel_hi:[1,0]
	v_mov_b32_e32 v178, v177
	v_mov_b32_e32 v174, v173
	v_pk_fma_f32 v[16:17], v[164:165], v[16:17], v[166:167]
	v_pk_mul_f32 v[14:15], v[14:15], v[178:179]
	v_pk_add_f32 v[172:173], v[174:175], 1.0 op_sel_hi:[1,0]
	v_mov_b32_e32 v170, v169
	v_pk_fma_f32 v[14:15], v[172:173], v[14:15], v[170:171]
	v_and_b32_sdwa v1, v17, v198 dst_sel:DWORD dst_unused:UNUSED_PAD src0_sel:WORD_1 src1_sel:DWORD
	v_and_b32_sdwa v168, v16, v198 dst_sel:DWORD dst_unused:UNUSED_PAD src0_sel:WORD_1 src1_sel:DWORD
	v_add3_u32 v16, v16, v168, s63
	v_add3_u32 v1, v17, v1, s63
	v_and_b32_sdwa v17, v15, v198 dst_sel:DWORD dst_unused:UNUSED_PAD src0_sel:WORD_1 src1_sel:DWORD
	v_and_b32_sdwa v168, v14, v198 dst_sel:DWORD dst_unused:UNUSED_PAD src0_sel:WORD_1 src1_sel:DWORD
	v_add3_u32 v15, v15, v17, s63
	v_add3_u32 v14, v14, v168, s63
	v_and_b32_e32 v15, 0xffff0000, v15
	v_and_b32_e32 v14, 0xffff0000, v14
	v_or_b32_sdwa v15, v15, v1 dst_sel:DWORD dst_unused:UNUSED_PAD src0_sel:DWORD src1_sel:WORD_1
	v_or_b32_sdwa v14, v14, v16 dst_sel:DWORD dst_unused:UNUSED_PAD src0_sel:DWORD src1_sel:WORD_1
	global_store_dwordx2 v[72:73], v[14:15], off
	s_nop 0
	s_waitcnt vmcnt(2)
	v_mov_b32_e32 v178, v180
	v_mov_b32_e32 v179, v182
	s_waitcnt vmcnt(2)
; __device__ __forceinline__ unsigned pack2(float a, float b) { return (unsigned)f2bf(a) | ((unsigned)f2bf(b) << 16); }
; __device__ void norm_phase(int tid_, int bid_, int nblk_, const Params& p, int lprev, int lnext) {
;     ...
; #pragma unroll
;       for (int i = 0; i < 8; ++i) {
;         int idx = i * 256 + lane * 4;
;         float4 s4 = *(const float4*)(shift + idx);
;         float4 c4 = *(const float4*)(scale + idx);
;         float4 n4 = *(const float4*)(npre + idx);
;         float h0 = xv[i * 4 + 0] * rs * n4.x * (1.f + c4.x) + s4.x;
;         float h1 = xv[i * 4 + 1] * rs * n4.y * (1.f + c4.y) + s4.y;
;         float h2 = xv[i * 4 + 2] * rs * n4.z * (1.f + c4.z) + s4.z;
;         float h3 = xv[i * 4 + 3] * rs * n4.w * (1.f + c4.w) + s4.w;
;         uint2 o;
;         o.x = pack2(h0, h1);
;         o.y = pack2(h2, h3);
;         *(uint2*)(hr + idx) = o;
;       }
	v_mov_b32_e32 v176, v188
	v_mov_b32_e32 v177, v190
	v_pk_mul_f32 v[12:13], v[12:13], v[176:177]
	v_mov_b32_e32 v176, v184
	v_mov_b32_e32 v177, v186
	v_pk_add_f32 v[176:177], v[176:177], 1.0 op_sel_hi:[1,0]
	v_mov_b32_e32 v190, v189
	v_mov_b32_e32 v186, v185
	v_pk_fma_f32 v[12:13], v[176:177], v[12:13], v[178:179]
	v_pk_mul_f32 v[10:11], v[10:11], v[190:191]
	v_pk_add_f32 v[184:185], v[186:187], 1.0 op_sel_hi:[1,0]
	v_mov_b32_e32 v182, v181
	v_pk_fma_f32 v[10:11], v[184:185], v[10:11], v[182:183]
	v_and_b32_sdwa v1, v13, v198 dst_sel:DWORD dst_unused:UNUSED_PAD src0_sel:WORD_1 src1_sel:DWORD
	v_and_b32_sdwa v180, v12, v198 dst_sel:DWORD dst_unused:UNUSED_PAD src0_sel:WORD_1 src1_sel:DWORD
	v_add3_u32 v12, v12, v180, s63
	v_add3_u32 v1, v13, v1, s63
	v_and_b32_sdwa v13, v11, v198 dst_sel:DWORD dst_unused:UNUSED_PAD src0_sel:WORD_1 src1_sel:DWORD
	v_and_b32_sdwa v180, v10, v198 dst_sel:DWORD dst_unused:UNUSED_PAD src0_sel:WORD_1 src1_sel:DWORD
	v_add3_u32 v11, v11, v13, s63
	v_add3_u32 v10, v10, v180, s63
	v_and_b32_e32 v11, 0xffff0000, v11
	v_and_b32_e32 v10, 0xffff0000, v10
	v_or_b32_sdwa v11, v11, v1 dst_sel:DWORD dst_unused:UNUSED_PAD src0_sel:DWORD src1_sel:WORD_1
	v_or_b32_sdwa v10, v10, v12 dst_sel:DWORD dst_unused:UNUSED_PAD src0_sel:DWORD src1_sel:WORD_1
	global_store_dwordx2 v[72:73], v[10:11], off offset:512
	global_load_dwordx4 v[120:123], v80, s[20:21]
	global_load_dwordx4 v[124:127], v80, s[22:23]
	global_load_dwordx4 v[128:131], v[66:67], off
	global_load_dwordx4 v[132:135], v81, s[20:21]
	global_load_dwordx4 v[136:139], v81, s[22:23]
	global_load_dwordx4 v[140:143], v[68:69], off
	s_nop 0
	s_waitcnt vmcnt(3)
	v_mov_b32_e32 v190, v120
	v_mov_b32_e32 v191, v122
	s_waitcnt vmcnt(3)
	v_mov_b32_e32 v188, v128
	v_mov_b32_e32 v189, v130
	v_pk_mul_f32 v[8:9], v[8:9], v[188:189]
	v_mov_b32_e32 v188, v124
	v_mov_b32_e32 v189, v126
	v_pk_add_f32 v[188:189], v[188:189], 1.0 op_sel_hi:[1,0]
	v_mov_b32_e32 v130, v129
	v_mov_b32_e32 v126, v125
	v_pk_fma_f32 v[8:9], v[188:189], v[8:9], v[190:191]
	v_pk_mul_f32 v[6:7], v[6:7], v[130:131]
	v_pk_add_f32 v[124:125], v[126:127], 1.0 op_sel_hi:[1,0]
	v_mov_b32_e32 v122, v121
	v_pk_fma_f32 v[6:7], v[124:125], v[6:7], v[122:123]
	v_and_b32_sdwa v1, v9, v198 dst_sel:DWORD dst_unused:UNUSED_PAD src0_sel:WORD_1 src1_sel:DWORD
	v_and_b32_sdwa v120, v8, v198 dst_sel:DWORD dst_unused:UNUSED_PAD src0_sel:WORD_1 src1_sel:DWORD
	v_add3_u32 v8, v8, v120, s63
	v_add3_u32 v1, v9, v1, s63
	v_and_b32_sdwa v9, v7, v198 dst_sel:DWORD dst_unused:UNUSED_PAD src0_sel:WORD_1 src1_sel:DWORD
	v_and_b32_sdwa v120, v6, v198 dst_sel:DWORD dst_unused:UNUSED_PAD src0_sel:WORD_1 src1_sel:DWORD
	v_add3_u32 v7, v7, v9, s63
	v_add3_u32 v6, v6, v120, s63
	v_and_b32_e32 v7, 0xffff0000, v7
	v_and_b32_e32 v6, 0xffff0000, v6
	v_or_b32_sdwa v7, v7, v1 dst_sel:DWORD dst_unused:UNUSED_PAD src0_sel:DWORD src1_sel:WORD_1
	v_or_b32_sdwa v6, v6, v8 dst_sel:DWORD dst_unused:UNUSED_PAD src0_sel:DWORD src1_sel:WORD_1
	global_store_dwordx2 v[72:73], v[6:7], off offset:1024
	s_nop 0
	s_waitcnt vmcnt(1)
	v_mov_b32_e32 v130, v132
	v_mov_b32_e32 v131, v134
	s_waitcnt vmcnt(1)
	v_mov_b32_e32 v128, v140
	v_mov_b32_e32 v129, v142
	v_pk_mul_f32 v[4:5], v[4:5], v[128:129]
	v_mov_b32_e32 v128, v136
	v_mov_b32_e32 v129, v138
	v_pk_add_f32 v[128:129], v[128:129], 1.0 op_sel_hi:[1,0]
	v_mov_b32_e32 v142, v141
	v_mov_b32_e32 v138, v137
	v_pk_fma_f32 v[4:5], v[128:129], v[4:5], v[130:131]
	v_pk_mul_f32 v[2:3], v[2:3], v[142:143]
	v_pk_add_f32 v[136:137], v[138:139], 1.0 op_sel_hi:[1,0]
	v_mov_b32_e32 v134, v133
	v_pk_fma_f32 v[2:3], v[136:137], v[2:3], v[134:135]
	v_and_b32_sdwa v1, v5, v198 dst_sel:DWORD dst_unused:UNUSED_PAD src0_sel:WORD_1 src1_sel:DWORD
	v_and_b32_sdwa v132, v4, v198 dst_sel:DWORD dst_unused:UNUSED_PAD src0_sel:WORD_1 src1_sel:DWORD
	v_add3_u32 v4, v4, v132, s63
	v_add3_u32 v1, v5, v1, s63
	v_and_b32_sdwa v5, v3, v198 dst_sel:DWORD dst_unused:UNUSED_PAD src0_sel:WORD_1 src1_sel:DWORD
	v_and_b32_sdwa v132, v2, v198 dst_sel:DWORD dst_unused:UNUSED_PAD src0_sel:WORD_1 src1_sel:DWORD
	v_add3_u32 v3, v3, v5, s63
	v_add3_u32 v2, v2, v132, s63
	v_and_b32_e32 v3, 0xffff0000, v3
	v_and_b32_e32 v2, 0xffff0000, v2
	v_or_b32_sdwa v3, v3, v1 dst_sel:DWORD dst_unused:UNUSED_PAD src0_sel:DWORD src1_sel:WORD_1
	v_or_b32_sdwa v2, v2, v4 dst_sel:DWORD dst_unused:UNUSED_PAD src0_sel:DWORD src1_sel:WORD_1
	global_store_dwordx2 v[72:73], v[2:3], off offset:1536
	s_branch .LBB0_327

; __device__ __forceinline__ unsigned pack2(float a, float b) { return (unsigned)f2bf(a) | ((unsigned)f2bf(b) << 16); }
; __device__ void transpose_job64(int tid_, int bid_, int nblk_, const float* __restrict__ src, u16* __restrict__ dst, int K, int N,
;                                 int nbatch, size_t sstride, size_t dstride, int ldd, float* sm) {
;     ...
;   for (int t = bid_; t < total; t += nblk_) {
;     int bi = t / per, r = t % per, kt = r / tn, nt = r % tn;
;     const float* s = src + (size_t)bi * sstride + (size_t)(kt * 64) * N + nt * 64;
; #pragma unroll
;     for (int i = 0; i < 16; ++i) {
;       int kk = (tid >> 6) + 4 * i, nn = tid & 63;
;       sm[kk * 65 + nn] = s[(size_t)kk * N + nn];
;     }
;     __syncthreads();
;     {
;       int n = tid >> 2, kc = tid & 3;
;       unsigned o[8];
; #pragma unroll
;       for (int e = 0; e < 8; ++e) o[e] = pack2(sm[(kc * 16 + 2 * e) * 65 + n], sm[(kc * 16 + 2 * e + 1) * 65 + n]);
;       u16* d = dst + (size_t)bi * dstride + (size_t)(nt * 64 + n) * ldd + kt * 64 + kc * 16;
;       *(uint4*)(d) = make_uint4(o[0], o[1], o[2], o[3]);
;       *(uint4*)(d + 8) = make_uint4(o[4], o[5], o[6], o[7]);
.LBB0_779:
	s_mul_hi_i32 s20, s0, 0x3e0f83e1
	s_lshr_b32 s21, s20, 31
	s_ashr_i32 s20, s20, 10
	s_add_i32 s20, s20, s21
	s_mul_i32 s21, s20, 0xffffef80
	s_add_i32 s21, s0, s21
	s_mul_i32 s22, s21, 0x3e1
	s_lshr_b32 s23, s22, 31
	s_ashr_i32 s22, s22, 17
	s_add_i32 s24, s22, s23
	s_mul_i32 s22, s24, 0x84
	s_sub_i32 s21, s21, s22
	s_mul_hi_i32 s23, s20, 0x1080000
	s_mul_i32 s22, s20, 0x1080000
	s_sext_i32_i16 s25, s21
	s_lshl_b64 s[20:21], s[22:23], 2
	s_add_u32 s26, s36, s20
	s_addc_u32 s27, s37, s21
	s_lshl_b32 s20, s24, 6
	s_ashr_i32 s21, s20, 31
	s_mul_i32 s24, s24, 0x210000
	s_mul_hi_i32 s28, s20, 0x8400
	s_add_u32 s29, s26, s24
	s_addc_u32 s28, s27, s28
	s_lshl_b32 s24, s25, 6
	s_ashr_i32 s25, s24, 31
	s_lshl_b64 s[26:27], s[24:25], 2
	s_add_u32 s26, s29, s26
	s_addc_u32 s27, s28, s27
	v_mov_b32_e32 v35, v0
	v_lshl_add_u64 v[38:39], s[26:27], 0, v[34:35]
	v_lshl_add_u64 v[42:43], v[38:39], 0, v[2:3]
	global_load_dword v60, v[42:43], off
	v_lshl_add_u64 v[42:43], v[38:39], 0, v[4:5]
	global_load_dword v61, v[42:43], off
	v_lshl_add_u64 v[42:43], v[38:39], 0, v[6:7]
	global_load_dword v62, v[42:43], off
	v_lshl_add_u64 v[42:43], v[38:39], 0, v[8:9]
	global_load_dword v63, v[42:43], off
	v_lshl_add_u64 v[42:43], v[38:39], 0, v[10:11]
	global_load_dword v64, v[42:43], off
	v_lshl_add_u64 v[42:43], v[38:39], 0, v[12:13]
	global_load_dword v65, v[42:43], off
	v_lshl_add_u64 v[42:43], v[38:39], 0, v[14:15]
	global_load_dword v66, v[42:43], off
	v_lshl_add_u64 v[42:43], v[38:39], 0, v[16:17]
	global_load_dword v67, v[42:43], off
	v_lshl_add_u64 v[42:43], v[38:39], 0, v[18:19]
	global_load_dword v68, v[42:43], off
	v_lshl_add_u64 v[42:43], v[38:39], 0, v[20:21]
	global_load_dword v69, v[42:43], off
	v_lshl_add_u64 v[42:43], v[38:39], 0, v[22:23]
	global_load_dword v70, v[42:43], off
	v_lshl_add_u64 v[42:43], v[38:39], 0, v[24:25]
	global_load_dword v71, v[42:43], off
	v_lshl_add_u64 v[42:43], v[38:39], 0, v[26:27]
	global_load_dword v72, v[42:43], off
	v_lshl_add_u64 v[42:43], v[38:39], 0, v[28:29]
	global_load_dword v73, v[42:43], off
	v_lshl_add_u64 v[42:43], v[38:39], 0, v[30:31]
	global_load_dword v74, v[42:43], off
	v_lshl_add_u64 v[42:43], v[38:39], 0, v[32:33]
	global_load_dword v75, v[42:43], off
	s_lshl_b64 s[22:23], s[22:23], 1
	v_add_u32_e32 v56, s24, v1
	s_add_u32 s22, s54, s22
	v_ashrrev_i32_e32 v57, 31, v56
	s_addc_u32 s23, s55, s23
	v_lshlrev_b64 v[56:57], 12, v[56:57]
	v_lshl_add_u64 v[56:57], s[22:23], 0, v[56:57]
	v_lshl_add_u64 v[56:57], s[20:21], 1, v[56:57]
	v_mov_b32_e32 v37, v0
	v_lshl_add_u64 v[56:57], v[56:57], 0, v[36:37]
	s_add_i32 s0, s0, s30
	s_cmpk_lt_i32 s0, 0x1080
	s_waitcnt vmcnt(0)
	ds_write_b32 v41, v60
	ds_write_b32 v41, v61 offset:1040
	ds_write_b32 v41, v62 offset:2080
	ds_write_b32 v41, v63 offset:3120
	ds_write_b32 v41, v64 offset:4160
	ds_write_b32 v41, v65 offset:5200
	ds_write_b32 v41, v66 offset:6240
	ds_write_b32 v41, v67 offset:7280
	ds_write_b32 v41, v68 offset:8320
	ds_write_b32 v41, v69 offset:9360
	ds_write_b32 v41, v70 offset:10400
	ds_write_b32 v41, v71 offset:11440
	ds_write_b32 v41, v72 offset:12480
	ds_write_b32 v41, v73 offset:13520
	ds_write_b32 v41, v74 offset:14560
	ds_write_b32 v41, v75 offset:15600
	s_waitcnt lgkmcnt(0)
	s_barrier
	ds_read2_b32 v[38:39], v40 offset1:65
	ds_read2_b32 v[42:43], v40 offset0:130 offset1:195
	v_add_u32_e32 v35, 0x400, v40
	ds_read2_b32 v[44:45], v35 offset0:4 offset1:69
	ds_read2_b32 v[46:47], v35 offset0:134 offset1:199
	v_add_u32_e32 v35, 0x800, v40
	ds_read2_b32 v[48:49], v35 offset0:8 offset1:73
	ds_read2_b32 v[50:51], v35 offset0:138 offset1:203
	v_add_u32_e32 v35, 0xc00, v40
	ds_read2_b32 v[52:53], v35 offset0:12 offset1:77
	ds_read2_b32 v[54:55], v35 offset0:142 offset1:207
	s_waitcnt lgkmcnt(6)
	v_and_b32_sdwa v35, v42, v198 dst_sel:DWORD dst_unused:UNUSED_PAD src0_sel:WORD_1 src1_sel:DWORD
	v_and_b32_sdwa v37, v38, v198 dst_sel:DWORD dst_unused:UNUSED_PAD src0_sel:WORD_1 src1_sel:DWORD
	v_add3_u32 v37, v38, v37, s63
	v_add3_u32 v35, v42, v35, s63
	v_and_b32_sdwa v38, v43, v198 dst_sel:DWORD dst_unused:UNUSED_PAD src0_sel:WORD_1 src1_sel:DWORD
	v_and_b32_sdwa v42, v39, v198 dst_sel:DWORD dst_unused:UNUSED_PAD src0_sel:WORD_1 src1_sel:DWORD
	v_add3_u32 v38, v43, v38, s63
	v_add3_u32 v39, v39, v42, s63
	v_and_b32_e32 v38, 0xffff0000, v38
	v_and_b32_e32 v39, 0xffff0000, v39
	v_or_b32_sdwa v43, v38, v35 dst_sel:DWORD dst_unused:UNUSED_PAD src0_sel:DWORD src1_sel:WORD_1
	v_or_b32_sdwa v42, v39, v37 dst_sel:DWORD dst_unused:UNUSED_PAD src0_sel:DWORD src1_sel:WORD_1
	s_waitcnt lgkmcnt(4)
	v_and_b32_sdwa v38, v47, v198 dst_sel:DWORD dst_unused:UNUSED_PAD src0_sel:WORD_1 src1_sel:DWORD
	v_and_b32_sdwa v39, v45, v198 dst_sel:DWORD dst_unused:UNUSED_PAD src0_sel:WORD_1 src1_sel:DWORD
	v_and_b32_sdwa v35, v46, v198 dst_sel:DWORD dst_unused:UNUSED_PAD src0_sel:WORD_1 src1_sel:DWORD
	v_and_b32_sdwa v37, v44, v198 dst_sel:DWORD dst_unused:UNUSED_PAD src0_sel:WORD_1 src1_sel:DWORD
	v_add3_u32 v38, v47, v38, s63
	v_add3_u32 v39, v45, v39, s63
	v_add3_u32 v37, v44, v37, s63
	v_add3_u32 v35, v46, v35, s63
	v_and_b32_e32 v38, 0xffff0000, v38
	v_and_b32_e32 v39, 0xffff0000, v39
	v_or_b32_sdwa v45, v38, v35 dst_sel:DWORD dst_unused:UNUSED_PAD src0_sel:DWORD src1_sel:WORD_1
	v_or_b32_sdwa v44, v39, v37 dst_sel:DWORD dst_unused:UNUSED_PAD src0_sel:DWORD src1_sel:WORD_1
	s_waitcnt lgkmcnt(2)
; __device__ __forceinline__ unsigned pack2(float a, float b) { return (unsigned)f2bf(a) | ((unsigned)f2bf(b) << 16); }
; __device__ __forceinline__ float siluf_(float x) { return x * __builtin_amdgcn_rcpf(1.f + __expf(-x)); }
; __device__ void transpose_job64(int tid_, int bid_, int nblk_, const float* __restrict__ src, u16* __restrict__ dst, int K, int N,
;                                 int nbatch, size_t sstride, size_t dstride, int ldd, float* sm) {
;     ...
;     {
;       int n = tid >> 2, kc = tid & 3;
;       unsigned o[8];
; #pragma unroll
;       for (int e = 0; e < 8; ++e) o[e] = pack2(sm[(kc * 16 + 2 * e) * 65 + n], sm[(kc * 16 + 2 * e + 1) * 65 + n]);
;       u16* d = dst + (size_t)bi * dstride + (size_t)(nt * 64 + n) * ldd + kt * 64 + kc * 16;
;       *(uint4*)(d) = make_uint4(o[0], o[1], o[2], o[3]);
;       *(uint4*)(d + 8) = make_uint4(o[4], o[5], o[6], o[7]);
;     }
;     __syncthreads();
;   }
; }
; __device__ void mod_phase(int tid_, int bid_, int nblk_, const Params& p, char* smem, int item0, int item1) {
;   if (item0 + bid_ >= item1) return;
;   float* sC = (float*)smem;
;   float* sRed = sC + 5 * 2048;
;   const int tid = tid_;
;   for (int i = tid; i < 5 * 2048; i += 256) {
;     int r = i / 2048, k = i % 2048;
;     float v = (r < 4) ? p.c[r * 2048 + k] : p.c_ctx[k];
;     sC[i] = siluf_(v);
;   }
	v_and_b32_sdwa v38, v51, v198 dst_sel:DWORD dst_unused:UNUSED_PAD src0_sel:WORD_1 src1_sel:DWORD
	v_and_b32_sdwa v39, v49, v198 dst_sel:DWORD dst_unused:UNUSED_PAD src0_sel:WORD_1 src1_sel:DWORD
	v_and_b32_sdwa v35, v50, v198 dst_sel:DWORD dst_unused:UNUSED_PAD src0_sel:WORD_1 src1_sel:DWORD
	v_and_b32_sdwa v37, v48, v198 dst_sel:DWORD dst_unused:UNUSED_PAD src0_sel:WORD_1 src1_sel:DWORD
	v_add3_u32 v38, v51, v38, s63
	v_add3_u32 v39, v49, v39, s63
	v_add3_u32 v37, v48, v37, s63
	v_add3_u32 v35, v50, v35, s63
	v_and_b32_e32 v38, 0xffff0000, v38
	v_and_b32_e32 v39, 0xffff0000, v39
	global_store_dwordx4 v[56:57], v[42:45], off
	s_nop 1
	v_or_b32_sdwa v43, v38, v35 dst_sel:DWORD dst_unused:UNUSED_PAD src0_sel:DWORD src1_sel:WORD_1
	v_or_b32_sdwa v42, v39, v37 dst_sel:DWORD dst_unused:UNUSED_PAD src0_sel:DWORD src1_sel:WORD_1
	s_waitcnt lgkmcnt(0)
	v_and_b32_sdwa v38, v55, v198 dst_sel:DWORD dst_unused:UNUSED_PAD src0_sel:WORD_1 src1_sel:DWORD
	v_and_b32_sdwa v39, v53, v198 dst_sel:DWORD dst_unused:UNUSED_PAD src0_sel:WORD_1 src1_sel:DWORD
	v_and_b32_sdwa v35, v54, v198 dst_sel:DWORD dst_unused:UNUSED_PAD src0_sel:WORD_1 src1_sel:DWORD
	v_and_b32_sdwa v37, v52, v198 dst_sel:DWORD dst_unused:UNUSED_PAD src0_sel:WORD_1 src1_sel:DWORD
	v_add3_u32 v38, v55, v38, s63
	v_add3_u32 v39, v53, v39, s63
	v_add3_u32 v37, v52, v37, s63
	v_add3_u32 v35, v54, v35, s63
	v_and_b32_e32 v38, 0xffff0000, v38
	v_and_b32_e32 v39, 0xffff0000, v39
	v_or_b32_sdwa v45, v38, v35 dst_sel:DWORD dst_unused:UNUSED_PAD src0_sel:DWORD src1_sel:WORD_1
	v_or_b32_sdwa v44, v39, v37 dst_sel:DWORD dst_unused:UNUSED_PAD src0_sel:DWORD src1_sel:WORD_1
	global_store_dwordx4 v[56:57], v[42:45], off offset:16
	s_barrier
	s_cbranch_scc1 .LBB0_779
.LBB0_780:
	s_cmpk_gt_i32 s60, 0x5f
	s_cbranch_scc1 .LBB0_795
	v_lshlrev_b32_e32 v1, 2, v118
	s_mov_b64 s[20:21], exec
	v_readlane_b32 s38, v252, 19
	v_readlane_b32 s39, v252, 20
	v_readlane_b32 s42, v252, 23
	v_readlane_b32 s43, v252, 24
	v_add_u32_e32 v142, 0x1000, v1
	s_add_u32 s22, s38, 0x0
	s_addc_u32 s23, s39, 0
	global_load_dword v60, v1, s[22:23]
	global_load_dword v61, v1, s[22:23] offset:1024
	global_load_dword v62, v1, s[22:23] offset:2048
	global_load_dword v63, v1, s[22:23] offset:3072
	global_load_dword v64, v142, s[22:23]
	global_load_dword v65, v142, s[22:23] offset:1024
	global_load_dword v66, v142, s[22:23] offset:2048
	global_load_dword v67, v142, s[22:23] offset:3072
	s_add_u32 s22, s38, 0x2000
	s_addc_u32 s23, s39, 0
	global_load_dword v68, v1, s[22:23]
	global_load_dword v69, v1, s[22:23] offset:1024
	global_load_dword v70, v1, s[22:23] offset:2048
	global_load_dword v71, v1, s[22:23] offset:3072
	global_load_dword v72, v142, s[22:23]
	global_load_dword v73, v142, s[22:23] offset:1024
	global_load_dword v74, v142, s[22:23] offset:2048
	global_load_dword v75, v142, s[22:23] offset:3072
	s_add_u32 s22, s38, 0x4000
	s_addc_u32 s23, s39, 0
	global_load_dword v76, v1, s[22:23]
	global_load_dword v77, v1, s[22:23] offset:1024
	global_load_dword v78, v1, s[22:23] offset:2048
	global_load_dword v79, v1, s[22:23] offset:3072
	global_load_dword v80, v142, s[22:23]
	global_load_dword v81, v142, s[22:23] offset:1024
	global_load_dword v82, v142, s[22:23] offset:2048
	global_load_dword v83, v142, s[22:23] offset:3072
	s_add_u32 s22, s38, 0x6000
	s_addc_u32 s23, s39, 0
	global_load_dword v84, v1, s[22:23]
	global_load_dword v85, v1, s[22:23] offset:1024
	global_load_dword v86, v1, s[22:23] offset:2048
	global_load_dword v87, v1, s[22:23] offset:3072
	global_load_dword v88, v142, s[22:23]
	global_load_dword v89, v142, s[22:23] offset:1024
	global_load_dword v90, v142, s[22:23] offset:2048
	global_load_dword v91, v142, s[22:23] offset:3072
	s_mov_b32 s22, s42
	s_mov_b32 s23, s43
	global_load_dword v92, v1, s[22:23]
	global_load_dword v93, v1, s[22:23] offset:1024
	global_load_dword v94, v1, s[22:23] offset:2048
	global_load_dword v95, v1, s[22:23] offset:3072
	global_load_dword v96, v142, s[22:23]
	global_load_dword v97, v142, s[22:23] offset:1024
	global_load_dword v98, v142, s[22:23] offset:2048
	global_load_dword v99, v142, s[22:23] offset:3072
	s_waitcnt vmcnt(0)
	v_mul_f32_e32 v100, 0xbfb8aa3b, v60
	v_mul_f32_e32 v101, 0xbfb8aa3b, v61
	v_mul_f32_e32 v102, 0xbfb8aa3b, v62
	v_mul_f32_e32 v103, 0xbfb8aa3b, v63
	v_mul_f32_e32 v104, 0xbfb8aa3b, v64
	v_mul_f32_e32 v105, 0xbfb8aa3b, v65
	v_mul_f32_e32 v106, 0xbfb8aa3b, v66
	v_mul_f32_e32 v107, 0xbfb8aa3b, v67
	v_mul_f32_e32 v108, 0xbfb8aa3b, v68
	v_mul_f32_e32 v109, 0xbfb8aa3b, v69
	v_mul_f32_e32 v110, 0xbfb8aa3b, v70
	v_mul_f32_e32 v111, 0xbfb8aa3b, v71
	v_mul_f32_e32 v112, 0xbfb8aa3b, v72
	v_mul_f32_e32 v113, 0xbfb8aa3b, v73
	v_mul_f32_e32 v114, 0xbfb8aa3b, v74
	v_mul_f32_e32 v115, 0xbfb8aa3b, v75
	v_mul_f32_e32 v116, 0xbfb8aa3b, v76
	v_mul_f32_e32 v117, 0xbfb8aa3b, v77
	v_mul_f32_e32 v120, 0xbfb8aa3b, v78
	v_mul_f32_e32 v121, 0xbfb8aa3b, v79
	v_mul_f32_e32 v122, 0xbfb8aa3b, v80
	v_mul_f32_e32 v123, 0xbfb8aa3b, v81
	v_mul_f32_e32 v124, 0xbfb8aa3b, v82
	v_mul_f32_e32 v125, 0xbfb8aa3b, v83
	v_mul_f32_e32 v126, 0xbfb8aa3b, v84
	v_mul_f32_e32 v127, 0xbfb8aa3b, v85
	v_mul_f32_e32 v128, 0xbfb8aa3b, v86
	v_mul_f32_e32 v129, 0xbfb8aa3b, v87
	v_mul_f32_e32 v130, 0xbfb8aa3b, v88
	v_mul_f32_e32 v131, 0xbfb8aa3b, v89
	v_mul_f32_e32 v132, 0xbfb8aa3b, v90
	v_mul_f32_e32 v133, 0xbfb8aa3b, v91
	v_mul_f32_e32 v134, 0xbfb8aa3b, v92
	v_mul_f32_e32 v135, 0xbfb8aa3b, v93
	v_mul_f32_e32 v136, 0xbfb8aa3b, v94
	v_mul_f32_e32 v137, 0xbfb8aa3b, v95
	v_mul_f32_e32 v138, 0xbfb8aa3b, v96
	v_mul_f32_e32 v139, 0xbfb8aa3b, v97
	v_mul_f32_e32 v140, 0xbfb8aa3b, v98
	v_mul_f32_e32 v141, 0xbfb8aa3b, v99
	v_exp_f32_e32 v100, v100
; __device__ __forceinline__ float siluf_(float x) { return x * __builtin_amdgcn_rcpf(1.f + __expf(-x)); }
; __device__ void mod_phase(int tid_, int bid_, int nblk_, const Params& p, char* smem, int item0, int item1) {
;     ...
;   for (int i = tid; i < 5 * 2048; i += 256) {
;     int r = i / 2048, k = i % 2048;
;     float v = (r < 4) ? p.c[r * 2048 + k] : p.c_ctx[k];
;     sC[i] = siluf_(v);
;   }
	v_exp_f32_e32 v101, v101
	v_exp_f32_e32 v102, v102
	v_exp_f32_e32 v103, v103
	v_exp_f32_e32 v104, v104
	v_exp_f32_e32 v105, v105
	v_exp_f32_e32 v106, v106
	v_exp_f32_e32 v107, v107
	v_exp_f32_e32 v108, v108
	v_exp_f32_e32 v109, v109
	v_exp_f32_e32 v110, v110
	v_exp_f32_e32 v111, v111
	v_exp_f32_e32 v112, v112
	v_exp_f32_e32 v113, v113
	v_exp_f32_e32 v114, v114
	v_exp_f32_e32 v115, v115
	v_exp_f32_e32 v116, v116
	v_exp_f32_e32 v117, v117
	v_exp_f32_e32 v120, v120
	v_exp_f32_e32 v121, v121
	v_exp_f32_e32 v122, v122
	v_exp_f32_e32 v123, v123
	v_exp_f32_e32 v124, v124
	v_exp_f32_e32 v125, v125
	v_exp_f32_e32 v126, v126
	v_exp_f32_e32 v127, v127
	v_exp_f32_e32 v128, v128
	v_exp_f32_e32 v129, v129
	v_exp_f32_e32 v130, v130
	v_exp_f32_e32 v131, v131
	v_exp_f32_e32 v132, v132
	v_exp_f32_e32 v133, v133
	v_exp_f32_e32 v134, v134
	v_exp_f32_e32 v135, v135
	v_exp_f32_e32 v136, v136
	v_exp_f32_e32 v137, v137
	v_exp_f32_e32 v138, v138
	v_exp_f32_e32 v139, v139
	v_exp_f32_e32 v140, v140
	v_exp_f32_e32 v141, v141
	v_add_f32_e32 v100, 1.0, v100
	v_add_f32_e32 v101, 1.0, v101
	v_add_f32_e32 v102, 1.0, v102
	v_add_f32_e32 v103, 1.0, v103
	v_add_f32_e32 v104, 1.0, v104
	v_add_f32_e32 v105, 1.0, v105
	v_add_f32_e32 v106, 1.0, v106
	v_add_f32_e32 v107, 1.0, v107
	v_add_f32_e32 v108, 1.0, v108
	v_add_f32_e32 v109, 1.0, v109
	v_add_f32_e32 v110, 1.0, v110
	v_add_f32_e32 v111, 1.0, v111
	v_add_f32_e32 v112, 1.0, v112
	v_add_f32_e32 v113, 1.0, v113
	v_add_f32_e32 v114, 1.0, v114
	v_add_f32_e32 v115, 1.0, v115
	v_add_f32_e32 v116, 1.0, v116
	v_add_f32_e32 v117, 1.0, v117
	v_add_f32_e32 v120, 1.0, v120
	v_add_f32_e32 v121, 1.0, v121
	v_add_f32_e32 v122, 1.0, v122
	v_add_f32_e32 v123, 1.0, v123
	v_add_f32_e32 v124, 1.0, v124
	v_add_f32_e32 v125, 1.0, v125
	v_add_f32_e32 v126, 1.0, v126
	v_add_f32_e32 v127, 1.0, v127
	v_add_f32_e32 v128, 1.0, v128
	v_add_f32_e32 v129, 1.0, v129
	v_add_f32_e32 v130, 1.0, v130
	v_add_f32_e32 v131, 1.0, v131
	v_add_f32_e32 v132, 1.0, v132
	v_add_f32_e32 v133, 1.0, v133
	v_add_f32_e32 v134, 1.0, v134
	v_add_f32_e32 v135, 1.0, v135
	v_add_f32_e32 v136, 1.0, v136
	v_add_f32_e32 v137, 1.0, v137
	v_add_f32_e32 v138, 1.0, v138
	v_add_f32_e32 v139, 1.0, v139
	v_add_f32_e32 v140, 1.0, v140
	v_add_f32_e32 v141, 1.0, v141
	v_rcp_f32_e32 v100, v100
	v_rcp_f32_e32 v101, v101
	v_rcp_f32_e32 v102, v102
	v_rcp_f32_e32 v103, v103
	v_rcp_f32_e32 v104, v104
	v_rcp_f32_e32 v105, v105
	v_rcp_f32_e32 v106, v106
	v_rcp_f32_e32 v107, v107
	v_rcp_f32_e32 v108, v108
	v_rcp_f32_e32 v109, v109
	v_rcp_f32_e32 v110, v110
	v_rcp_f32_e32 v111, v111
	v_rcp_f32_e32 v112, v112
	v_rcp_f32_e32 v113, v113
	v_rcp_f32_e32 v114, v114
	v_rcp_f32_e32 v115, v115
	v_rcp_f32_e32 v116, v116
	v_rcp_f32_e32 v117, v117
	v_rcp_f32_e32 v120, v120
	v_rcp_f32_e32 v121, v121
	v_rcp_f32_e32 v122, v122
	v_rcp_f32_e32 v123, v123
	v_rcp_f32_e32 v124, v124
	v_rcp_f32_e32 v125, v125
	v_rcp_f32_e32 v126, v126
	v_rcp_f32_e32 v127, v127
	v_rcp_f32_e32 v128, v128
	v_rcp_f32_e32 v129, v129
	v_rcp_f32_e32 v130, v130
	v_rcp_f32_e32 v131, v131
	v_rcp_f32_e32 v132, v132
	v_rcp_f32_e32 v133, v133
	v_rcp_f32_e32 v134, v134
	v_rcp_f32_e32 v135, v135
	v_rcp_f32_e32 v136, v136
	v_rcp_f32_e32 v137, v137
	v_rcp_f32_e32 v138, v138
	v_rcp_f32_e32 v139, v139
	v_rcp_f32_e32 v140, v140
	v_rcp_f32_e32 v141, v141
	v_mul_f32_e32 v60, v60, v100
	v_mul_f32_e32 v61, v61, v101
	v_mul_f32_e32 v62, v62, v102
	v_mul_f32_e32 v63, v63, v103
	v_mul_f32_e32 v64, v64, v104
	v_mul_f32_e32 v65, v65, v105
	v_mul_f32_e32 v66, v66, v106
	v_mul_f32_e32 v67, v67, v107
	v_mul_f32_e32 v68, v68, v108
	v_mul_f32_e32 v69, v69, v109
	v_mul_f32_e32 v70, v70, v110
	v_mul_f32_e32 v71, v71, v111
	v_mul_f32_e32 v72, v72, v112
	v_mul_f32_e32 v73, v73, v113
	v_mul_f32_e32 v74, v74, v114
	v_mul_f32_e32 v75, v75, v115
	v_mul_f32_e32 v76, v76, v116
	v_mul_f32_e32 v77, v77, v117
	v_mul_f32_e32 v78, v78, v120
	v_mul_f32_e32 v79, v79, v121
	v_mul_f32_e32 v80, v80, v122
	v_mul_f32_e32 v81, v81, v123
	v_mul_f32_e32 v82, v82, v124
	v_mul_f32_e32 v83, v83, v125
	v_mul_f32_e32 v84, v84, v126
	v_mul_f32_e32 v85, v85, v127
	v_mul_f32_e32 v86, v86, v128
	v_mul_f32_e32 v87, v87, v129
	v_mul_f32_e32 v88, v88, v130
	v_mul_f32_e32 v89, v89, v131
	v_mul_f32_e32 v90, v90, v132
	v_mul_f32_e32 v91, v91, v133
	v_mul_f32_e32 v92, v92, v134
	v_mul_f32_e32 v93, v93, v135
	v_mul_f32_e32 v94, v94, v136
	v_mul_f32_e32 v95, v95, v137
	v_mul_f32_e32 v96, v96, v138
	v_mul_f32_e32 v97, v97, v139
	v_mul_f32_e32 v98, v98, v140
	v_mul_f32_e32 v99, v99, v141
	ds_write_b32 v1, v60
	ds_write_b32 v1, v61 offset:1024
	ds_write_b32 v1, v62 offset:2048
	ds_write_b32 v1, v63 offset:3072
	ds_write_b32 v1, v64 offset:4096
	ds_write_b32 v1, v65 offset:5120
	ds_write_b32 v1, v66 offset:6144
	ds_write_b32 v1, v67 offset:7168
	ds_write_b32 v1, v68 offset:8192
	ds_write_b32 v1, v69 offset:9216
	ds_write_b32 v1, v70 offset:10240
	ds_write_b32 v1, v71 offset:11264
	ds_write_b32 v1, v72 offset:12288
	ds_write_b32 v1, v73 offset:13312
	ds_write_b32 v1, v74 offset:14336
	ds_write_b32 v1, v75 offset:15360
	ds_write_b32 v1, v76 offset:16384
	ds_write_b32 v1, v77 offset:17408
	ds_write_b32 v1, v78 offset:18432
	ds_write_b32 v1, v79 offset:19456
	ds_write_b32 v1, v80 offset:20480
	ds_write_b32 v1, v81 offset:21504
	ds_write_b32 v1, v82 offset:22528
	ds_write_b32 v1, v83 offset:23552
	ds_write_b32 v1, v84 offset:24576
	ds_write_b32 v1, v85 offset:25600
	ds_write_b32 v1, v86 offset:26624
	ds_write_b32 v1, v87 offset:27648
	ds_write_b32 v1, v88 offset:28672
	ds_write_b32 v1, v89 offset:29696
	ds_write_b32 v1, v90 offset:30720
	ds_write_b32 v1, v91 offset:31744
	ds_write_b32 v1, v92 offset:32768
	ds_write_b32 v1, v93 offset:33792
	ds_write_b32 v1, v94 offset:34816
	ds_write_b32 v1, v95 offset:35840
	ds_write_b32 v1, v96 offset:36864
	ds_write_b32 v1, v97 offset:37888
	ds_write_b32 v1, v98 offset:38912
	ds_write_b32 v1, v99 offset:39936

; __device__ void mod_phase(int tid_, int bid_, int nblk_, const Params& p, char* smem, int item0, int item1) {
;     ...
; #pragma unroll 8
;     for (int k = kg * 128; k < kg * 128 + 128; ++k) {
;       float4 w4 = *(const float4*)(W + (size_t)k * 6144 + col);
; #pragma unroll
;       for (int r = 0; r < 5; ++r) {
;         float s = sC[r * 2048 + k];
;         acc[r][0] += s * w4.x; acc[r][1] += s * w4.y; acc[r][2] += s * w4.z; acc[r][3] += s * w4.w;
;       }
;     }
.LBB0_791:
	v_lshl_add_u64 v[30:31], v[28:29], 0, s[20:21]
	ds_read_b128 v[36:39], v34
	ds_read_b128 v[22:25], v34 offset:16
	global_load_dwordx4 v[60:63], v[30:31], off
	v_add_co_u32_e64 v92, s[38:39], s3, v30
	s_nop 1
	v_addc_co_u32_e64 v93, s[38:39], 0, v31, s[38:39]
	global_load_dwordx4 v[64:67], v[92:93], off
	v_add_co_u32_e64 v92, s[38:39], s97, v30
	s_nop 1
	v_addc_co_u32_e64 v93, s[38:39], 0, v31, s[38:39]
	global_load_dwordx4 v[68:71], v[92:93], off
	v_add_co_u32_e64 v92, s[38:39], s83, v30
	s_nop 1
	v_addc_co_u32_e64 v93, s[38:39], 0, v31, s[38:39]
	global_load_dwordx4 v[72:75], v[92:93], off
	v_add_co_u32_e64 v92, s[38:39], s82, v30
	s_nop 1
	v_addc_co_u32_e64 v93, s[38:39], 0, v31, s[38:39]
	global_load_dwordx4 v[76:79], v[92:93], off
	v_add_co_u32_e64 v92, s[38:39], s92, v30
	s_nop 1
	v_addc_co_u32_e64 v93, s[38:39], 0, v31, s[38:39]
	global_load_dwordx4 v[80:83], v[92:93], off
	v_add_co_u32_e64 v92, s[38:39], s91, v30
	s_nop 1
	v_addc_co_u32_e64 v93, s[38:39], 0, v31, s[38:39]
	global_load_dwordx4 v[84:87], v[92:93], off
	v_add_co_u32_e64 v92, s[38:39], s85, v30
	s_nop 1
	v_addc_co_u32_e64 v93, s[38:39], 0, v31, s[38:39]
	global_load_dwordx4 v[88:91], v[92:93], off
	s_add_u32 s20, s20, 0x30000
	s_addc_u32 s21, s21, 0
	s_cmp_lg_u32 s20, 0x300000
	s_waitcnt vmcnt(7) lgkmcnt(1)
	v_pk_fma_f32 v[44:45], v[60:61], v[36:37], v[18:19] op_sel_hi:[1,0,1]
	v_pk_fma_f32 v[46:47], v[62:63], v[36:37], v[20:21] op_sel_hi:[1,0,1]
	ds_read_b128 v[18:21], v34 offset:8192
	s_waitcnt lgkmcnt(0)
	v_pk_fma_f32 v[48:49], v[60:61], v[18:19], v[14:15] op_sel_hi:[1,0,1]
	v_pk_fma_f32 v[50:51], v[62:63], v[18:19], v[16:17] op_sel_hi:[1,0,1]
	ds_read_b128 v[14:17], v34 offset:16384
	s_waitcnt lgkmcnt(0)
	v_pk_fma_f32 v[52:53], v[60:61], v[14:15], v[10:11] op_sel_hi:[1,0,1]
	v_pk_fma_f32 v[54:55], v[62:63], v[14:15], v[12:13] op_sel_hi:[1,0,1]
	ds_read_b128 v[10:13], v34 offset:24576
	s_waitcnt lgkmcnt(0)
	v_pk_fma_f32 v[56:57], v[60:61], v[10:11], v[6:7] op_sel_hi:[1,0,1]
	v_pk_fma_f32 v[58:59], v[62:63], v[10:11], v[8:9] op_sel_hi:[1,0,1]
	ds_read_b128 v[6:9], v34 offset:32768
	s_waitcnt lgkmcnt(0)
	v_pk_fma_f32 v[40:41], v[60:61], v[6:7], v[2:3] op_sel_hi:[1,0,1]
	v_pk_fma_f32 v[42:43], v[62:63], v[6:7], v[4:5] op_sel_hi:[1,0,1]
	s_nop 0
	s_waitcnt vmcnt(6)
	v_pk_fma_f32 v[44:45], v[64:65], v[36:37], v[44:45] op_sel:[0,1,0]
	v_pk_fma_f32 v[36:37], v[66:67], v[36:37], v[46:47] op_sel:[0,1,0]
	v_pk_fma_f32 v[46:47], v[64:65], v[18:19], v[48:49] op_sel:[0,1,0]
	v_pk_fma_f32 v[18:19], v[66:67], v[18:19], v[50:51] op_sel:[0,1,0]
	v_pk_fma_f32 v[48:49], v[64:65], v[14:15], v[52:53] op_sel:[0,1,0]
	v_pk_fma_f32 v[50:51], v[64:65], v[10:11], v[56:57] op_sel:[0,1,0]
	v_pk_fma_f32 v[40:41], v[64:65], v[6:7], v[40:41] op_sel:[0,1,0]
	v_pk_fma_f32 v[14:15], v[66:67], v[14:15], v[54:55] op_sel:[0,1,0]
	s_nop 0
	v_pk_fma_f32 v[10:11], v[66:67], v[10:11], v[58:59] op_sel:[0,1,0]
	v_pk_fma_f32 v[6:7], v[66:67], v[6:7], v[42:43] op_sel:[0,1,0]
	s_waitcnt vmcnt(5)
	v_pk_fma_f32 v[42:43], v[68:69], v[38:39], v[44:45] op_sel_hi:[1,0,1]
	v_pk_fma_f32 v[44:45], v[68:69], v[20:21], v[46:47] op_sel_hi:[1,0,1]
	v_pk_fma_f32 v[46:47], v[68:69], v[16:17], v[48:49] op_sel_hi:[1,0,1]
	v_pk_fma_f32 v[48:49], v[68:69], v[12:13], v[50:51] op_sel_hi:[1,0,1]
	v_pk_fma_f32 v[40:41], v[68:69], v[8:9], v[40:41] op_sel_hi:[1,0,1]
	v_pk_fma_f32 v[36:37], v[70:71], v[38:39], v[36:37] op_sel_hi:[1,0,1]
	s_nop 0
	v_pk_fma_f32 v[18:19], v[70:71], v[20:21], v[18:19] op_sel_hi:[1,0,1]
	v_pk_fma_f32 v[14:15], v[70:71], v[16:17], v[14:15] op_sel_hi:[1,0,1]
	v_pk_fma_f32 v[10:11], v[70:71], v[12:13], v[10:11] op_sel_hi:[1,0,1]
	v_pk_fma_f32 v[6:7], v[70:71], v[8:9], v[6:7] op_sel_hi:[1,0,1]
	v_mov_b32_e32 v8, v39
	s_waitcnt vmcnt(4)
	v_pk_fma_f32 v[38:39], v[72:73], v[8:9], v[42:43] op_sel_hi:[1,0,1]
	v_pk_fma_f32 v[36:37], v[74:75], v[8:9], v[36:37] op_sel_hi:[1,0,1]
	v_mov_b32_e32 v8, v21
	v_pk_fma_f32 v[20:21], v[72:73], v[8:9], v[44:45] op_sel_hi:[1,0,1]
	v_pk_fma_f32 v[18:19], v[74:75], v[8:9], v[18:19] op_sel_hi:[1,0,1]
	v_mov_b32_e32 v8, v17
	v_pk_fma_f32 v[16:17], v[72:73], v[8:9], v[46:47] op_sel_hi:[1,0,1]
	v_pk_fma_f32 v[14:15], v[74:75], v[8:9], v[14:15] op_sel_hi:[1,0,1]
	v_mov_b32_e32 v8, v13
	v_pk_fma_f32 v[42:43], v[72:73], v[8:9], v[48:49] op_sel_hi:[1,0,1]
	v_pk_fma_f32 v[44:45], v[74:75], v[8:9], v[10:11] op_sel_hi:[1,0,1]
	v_mov_b32_e32 v8, v9
	v_pk_fma_f32 v[46:47], v[72:73], v[8:9], v[40:41] op_sel_hi:[1,0,1]
	v_pk_fma_f32 v[48:49], v[74:75], v[8:9], v[6:7] op_sel_hi:[1,0,1]
	s_nop 0
	ds_read_b128 v[10:13], v34 offset:16400
	ds_read_b128 v[6:9], v34 offset:8208
	s_waitcnt vmcnt(3)
; __device__ void mod_phase(int tid_, int bid_, int nblk_, const Params& p, char* smem, int item0, int item1) {
;     ...
; #pragma unroll 8
;     for (int k = kg * 128; k < kg * 128 + 128; ++k) {
;       float4 w4 = *(const float4*)(W + (size_t)k * 6144 + col);
; #pragma unroll
;       for (int r = 0; r < 5; ++r) {
;         float s = sC[r * 2048 + k];
;         acc[r][0] += s * w4.x; acc[r][1] += s * w4.y; acc[r][2] += s * w4.z; acc[r][3] += s * w4.w;
;       }
;     }
; #pragma unroll
;     for (int r = 0; r < 5; ++r)
; #pragma unroll
;       for (int e = 0; e < 4; ++e) sRed[(kg * 5 + r) * 64 + cl * 4 + e] = acc[r][e];
;     __syncthreads();
;     for (int o = tid; o < 320; o += 256) {
;       int r = o / 64, cc = o % 64;
	v_pk_fma_f32 v[50:51], v[76:77], v[22:23], v[38:39] op_sel_hi:[1,0,1]
	v_pk_fma_f32 v[52:53], v[78:79], v[22:23], v[36:37] op_sel_hi:[1,0,1]
	ds_read_b128 v[36:39], v34 offset:24592
	s_waitcnt lgkmcnt(2)
	v_pk_fma_f32 v[16:17], v[76:77], v[10:11], v[16:17] op_sel_hi:[1,0,1]
	v_pk_fma_f32 v[14:15], v[78:79], v[10:11], v[14:15] op_sel_hi:[1,0,1]
	s_waitcnt lgkmcnt(0)
	v_pk_fma_f32 v[54:55], v[76:77], v[36:37], v[42:43] op_sel_hi:[1,0,1]
	ds_read_b128 v[40:43], v34 offset:32784
	v_pk_fma_f32 v[20:21], v[76:77], v[6:7], v[20:21] op_sel_hi:[1,0,1]
	v_pk_fma_f32 v[18:19], v[78:79], v[6:7], v[18:19] op_sel_hi:[1,0,1]
	v_pk_fma_f32 v[44:45], v[78:79], v[36:37], v[44:45] op_sel_hi:[1,0,1]
	v_add_u32_e32 v34, 32, v34
	s_waitcnt lgkmcnt(0)
	v_pk_fma_f32 v[46:47], v[76:77], v[40:41], v[46:47] op_sel_hi:[1,0,1]
	v_pk_fma_f32 v[48:49], v[78:79], v[40:41], v[48:49] op_sel_hi:[1,0,1]
	s_nop 0
	s_waitcnt vmcnt(2)
	v_pk_fma_f32 v[50:51], v[80:81], v[22:23], v[50:51] op_sel:[0,1,0]
	v_pk_fma_f32 v[20:21], v[80:81], v[6:7], v[20:21] op_sel:[0,1,0]
	v_pk_fma_f32 v[6:7], v[82:83], v[6:7], v[18:19] op_sel:[0,1,0]
	v_pk_fma_f32 v[16:17], v[80:81], v[10:11], v[16:17] op_sel:[0,1,0]
	v_pk_fma_f32 v[10:11], v[82:83], v[10:11], v[14:15] op_sel:[0,1,0]
	v_pk_fma_f32 v[14:15], v[80:81], v[36:37], v[54:55] op_sel:[0,1,0]
	v_pk_fma_f32 v[18:19], v[82:83], v[36:37], v[44:45] op_sel:[0,1,0]
	v_pk_fma_f32 v[36:37], v[80:81], v[40:41], v[46:47] op_sel:[0,1,0]
	v_pk_fma_f32 v[22:23], v[82:83], v[22:23], v[52:53] op_sel:[0,1,0]
	s_nop 0
	v_pk_fma_f32 v[40:41], v[82:83], v[40:41], v[48:49] op_sel:[0,1,0]
	s_waitcnt vmcnt(1)
	v_pk_fma_f32 v[44:45], v[84:85], v[24:25], v[50:51] op_sel_hi:[1,0,1]
	v_pk_fma_f32 v[46:47], v[84:85], v[8:9], v[20:21] op_sel_hi:[1,0,1]
	v_pk_fma_f32 v[48:49], v[84:85], v[12:13], v[16:17] op_sel_hi:[1,0,1]
	v_pk_fma_f32 v[52:53], v[84:85], v[38:39], v[14:15] op_sel_hi:[1,0,1]
	v_pk_fma_f32 v[36:37], v[84:85], v[42:43], v[36:37] op_sel_hi:[1,0,1]
	v_pk_fma_f32 v[22:23], v[86:87], v[24:25], v[22:23] op_sel_hi:[1,0,1]
	s_nop 0
	v_pk_fma_f32 v[6:7], v[86:87], v[8:9], v[6:7] op_sel_hi:[1,0,1]
	v_pk_fma_f32 v[50:51], v[86:87], v[12:13], v[10:11] op_sel_hi:[1,0,1]
	v_pk_fma_f32 v[54:55], v[86:87], v[38:39], v[18:19] op_sel_hi:[1,0,1]
	v_pk_fma_f32 v[40:41], v[86:87], v[42:43], v[40:41] op_sel_hi:[1,0,1]
	v_mov_b32_e32 v8, v25
	s_waitcnt vmcnt(0)
	v_pk_fma_f32 v[18:19], v[88:89], v[8:9], v[44:45] op_sel_hi:[1,0,1]
	v_pk_fma_f32 v[20:21], v[90:91], v[8:9], v[22:23] op_sel_hi:[1,0,1]
	v_mov_b32_e32 v8, v9
	v_pk_fma_f32 v[14:15], v[88:89], v[8:9], v[46:47] op_sel_hi:[1,0,1]
	v_pk_fma_f32 v[16:17], v[90:91], v[8:9], v[6:7] op_sel_hi:[1,0,1]
	v_mov_b32_e32 v6, v13
	v_mov_b32_e32 v8, v39
	v_mov_b32_e32 v22, v43
	v_pk_fma_f32 v[10:11], v[88:89], v[6:7], v[48:49] op_sel_hi:[1,0,1]
	v_pk_fma_f32 v[12:13], v[90:91], v[6:7], v[50:51] op_sel_hi:[1,0,1]
	v_pk_fma_f32 v[6:7], v[88:89], v[8:9], v[52:53] op_sel_hi:[1,0,1]
	v_pk_fma_f32 v[8:9], v[90:91], v[8:9], v[54:55] op_sel_hi:[1,0,1]
	v_pk_fma_f32 v[2:3], v[88:89], v[22:23], v[36:37] op_sel_hi:[1,0,1]
	v_pk_fma_f32 v[4:5], v[90:91], v[22:23], v[40:41] op_sel_hi:[1,0,1]
	s_cbranch_scc1 .LBB0_791
	ds_write_b128 v33, v[18:21] offset:40960
	ds_write_b128 v33, v[14:17] offset:41216
	ds_write_b128 v33, v[10:13] offset:41472
	ds_write_b128 v33, v[6:9] offset:41728
	ds_write_b128 v33, v[2:5] offset:41984
	s_waitcnt lgkmcnt(0)
	s_barrier
	s_and_saveexec_b64 s[20:21], vcc
	v_readlane_b32 s36, v252, 17
	s_movk_i32 s26, 0x17c0
	v_readlane_b32 s46, v252, 27
	v_readlane_b32 s47, v252, 28
	v_readlane_b32 s37, v252, 18
	v_readlane_b32 s38, v252, 19
	v_readlane_b32 s39, v252, 20
	v_readlane_b32 s40, v252, 21
	v_readlane_b32 s41, v252, 22
	v_readlane_b32 s42, v252, 23
	v_readlane_b32 s43, v252, 24
	v_readlane_b32 s44, v252, 25
	v_readlane_b32 s45, v252, 26
	v_readlane_b32 s48, v252, 29
	v_readlane_b32 s49, v252, 30
	v_readlane_b32 s50, v252, 31
	v_readlane_b32 s51, v252, 32
	s_cbranch_execz .LBB0_789
	s_mul_i32 s24, s0, 0x1800
	s_add_i32 s24, s24, s22
	s_mulk_i32 s0, 0x6000
	v_lshl_add_u32 v2, v118, 2, v231
	s_add_i32 s0, s0, s24
	s_mov_b64 s[22:23], 0
	v_mov_b32_e32 v3, v118
